# GEMM loops: per-phase s_setprio flips removed, one static s_setprio 1 for waves 4-7 per GEMM phase (reset at phase end); paired MFMA order kept
# speedup vs baseline: 1.0293x; 1.0123x over previous
; __global__ void __launch_bounds__(512, 2) mega(Params p) {
;     ...
;     for (int ph = 0; ph < 17; ++ph) {
;         if (ph == 8) continue;
;         unsigned char* ws = p.ws;
;         float* out = p.out;
;         bf16_t* xb = (bf16_t*)(ws + OFF_XB); bf16_t* Hb = (bf16_t*)(ws + OFF_H);
;         int kind;
;         if (ph == 0) kind = 0; else if (ph == 1 || ph == 14) kind = 1; else if (ph == 2 || ph == 12 || ph == 15) kind = 2; else if (ph == 3 || ph == 8 || ph == 13 || ph == 16) kind = 3;
;         else if (ph == 4 || ph == 9) kind = 4; else if (ph == 5) kind = 5; else if (ph == 6) kind = 6; else if (ph == 7) kind = 7; else kind = 8;
.LBB0_6:
	s_setprio 0
	v_readlane_b32 s3, v255, 41

; __device__ __forceinline__ int otid() { int t = threadIdx.x; asm volatile("" : "+v"(t)); return t; }
; #define PG8_STAGE(bufoff, gbase, voff) do { _Pragma("unroll") for (int _i = 0; _i < 2; ++_i) \
;         __builtin_amdgcn_global_load_lds((const unsigned*)((const char*)(gbase) + (voff)[_i]), (LAS unsigned*)(lds + (bufoff) + ldsw + _i * 8192), 16, 0, 0); } while (0)
; #define PG8_BAR __builtin_amdgcn_s_barrier()
; template <class Epi>
; __device__ __forceinline__ void gemm_phase(LAS unsigned char* lds, const Gemm g, const StaticOrder& S, const Epi& E) {
;     const int tid = otid(), wid = __builtin_amdgcn_readfirstlane(tid >> 6), lane = tid & 63, wr = wid >> 2, wc = wid & 3, fr = lane & 15, fq = lane >> 4;
;     const int K = g.K, nt = K / BK;
;     unsigned voffA[2], voffB[2];
; #pragma unroll
;     for (int i = 0; i < 2; ++i) { int R, C; stage_rc(tid * 16 + i * 8192, R, C); const int Rb = Epi::PERM ? ((R & ~31) + perm32(R & 31)) : R;
;         voffA[i] = (unsigned)(R * K + C) * 2u; voffB[i] = (unsigned)(Rb * K + C) * 2u; }
;     const size_t kstep = (size_t)(BK * 2);
;     const size_t hstep = (size_t)HALF * K * 2;
;     const size_t tstep = 2 * hstep;
;     const unsigned ldsw = (unsigned)wid * 1024u;
;     const int aoff = lds_byte(wr * 64 + fr, fq * 8), boff = lds_byte(wc * 32 + fr, fq * 8);
;     ...
;     Unit cur, nxt; int ui = 0;
;     if (!S.next(0, cur)) return;
;     f32x4 acc[2][2][4][2];
; #pragma unroll
;     for (int a = 0; a < 2; ++a)
; #pragma unroll
;         for (int b = 0; b < 2; ++b)
; #pragma unroll
;             for (int m = 0; m < 4; ++m)
; #pragma unroll
;                 for (int n = 0; n < 2; ++n) acc[a][b][m][n] = (f32x4){0.f, 0.f, 0.f, 0.f};
;     bf16x8 At[4][2], B0[2][2], B1[2][2];
;     const char* cA = (const char*)g.A + (size_t)cur.pm * tstep; const char* cB = (const char*)g.Bt + (size_t)cur.pn * tstep;
;     PG8_STAGE(PG8_SB(0, 0), cB, voffB); PG8_STAGE(PG8_SA(0, 0), cA, voffA); PG8_STAGE(PG8_SB(0, 1), cB + hstep, voffB); PG8_STAGE(PG8_SA(0, 1), cA + hstep, voffA);
;     if (wr == 1) PG8_BAR;
.LBB0_35:
	s_andn2_b64 vcc, exec, s[0:1]
	s_cbranch_vccnz .LBB0_94
	v_ashrrev_i32_e32 v1, 31, v12
	v_lshrrev_b32_e32 v1, 26, v1
	v_add_u32_e32 v1, v12, v1
	v_ashrrev_i32_e32 v8, 6, v1
	v_bfe_i32 v1, v12, 27, 1
	v_lshlrev_b32_e32 v0, 4, v12
	v_lshrrev_b32_e32 v1, 22, v1
	v_add_u32_e32 v1, v0, v1
	v_and_b32_e32 v1, 0xfffffc00, v1
	v_sub_u32_e32 v1, v0, v1
	v_lshrrev_b32_e32 v2, 4, v1
	v_bitop3_b32 v2, v2, v1, 32 bitop3:0x6c
	v_ashrrev_i32_e32 v1, 31, v1
	v_readlane_b32 s0, v255, 41
	v_lshrrev_b32_e32 v1, 26, v1
	s_cmp_eq_u32 s0, 11
	v_add_u32_e32 v1, v2, v1
	s_cselect_b64 s[0:1], -1, 0
	v_ashrrev_i32_e32 v9, 6, v1
	s_and_b64 s[6:7], s[0:1], exec
	v_lshlrev_b32_e32 v3, 3, v8
	v_mul_i32_i24_e32 v4, 64, v9
	s_cselect_b32 s3, 0x5000000, 0
	s_mov_b32 s6, 0x7300000
	v_readlane_b32 s10, v253, 19
	v_and_b32_e32 v3, -16, v3
	v_sub_u32_e32 v2, v2, v4
	s_cselect_b32 s6, s6, 0x6f00000
	v_readlane_b32 s11, v253, 20
	s_add_u32 s30, s10, s3
	v_add_u32_e32 v1, v9, v3
	v_lshlrev_b32_e32 v3, 5, v8
	v_ashrrev_i16_sdwa v2, v236, sext(v2) dst_sel:DWORD dst_unused:UNUSED_PAD src0_sel:DWORD src1_sel:BYTE_0
	s_addc_u32 s31, s11, 0
	v_and_b32_e32 v3, 32, v3
	v_bfe_i32 v10, v2, 0, 16
	s_add_u32 s34, s80, s6
	v_and_b32_e32 v5, 3, v9
	s_mov_b32 s6, 0x1fffe0
	v_add_lshl_u32 v3, v3, v10, 1
	v_add_u32_e32 v0, 0x2000, v0
	v_lshlrev_b32_e32 v2, 1, v1
	v_lshrrev_b32_e32 v4, 2, v1
	v_and_or_b32 v5, v1, s6, v5
	v_lshl_add_u32 v208, v1, 11, v3
	v_ashrrev_i32_e32 v1, 31, v0
	v_lshrrev_b32_e32 v1, 22, v1
	v_add_u32_e32 v1, v0, v1
	v_ashrrev_i32_e32 v11, 10, v1
	v_mul_i32_i24_e32 v1, 0x400, v11
	v_sub_u32_e32 v0, v0, v1
	v_and_b32_e32 v2, 24, v2
	v_and_b32_e32 v4, 4, v4
	v_lshrrev_b32_e32 v1, 4, v0
	v_or3_b32 v2, v5, v4, v2
	v_bitop3_b32 v0, v1, v0, 32 bitop3:0x6c
	v_lshl_add_u32 v184, v2, 11, v3
	v_ashrrev_i32_e32 v2, 31, v0
	v_lshrrev_b32_e32 v2, 26, v2
	v_lshlrev_b32_e32 v1, 3, v11
	v_add_u32_e32 v2, v0, v2
	v_and_b32_e32 v1, -16, v1
	v_ashrrev_i32_e32 v13, 6, v2
	v_add_u32_e32 v1, v13, v1
	v_and_b32_e32 v4, 3, v13
	s_addc_u32 s35, s81, 0
	v_and_b32_e32 v2, 0xc0, v2
	v_and_or_b32 v4, v1, s6, v4
	s_ashr_i32 s6, s29, 6
	s_ashr_i32 s21, s20, 31
	s_ashr_i32 s9, s8, 31
	s_ashr_i32 s3, s29, 8
	v_sub_u32_e32 v0, v0, v2
	s_lshl_b32 s36, s6, 10
	s_lshl_b64 s[10:11], s[20:21], 19
	s_lshl_b64 s[12:13], s[8:9], 19
	v_ashrrev_i16_sdwa v0, v236, sext(v0) dst_sel:DWORD dst_unused:UNUSED_PAD src0_sel:DWORD src1_sel:BYTE_0
	s_add_u32 s24, s34, s12
	v_lshlrev_b32_e32 v3, 5, v11
	v_bfe_i32 v14, v0, 0, 16
	v_lshlrev_b32_e32 v0, 1, v1
	v_lshrrev_b32_e32 v2, 2, v1
	s_addc_u32 s25, s35, s13
	s_add_i32 s21, s36, 0
	v_and_b32_e32 v3, 32, v3
	v_and_b32_e32 v0, 24, v0
	v_and_b32_e32 v2, 4, v2
	s_add_i32 m0, s21, 0x10000
	v_or3_b32 v0, v4, v2, v0
	v_add_lshl_u32 v2, v3, v14, 1
	global_load_lds_dwordx4 v184, s[24:25]
	s_add_i32 m0, s21, 0x12000
	v_lshl_add_u32 v212, v0, 11, v2
	s_add_u32 s22, s30, s10
	global_load_lds_dwordx4 v212, s[24:25]
	s_addc_u32 s23, s31, s11
	s_mov_b32 m0, s21
	s_add_i32 s37, s21, 0x2000
	v_lshl_add_u32 v210, v1, 11, v2
	global_load_lds_dwordx4 v208, s[22:23]
	s_mov_b32 m0, s37
	s_add_u32 s10, s24, 0x40000
	global_load_lds_dwordx4 v210, s[22:23]
	s_addc_u32 s11, s25, 0
	s_add_i32 m0, s21, 0x14000
	v_mov_b32_e32 v213, v185
	global_load_lds_dwordx4 v184, s[10:11]
	s_add_i32 m0, s21, 0x16000
	v_mov_b32_e32 v209, v185
	global_load_lds_dwordx4 v212, s[10:11]
	s_add_u32 s10, s22, 0x40000
	s_addc_u32 s11, s23, 0
	s_add_i32 s38, s21, 0x4000
	s_mov_b32 m0, s38
	s_add_i32 s39, s21, 0x6000
	global_load_lds_dwordx4 v208, s[10:11]
	s_mov_b32 m0, s39
	v_mov_b32_e32 v211, v185
	global_load_lds_dwordx4 v210, s[10:11]
	v_mov_b32_e32 v238, 0x3d800000
	v_lshl_add_u64 v[6:7], s[24:25], 0, v[184:185]
	v_lshl_add_u64 v[4:5], s[24:25], 0, v[212:213]
	v_lshl_add_u64 v[2:3], s[22:23], 0, v[208:209]
	s_cmp_lg_u32 s3, 1
	v_lshl_add_u64 v[0:1], s[22:23], 0, v[210:211]
	s_cbranch_scc1 .LBB0_38
	s_setprio 1
	s_barrier

; #define PG8_STAGE(bufoff, gbase, voff) do { _Pragma("unroll") for (int _i = 0; _i < 2; ++_i) \
;         __builtin_amdgcn_global_load_lds((const unsigned*)((const char*)(gbase) + (voff)[_i]), (LAS unsigned*)(lds + (bufoff) + ldsw + _i * 8192), 16, 0, 0); } while (0)
; #define PG8_LDA(dst, b, h) do { _Pragma("unroll") for (int m = 0; m < 4; ++m) _Pragma("unroll") for (int k = 0; k < 2; ++k) dst[m][k] = *(const LAS bf16x8*)(lds + PG8_SA(b, h) + aoff + m * 2048 + k * 1024); } while (0)
; #define PG8_LDB(dst, b, h) do { _Pragma("unroll") for (int n = 0; n < 2; ++n) _Pragma("unroll") for (int k = 0; k < 2; ++k) dst[n][k] = *(const LAS bf16x8*)(lds + PG8_SB(b, h) + boff + n * 2048 + k * 1024); } while (0)
; #define PG8_MMA(ai, bj, At, Bt) do { __builtin_amdgcn_s_setprio(1); _Pragma("unroll") for (int m = 0; m < 4; ++m) _Pragma("unroll") for (int n = 0; n < 2; ++n) _Pragma("unroll") for (int k = 0; k < 2; ++k) \
;         acc[ai][bj][m][n] = __builtin_amdgcn_mfma_f32_16x16x32_bf16(Bt[n][k], At[m][k], acc[ai][bj][m][n], 0, 0, 0); __builtin_amdgcn_s_setprio(0); } while (0)
; #define PG8_WAIT_L(n) asm volatile("s_waitcnt lgkmcnt(" #n ")" ::: "memory")
; #define PG8_BAR __builtin_amdgcn_s_barrier()
; #define PG8_SCHED __builtin_amdgcn_sched_barrier(0)
; template <class Epi>
; __device__ __forceinline__ void gemm_phase(LAS unsigned char* lds, const Gemm g, const StaticOrder& S, const Epi& E) {
;     ...
;         for (int t = 0; t < nt; t += 2) {
;             const bool last = (t == nt - 2);
;             const char* a1 = cA + (size_t)(t + 1) * kstep;
;             const char* a2 = last ? nA : cA + (size_t)(t + 2) * kstep; const char* b2 = last ? nB : cB + (size_t)(t + 2) * kstep;
;             const char* a3 = a2 + kstep; const char* b3 = b2 + kstep;
;             PG8_LDB(B0, 0, 0); PG8_SCHED; PG8_LDA(At, 0, 0); PG8_STAGE(PG8_SA(1, 1), a1 + hstep, voffA);
;             PG8_WAIT_L(8); PG8_BAR; PG8_WAIT_L(0); PG8_MMA(0, 0, At, B0); PG8_BAR; PG8_SCHED;
;             PG8_LDB(B1, 0, 1); PG8_STAGE(PG8_SB(0, 0), b2, voffB);
;             PG8_BAR; PG8_WAIT_L(0); PG8_MMA(0, 1, At, B1); PG8_BAR;
;             PG8_LDA(At, 0, 1); PG8_STAGE(PG8_SA(0, 0), a2, voffA);
;             PG8_BAR; PG8_WAIT_L(0); PG8_MMA(1, 0, At, B0); PG8_BAR; PG8_SCHED;
.LBB0_43:
	s_add_u32 s24, s22, 0xfffc0080
	s_addc_u32 s25, s23, -1
	s_add_i32 s47, 0, 0x10000
	v_add_u32_e32 v140, s47, v247
	ds_read_b128 v[128:131], v140
	ds_read_b128 v[132:135], v140 offset:1024
	ds_read_b128 v[136:139], v140 offset:2048
	ds_read_b128 v[140:143], v140 offset:3072
	s_cmp_eq_u32 s46, 12
	s_cselect_b32 s27, s3, s25
	s_cselect_b32 s26, s9, s24
	s_cselect_b32 s25, s13, s45
	s_cselect_b32 s24, s15, s43
	v_lshl_add_u64 v[176:177], s[22:23], 0, v[214:215]
	s_add_i32 m0, s21, 0xc000
	ds_read_b128 v[144:147], v249
	ds_read_b128 v[148:151], v249 offset:1024
	ds_read_b128 v[152:155], v249 offset:2048
	ds_read_b128 v[156:159], v249 offset:3072
	ds_read_b128 v[160:163], v249 offset:4096
	ds_read_b128 v[164:167], v249 offset:5120
	ds_read_b128 v[168:171], v249 offset:6144
	ds_read_b128 v[172:175], v249 offset:7168
	global_load_lds_dwordx4 v[176:177], off
	v_lshl_add_u64 v[176:177], s[22:23], 0, v[216:217]
	s_add_i32 m0, s21, 0xe000
	s_nop 0
	global_load_lds_dwordx4 v[176:177], off
	s_waitcnt lgkmcnt(8)
	s_barrier
	s_waitcnt lgkmcnt(0)
	s_waitcnt lgkmcnt(0)
	v_mfma_f32_16x16x32_bf16 v[124:127], v[128:131], v[144:147], v[124:127]
	v_mfma_f32_16x16x32_bf16 v[124:127], v[132:135], v[148:151], v[124:127]
	v_mfma_f32_16x16x32_bf16 v[108:111], v[128:131], v[152:155], v[108:111]
	v_mfma_f32_16x16x32_bf16 v[108:111], v[132:135], v[156:159], v[108:111]
	v_mfma_f32_16x16x32_bf16 v[92:95], v[128:131], v[160:163], v[92:95]
	v_mfma_f32_16x16x32_bf16 v[92:95], v[132:135], v[164:167], v[92:95]
	v_mfma_f32_16x16x32_bf16 v[76:79], v[128:131], v[168:171], v[76:79]
	v_mfma_f32_16x16x32_bf16 v[76:79], v[132:135], v[172:175], v[76:79]
	v_mfma_f32_16x16x32_bf16 v[72:75], v[136:139], v[168:171], v[72:75]
	v_mfma_f32_16x16x32_bf16 v[72:75], v[140:143], v[172:175], v[72:75]
	v_mfma_f32_16x16x32_bf16 v[88:91], v[136:139], v[160:163], v[88:91]
	v_mfma_f32_16x16x32_bf16 v[88:91], v[140:143], v[164:167], v[88:91]
	v_mfma_f32_16x16x32_bf16 v[104:107], v[136:139], v[152:155], v[104:107]
	v_mfma_f32_16x16x32_bf16 v[104:107], v[140:143], v[156:159], v[104:107]
	v_mfma_f32_16x16x32_bf16 v[120:123], v[136:139], v[144:147], v[120:123]
	v_mfma_f32_16x16x32_bf16 v[120:123], v[140:143], v[148:151], v[120:123]
	s_barrier
	s_add_i32 s52, 0, 0x14000
	v_add_u32_e32 v188, s52, v247
	s_add_i32 s47, s47, s36
	ds_read_b128 v[176:179], v188
	ds_read_b128 v[180:183], v188 offset:1024
	ds_read_b128 v[204:207], v188 offset:2048
	ds_read_b128 v[218:221], v188 offset:3072
	v_lshl_add_u64 v[188:189], s[24:25], 0, v[184:185]
	s_mov_b32 m0, s47
	v_lshl_add_u64 v[190:191], s[24:25], 0, v[212:213]
	global_load_lds_dwordx4 v[188:189], off
	s_add_i32 m0, s47, 0x2000
	s_nop 0
	global_load_lds_dwordx4 v[190:191], off
	s_barrier
	s_waitcnt lgkmcnt(0)
	s_waitcnt lgkmcnt(0)
	v_mfma_f32_16x16x32_bf16 v[116:119], v[176:179], v[144:147], v[116:119]
	v_mfma_f32_16x16x32_bf16 v[116:119], v[180:183], v[148:151], v[116:119]
	v_mfma_f32_16x16x32_bf16 v[100:103], v[176:179], v[152:155], v[100:103]
	v_mfma_f32_16x16x32_bf16 v[100:103], v[180:183], v[156:159], v[100:103]
	v_mfma_f32_16x16x32_bf16 v[84:87], v[176:179], v[160:163], v[84:87]
	v_mfma_f32_16x16x32_bf16 v[84:87], v[180:183], v[164:167], v[84:87]
	v_mfma_f32_16x16x32_bf16 v[68:71], v[176:179], v[168:171], v[68:71]
	v_mfma_f32_16x16x32_bf16 v[68:71], v[180:183], v[172:175], v[68:71]
	v_mfma_f32_16x16x32_bf16 v[64:67], v[204:207], v[168:171], v[64:67]
	v_mfma_f32_16x16x32_bf16 v[64:67], v[218:221], v[172:175], v[64:67]
	v_mfma_f32_16x16x32_bf16 v[80:83], v[204:207], v[160:163], v[80:83]
	v_mfma_f32_16x16x32_bf16 v[80:83], v[218:221], v[164:167], v[80:83]
	v_mfma_f32_16x16x32_bf16 v[96:99], v[204:207], v[152:155], v[96:99]
	v_mfma_f32_16x16x32_bf16 v[96:99], v[218:221], v[156:159], v[96:99]
	v_mfma_f32_16x16x32_bf16 v[112:115], v[204:207], v[144:147], v[112:115]
	v_mfma_f32_16x16x32_bf16 v[112:115], v[218:221], v[148:151], v[112:115]
	s_mov_b32 m0, s21
	v_lshl_add_u64 v[192:193], s[26:27], 0, v[208:209]
	s_barrier
	ds_read_b128 v[144:147], v249 offset:16384
	ds_read_b128 v[148:151], v249 offset:17408
	ds_read_b128 v[152:155], v249 offset:18432
	ds_read_b128 v[156:159], v249 offset:19456
	ds_read_b128 v[160:163], v249 offset:20480
	ds_read_b128 v[164:167], v249 offset:21504
	ds_read_b128 v[168:171], v249 offset:22528
	ds_read_b128 v[172:175], v249 offset:23552
	global_load_lds_dwordx4 v[192:193], off
	v_lshl_add_u64 v[222:223], s[26:27], 0, v[210:211]
	s_mov_b32 m0, s37
	s_nop 0
	global_load_lds_dwordx4 v[222:223], off
	s_barrier
	s_waitcnt lgkmcnt(0)
	s_waitcnt lgkmcnt(0)
	v_mfma_f32_16x16x32_bf16 v[60:63], v[128:131], v[144:147], v[60:63]
	v_mfma_f32_16x16x32_bf16 v[60:63], v[132:135], v[148:151], v[60:63]
	v_mfma_f32_16x16x32_bf16 v[44:47], v[128:131], v[152:155], v[44:47]
	v_mfma_f32_16x16x32_bf16 v[44:47], v[132:135], v[156:159], v[44:47]
	v_mfma_f32_16x16x32_bf16 v[28:31], v[128:131], v[160:163], v[28:31]
	v_mfma_f32_16x16x32_bf16 v[28:31], v[132:135], v[164:167], v[28:31]
	v_mfma_f32_16x16x32_bf16 v[16:19], v[128:131], v[168:171], v[16:19]
	v_mfma_f32_16x16x32_bf16 v[16:19], v[132:135], v[172:175], v[16:19]
	v_mfma_f32_16x16x32_bf16 v[8:11], v[136:139], v[168:171], v[8:11]
	v_mfma_f32_16x16x32_bf16 v[8:11], v[140:143], v[172:175], v[8:11]
	v_mfma_f32_16x16x32_bf16 v[24:27], v[136:139], v[160:163], v[24:27]
	v_mfma_f32_16x16x32_bf16 v[24:27], v[140:143], v[164:167], v[24:27]
	v_mfma_f32_16x16x32_bf16 v[40:43], v[136:139], v[152:155], v[40:43]
	v_mfma_f32_16x16x32_bf16 v[40:43], v[140:143], v[156:159], v[40:43]
	v_mfma_f32_16x16x32_bf16 v[56:59], v[136:139], v[144:147], v[56:59]
	v_mfma_f32_16x16x32_bf16 v[56:59], v[140:143], v[148:151], v[56:59]
	s_barrier
; #define PG8_STAGE(bufoff, gbase, voff) do { _Pragma("unroll") for (int _i = 0; _i < 2; ++_i) \
;         __builtin_amdgcn_global_load_lds((const unsigned*)((const char*)(gbase) + (voff)[_i]), (LAS unsigned*)(lds + (bufoff) + ldsw + _i * 8192), 16, 0, 0); } while (0)
; #define PG8_LDA(dst, b, h) do { _Pragma("unroll") for (int m = 0; m < 4; ++m) _Pragma("unroll") for (int k = 0; k < 2; ++k) dst[m][k] = *(const LAS bf16x8*)(lds + PG8_SA(b, h) + aoff + m * 2048 + k * 1024); } while (0)
; #define PG8_LDB(dst, b, h) do { _Pragma("unroll") for (int n = 0; n < 2; ++n) _Pragma("unroll") for (int k = 0; k < 2; ++k) dst[n][k] = *(const LAS bf16x8*)(lds + PG8_SB(b, h) + boff + n * 2048 + k * 1024); } while (0)
; #define PG8_MMA(ai, bj, At, Bt) do { __builtin_amdgcn_s_setprio(1); _Pragma("unroll") for (int m = 0; m < 4; ++m) _Pragma("unroll") for (int n = 0; n < 2; ++n) _Pragma("unroll") for (int k = 0; k < 2; ++k) \
;         acc[ai][bj][m][n] = __builtin_amdgcn_mfma_f32_16x16x32_bf16(Bt[n][k], At[m][k], acc[ai][bj][m][n], 0, 0, 0); __builtin_amdgcn_s_setprio(0); } while (0)
; #define PG8_WAIT_V(n) asm volatile("s_waitcnt vmcnt(" #n ")" ::: "memory")
; #define PG8_WAIT_L(n) asm volatile("s_waitcnt lgkmcnt(" #n ")" ::: "memory")
; #define PG8_BAR __builtin_amdgcn_s_barrier()
; #define PG8_SCHED __builtin_amdgcn_sched_barrier(0)
; template <class Epi>
; __device__ __forceinline__ void gemm_phase(LAS unsigned char* lds, const Gemm g, const StaticOrder& S, const Epi& E) {
;     ...
;             PG8_STAGE(PG8_SB(0, 1), b2 + hstep, voffB);
;             PG8_WAIT_V(6); PG8_BAR; PG8_MMA(1, 1, At, B1); PG8_BAR;
;             PG8_LDB(B0, 1, 0); PG8_SCHED; PG8_LDA(At, 1, 0); PG8_STAGE(PG8_SA(0, 1), a2 + hstep, voffA);
;             PG8_WAIT_L(8); PG8_BAR; PG8_WAIT_L(0); PG8_MMA(0, 0, At, B0); PG8_BAR; PG8_SCHED;
;             PG8_LDB(B1, 1, 1); PG8_STAGE(PG8_SB(1, 0), b3, voffB);
;             PG8_BAR; PG8_WAIT_L(0); PG8_MMA(0, 1, At, B1); PG8_BAR;
;             PG8_LDA(At, 1, 1); PG8_STAGE(PG8_SA(1, 0), a3, voffA);
;             PG8_BAR; PG8_WAIT_L(0); PG8_MMA(1, 0, At, B0); PG8_BAR; PG8_SCHED;
	s_add_u32 s50, s24, 0x40000
	s_addc_u32 s51, s25, 0
	s_add_i32 s47, s52, s36
	v_lshl_add_u64 v[128:129], s[50:51], 0, v[184:185]
	s_mov_b32 m0, s47
	s_nop 0
	global_load_lds_dwordx4 v[128:129], off
	v_lshl_add_u64 v[128:129], s[50:51], 0, v[212:213]
	s_add_i32 m0, s47, 0x2000
	s_nop 0
	global_load_lds_dwordx4 v[128:129], off
	s_waitcnt vmcnt(6)
	s_barrier
	v_mfma_f32_16x16x32_bf16 v[52:55], v[176:179], v[144:147], v[52:55]
	v_mfma_f32_16x16x32_bf16 v[52:55], v[180:183], v[148:151], v[52:55]
	v_mfma_f32_16x16x32_bf16 v[36:39], v[176:179], v[152:155], v[36:39]
	v_mfma_f32_16x16x32_bf16 v[36:39], v[180:183], v[156:159], v[36:39]
	v_mfma_f32_16x16x32_bf16 v[20:23], v[176:179], v[160:163], v[20:23]
	v_mfma_f32_16x16x32_bf16 v[20:23], v[180:183], v[164:167], v[20:23]
	v_mfma_f32_16x16x32_bf16 v[4:7], v[176:179], v[168:171], v[4:7]
	v_mfma_f32_16x16x32_bf16 v[4:7], v[180:183], v[172:175], v[4:7]
	v_mfma_f32_16x16x32_bf16 v[0:3], v[204:207], v[168:171], v[0:3]
	v_mfma_f32_16x16x32_bf16 v[0:3], v[218:221], v[172:175], v[0:3]
	v_mfma_f32_16x16x32_bf16 v[12:15], v[204:207], v[160:163], v[12:15]
	v_mfma_f32_16x16x32_bf16 v[12:15], v[218:221], v[164:167], v[12:15]
	v_mfma_f32_16x16x32_bf16 v[32:35], v[204:207], v[152:155], v[32:35]
	v_mfma_f32_16x16x32_bf16 v[32:35], v[218:221], v[156:159], v[32:35]
	v_mfma_f32_16x16x32_bf16 v[48:51], v[204:207], v[144:147], v[48:51]
	v_mfma_f32_16x16x32_bf16 v[48:51], v[218:221], v[148:151], v[48:51]
	s_add_i32 s47, 0, 0x18000
	v_add_u32_e32 v140, s47, v247
	s_barrier
	ds_read_b128 v[128:131], v140
	ds_read_b128 v[132:135], v140 offset:1024
	ds_read_b128 v[136:139], v140 offset:2048
	ds_read_b128 v[140:143], v140 offset:3072
	s_add_u32 s26, s26, 0x40000
	s_addc_u32 s27, s27, 0
	s_mov_b32 m0, s38
	v_lshl_add_u64 v[176:177], s[26:27], 0, v[208:209]
	ds_read_b128 v[144:147], v249 offset:32768
	ds_read_b128 v[148:151], v249 offset:33792
	ds_read_b128 v[152:155], v249 offset:34816
	ds_read_b128 v[156:159], v249 offset:35840
	ds_read_b128 v[160:163], v249 offset:36864
	ds_read_b128 v[164:167], v249 offset:37888
	ds_read_b128 v[168:171], v249 offset:38912
	ds_read_b128 v[172:175], v249 offset:39936
	global_load_lds_dwordx4 v[176:177], off
	v_lshl_add_u64 v[176:177], s[26:27], 0, v[210:211]
	s_mov_b32 m0, s39
	s_nop 0
	global_load_lds_dwordx4 v[176:177], off
	s_waitcnt lgkmcnt(8)
	s_barrier
	s_waitcnt lgkmcnt(0)
	s_waitcnt lgkmcnt(0)
	v_mfma_f32_16x16x32_bf16 v[124:127], v[128:131], v[144:147], v[124:127]
	v_mfma_f32_16x16x32_bf16 v[124:127], v[132:135], v[148:151], v[124:127]
	v_mfma_f32_16x16x32_bf16 v[108:111], v[128:131], v[152:155], v[108:111]
	v_mfma_f32_16x16x32_bf16 v[108:111], v[132:135], v[156:159], v[108:111]
	v_mfma_f32_16x16x32_bf16 v[92:95], v[128:131], v[160:163], v[92:95]
	v_mfma_f32_16x16x32_bf16 v[92:95], v[132:135], v[164:167], v[92:95]
	v_mfma_f32_16x16x32_bf16 v[76:79], v[128:131], v[168:171], v[76:79]
	v_mfma_f32_16x16x32_bf16 v[76:79], v[132:135], v[172:175], v[76:79]
	v_mfma_f32_16x16x32_bf16 v[72:75], v[136:139], v[168:171], v[72:75]
	v_mfma_f32_16x16x32_bf16 v[72:75], v[140:143], v[172:175], v[72:75]
	v_mfma_f32_16x16x32_bf16 v[88:91], v[136:139], v[160:163], v[88:91]
	v_mfma_f32_16x16x32_bf16 v[88:91], v[140:143], v[164:167], v[88:91]
	v_mfma_f32_16x16x32_bf16 v[104:107], v[136:139], v[152:155], v[104:107]
	v_mfma_f32_16x16x32_bf16 v[104:107], v[140:143], v[156:159], v[104:107]
	v_mfma_f32_16x16x32_bf16 v[120:123], v[136:139], v[144:147], v[120:123]
	v_mfma_f32_16x16x32_bf16 v[120:123], v[140:143], v[148:151], v[120:123]
	s_barrier
	s_add_i32 s26, 0, 0x1c000
	s_add_i32 s27, s47, s36
	v_add_u32_e32 v218, s26, v247
	v_lshl_add_u64 v[188:189], v[188:189], 0, s[58:59]
	s_mov_b32 m0, s27
	ds_read_b128 v[176:179], v218
	ds_read_b128 v[180:183], v218 offset:1024
	ds_read_b128 v[204:207], v218 offset:2048
	ds_read_b128 v[218:221], v218 offset:3072
	global_load_lds_dwordx4 v[188:189], off
	v_lshl_add_u64 v[188:189], v[190:191], 0, s[58:59]
	s_add_i32 m0, s27, 0x2000
	s_nop 0
	global_load_lds_dwordx4 v[188:189], off
	s_barrier
	s_waitcnt lgkmcnt(0)
	s_waitcnt lgkmcnt(0)
	v_mfma_f32_16x16x32_bf16 v[116:119], v[176:179], v[144:147], v[116:119]
	v_mfma_f32_16x16x32_bf16 v[116:119], v[180:183], v[148:151], v[116:119]
	v_mfma_f32_16x16x32_bf16 v[100:103], v[176:179], v[152:155], v[100:103]
	v_mfma_f32_16x16x32_bf16 v[100:103], v[180:183], v[156:159], v[100:103]
	v_mfma_f32_16x16x32_bf16 v[84:87], v[176:179], v[160:163], v[84:87]
	v_mfma_f32_16x16x32_bf16 v[84:87], v[180:183], v[164:167], v[84:87]
	v_mfma_f32_16x16x32_bf16 v[68:71], v[176:179], v[168:171], v[68:71]
	v_mfma_f32_16x16x32_bf16 v[68:71], v[180:183], v[172:175], v[68:71]
	v_mfma_f32_16x16x32_bf16 v[64:67], v[204:207], v[168:171], v[64:67]
	v_mfma_f32_16x16x32_bf16 v[64:67], v[218:221], v[172:175], v[64:67]
	v_mfma_f32_16x16x32_bf16 v[80:83], v[204:207], v[160:163], v[80:83]
	v_mfma_f32_16x16x32_bf16 v[80:83], v[218:221], v[164:167], v[80:83]
	v_mfma_f32_16x16x32_bf16 v[96:99], v[204:207], v[152:155], v[96:99]
	v_mfma_f32_16x16x32_bf16 v[96:99], v[218:221], v[156:159], v[96:99]
	v_mfma_f32_16x16x32_bf16 v[112:115], v[204:207], v[144:147], v[112:115]
	v_mfma_f32_16x16x32_bf16 v[112:115], v[218:221], v[148:151], v[112:115]
	s_mov_b32 m0, s41
	v_lshl_add_u64 v[188:189], v[192:193], 0, s[58:59]
	s_barrier
; #define PG8_STAGE(bufoff, gbase, voff) do { _Pragma("unroll") for (int _i = 0; _i < 2; ++_i) \
;         __builtin_amdgcn_global_load_lds((const unsigned*)((const char*)(gbase) + (voff)[_i]), (LAS unsigned*)(lds + (bufoff) + ldsw + _i * 8192), 16, 0, 0); } while (0)
; #define PG8_LDA(dst, b, h) do { _Pragma("unroll") for (int m = 0; m < 4; ++m) _Pragma("unroll") for (int k = 0; k < 2; ++k) dst[m][k] = *(const LAS bf16x8*)(lds + PG8_SA(b, h) + aoff + m * 2048 + k * 1024); } while (0)
; #define PG8_MMA(ai, bj, At, Bt) do { __builtin_amdgcn_s_setprio(1); _Pragma("unroll") for (int m = 0; m < 4; ++m) _Pragma("unroll") for (int n = 0; n < 2; ++n) _Pragma("unroll") for (int k = 0; k < 2; ++k) \
;         acc[ai][bj][m][n] = __builtin_amdgcn_mfma_f32_16x16x32_bf16(Bt[n][k], At[m][k], acc[ai][bj][m][n], 0, 0, 0); __builtin_amdgcn_s_setprio(0); } while (0)
; #define PG8_WAIT_V(n) asm volatile("s_waitcnt vmcnt(" #n ")" ::: "memory")
; #define PG8_WAIT_L(n) asm volatile("s_waitcnt lgkmcnt(" #n ")" ::: "memory")
; #define PG8_BAR __builtin_amdgcn_s_barrier()
; #define PG8_SCHED __builtin_amdgcn_sched_barrier(0)
; template <class Epi>
; __device__ __forceinline__ void gemm_phase(LAS unsigned char* lds, const Gemm g, const StaticOrder& S, const Epi& E) {
;     ...
;             PG8_LDA(At, 1, 1); PG8_STAGE(PG8_SA(1, 0), a3, voffA);
;             PG8_BAR; PG8_WAIT_L(0); PG8_MMA(1, 0, At, B0); PG8_BAR; PG8_SCHED;
;             PG8_STAGE(PG8_SB(1, 1), b3 + hstep, voffB);
;             PG8_WAIT_V(6); PG8_BAR; PG8_MMA(1, 1, At, B1); PG8_BAR;
;     __device__ __forceinline__ void operator()(const Acc& acc, const Unit& u, int wr, int wc, int fr, int fq) const {
;         const int row0 = u.pm * 256 + wr * 64 + fr, col0 = u.pn * 256 + wc * 32 + 8 * fq;
;         const bf16_t* __restrict__ gp = gate; bf16_t* __restrict__ mg = merged;
;         u32x4 gw[4][2], pw[2][2];
; #pragma unroll
;         for (int gidx = 0; gidx < 4; ++gidx)
; #pragma unroll
;             for (int bj = 0; bj < 2; ++bj) gw[gidx][bj] = *(const u32x4*)(gp + (size_t)(row0 + gidx * 16) * 4096 + col0 + bj * 128);
; #pragma unroll
;         for (int bj = 0; bj < 2; ++bj) pw[0][bj] = accum ? *(const u32x4*)(mg + (size_t)row0 * 2048 + col0 + bj * 128) : (u32x4){0u, 0u, 0u, 0u};
	ds_read_b128 v[144:147], v249 offset:49152
	ds_read_b128 v[148:151], v249 offset:50176
	ds_read_b128 v[152:155], v249 offset:51200
	ds_read_b128 v[156:159], v249 offset:52224
	ds_read_b128 v[160:163], v249 offset:53248
	ds_read_b128 v[164:167], v249 offset:54272
	ds_read_b128 v[168:171], v249 offset:55296
	ds_read_b128 v[172:175], v249 offset:56320
	global_load_lds_dwordx4 v[188:189], off
	v_lshl_add_u64 v[188:189], v[222:223], 0, s[58:59]
	s_mov_b32 m0, s42
	s_nop 0
	global_load_lds_dwordx4 v[188:189], off
	s_barrier
	s_waitcnt lgkmcnt(0)
	s_waitcnt lgkmcnt(0)
	v_mfma_f32_16x16x32_bf16 v[60:63], v[128:131], v[144:147], v[60:63]
	v_mfma_f32_16x16x32_bf16 v[60:63], v[132:135], v[148:151], v[60:63]
	v_mfma_f32_16x16x32_bf16 v[44:47], v[128:131], v[152:155], v[44:47]
	v_mfma_f32_16x16x32_bf16 v[44:47], v[132:135], v[156:159], v[44:47]
	v_mfma_f32_16x16x32_bf16 v[28:31], v[128:131], v[160:163], v[28:31]
	v_mfma_f32_16x16x32_bf16 v[28:31], v[132:135], v[164:167], v[28:31]
	v_mfma_f32_16x16x32_bf16 v[16:19], v[128:131], v[168:171], v[16:19]
	v_mfma_f32_16x16x32_bf16 v[16:19], v[132:135], v[172:175], v[16:19]
	v_mfma_f32_16x16x32_bf16 v[8:11], v[136:139], v[168:171], v[8:11]
	v_mfma_f32_16x16x32_bf16 v[8:11], v[140:143], v[172:175], v[8:11]
	v_mfma_f32_16x16x32_bf16 v[24:27], v[136:139], v[160:163], v[24:27]
	v_mfma_f32_16x16x32_bf16 v[24:27], v[140:143], v[164:167], v[24:27]
	v_mfma_f32_16x16x32_bf16 v[40:43], v[136:139], v[152:155], v[40:43]
	v_mfma_f32_16x16x32_bf16 v[40:43], v[140:143], v[156:159], v[40:43]
	v_mfma_f32_16x16x32_bf16 v[56:59], v[136:139], v[144:147], v[56:59]
	v_mfma_f32_16x16x32_bf16 v[56:59], v[140:143], v[148:151], v[56:59]
	s_barrier
	s_add_u32 s24, s24, 0x40080
	s_addc_u32 s25, s25, 0
	s_add_i32 s26, s26, s36
	v_lshl_add_u64 v[128:129], s[24:25], 0, v[184:185]
	s_mov_b32 m0, s26
	s_nop 0
	global_load_lds_dwordx4 v[128:129], off
	v_lshl_add_u64 v[128:129], s[24:25], 0, v[212:213]
	s_add_i32 m0, s26, 0x2000
	s_nop 0
	global_load_lds_dwordx4 v[128:129], off
	s_waitcnt vmcnt(6)
	s_barrier
	v_mfma_f32_16x16x32_bf16 v[52:55], v[176:179], v[144:147], v[52:55]
	v_mfma_f32_16x16x32_bf16 v[52:55], v[180:183], v[148:151], v[52:55]
	v_mfma_f32_16x16x32_bf16 v[36:39], v[176:179], v[152:155], v[36:39]
	v_mfma_f32_16x16x32_bf16 v[36:39], v[180:183], v[156:159], v[36:39]
	v_mfma_f32_16x16x32_bf16 v[20:23], v[176:179], v[160:163], v[20:23]
	v_mfma_f32_16x16x32_bf16 v[20:23], v[180:183], v[164:167], v[20:23]
	v_mfma_f32_16x16x32_bf16 v[4:7], v[176:179], v[168:171], v[4:7]
	v_mfma_f32_16x16x32_bf16 v[4:7], v[180:183], v[172:175], v[4:7]
	v_mfma_f32_16x16x32_bf16 v[0:3], v[204:207], v[168:171], v[0:3]
	v_mfma_f32_16x16x32_bf16 v[0:3], v[218:221], v[172:175], v[0:3]
	v_mfma_f32_16x16x32_bf16 v[12:15], v[204:207], v[160:163], v[12:15]
	v_mfma_f32_16x16x32_bf16 v[12:15], v[218:221], v[164:167], v[12:15]
	v_mfma_f32_16x16x32_bf16 v[32:35], v[204:207], v[152:155], v[32:35]
	v_mfma_f32_16x16x32_bf16 v[32:35], v[218:221], v[156:159], v[32:35]
	v_mfma_f32_16x16x32_bf16 v[48:51], v[204:207], v[144:147], v[48:51]
	v_mfma_f32_16x16x32_bf16 v[48:51], v[218:221], v[148:151], v[48:51]
	s_add_i32 s46, s46, 2
	s_add_u32 s22, s22, 0x100
	s_addc_u32 s23, s23, 0
	s_add_u32 s43, s43, 0x100
	s_addc_u32 s45, s45, 0
	s_cmp_gt_u32 s46, 13
	s_barrier
	s_cbranch_scc0 .LBB0_43
	v_lshl_or_b32 v128, s8, 8, v248
	v_lshl_add_u32 v222, s20, 8, v187
	v_ashrrev_i32_e32 v129, 31, v128
	v_lshlrev_b64 v[136:137], 1, v[128:129]
	v_ashrrev_i32_e32 v223, 31, v222
	v_lshl_add_u64 v[224:225], s[10:11], 0, v[136:137]
	v_lshlrev_b64 v[130:131], 13, v[222:223]
	v_lshl_add_u64 v[130:131], v[224:225], 0, v[130:131]
	global_load_dwordx4 v[176:179], v[130:131], off
	global_load_dwordx4 v[168:171], v[130:131], off offset:256
	v_or_b32_e32 v130, 16, v222
	v_ashrrev_i32_e32 v131, 31, v130
	v_lshlrev_b64 v[132:133], 13, v[130:131]
	v_or_b32_e32 v230, 32, v222
	v_lshl_add_u64 v[132:133], v[224:225], 0, v[132:133]
	v_ashrrev_i32_e32 v231, 31, v230
	global_load_dwordx4 v[156:159], v[132:133], off
	global_load_dwordx4 v[152:155], v[132:133], off offset:256
	v_lshlrev_b64 v[132:133], 13, v[230:231]
	v_or_b32_e32 v226, 48, v222
	v_lshl_add_u64 v[132:133], v[224:225], 0, v[132:133]
	v_ashrrev_i32_e32 v227, 31, v226
	global_load_dwordx4 v[148:151], v[132:133], off
	global_load_dwordx4 v[144:147], v[132:133], off offset:256
	v_lshlrev_b64 v[132:133], 13, v[226:227]
	v_lshl_add_u64 v[132:133], v[224:225], 0, v[132:133]
	global_load_dwordx4 v[140:143], v[132:133], off
	s_nop 0
	global_load_dwordx4 v[132:135], v[132:133], off offset:256
	v_lshlrev_b64 v[232:233], 12, v[222:223]
	v_lshl_add_u64 v[138:139], s[66:67], 0, v[232:233]
	v_lshl_add_u64 v[136:137], v[138:139], 0, v[136:137]
	v_cndmask_b32_e64 v138, 0, 1, s[0:1]
	v_mov_b32_e32 v172, 0
	v_cmp_ne_u32_e64 s[8:9], 1, v138
	s_andn2_b64 vcc, exec, s[0:1]
	v_mov_b32_e32 v180, 0
	v_mov_b32_e32 v181, 0
	v_mov_b32_e32 v182, 0
	v_mov_b32_e32 v183, 0
	s_cbranch_vccnz .LBB0_46
	global_load_dwordx4 v[180:183], v[136:137], off

; __device__ __forceinline__ int otid() { int t = threadIdx.x; asm volatile("" : "+v"(t)); return t; }
; #define PG8_STAGE(bufoff, gbase, voff) do { _Pragma("unroll") for (int _i = 0; _i < 2; ++_i) \
;         __builtin_amdgcn_global_load_lds((const unsigned*)((const char*)(gbase) + (voff)[_i]), (LAS unsigned*)(lds + (bufoff) + ldsw + _i * 8192), 16, 0, 0); } while (0)
; #define PG8_BAR __builtin_amdgcn_s_barrier()
; template <class Epi>
; __device__ __forceinline__ void gemm_phase(LAS unsigned char* lds, const Gemm g, const StaticOrder& S, const Epi& E) {
;     const int tid = otid(), wid = __builtin_amdgcn_readfirstlane(tid >> 6), lane = tid & 63, wr = wid >> 2, wc = wid & 3, fr = lane & 15, fq = lane >> 4;
;     const int K = g.K, nt = K / BK;
;     unsigned voffA[2], voffB[2];
; #pragma unroll
;     for (int i = 0; i < 2; ++i) { int R, C; stage_rc(tid * 16 + i * 8192, R, C); const int Rb = Epi::PERM ? ((R & ~31) + perm32(R & 31)) : R;
;         voffA[i] = (unsigned)(R * K + C) * 2u; voffB[i] = (unsigned)(Rb * K + C) * 2u; }
;     const size_t kstep = (size_t)(BK * 2);
;     const size_t hstep = (size_t)HALF * K * 2;
;     const size_t tstep = 2 * hstep;
;     const unsigned ldsw = (unsigned)wid * 1024u;
;     const int aoff = lds_byte(wr * 64 + fr, fq * 8), boff = lds_byte(wc * 32 + fr, fq * 8);
;     ...
;     Unit cur, nxt; int ui = 0;
;     if (!S.next(0, cur)) return;
;     f32x4 acc[2][2][4][2];
; #pragma unroll
;     for (int a = 0; a < 2; ++a)
; #pragma unroll
;         for (int b = 0; b < 2; ++b)
; #pragma unroll
;             for (int m = 0; m < 4; ++m)
; #pragma unroll
;                 for (int n = 0; n < 2; ++n) acc[a][b][m][n] = (f32x4){0.f, 0.f, 0.f, 0.f};
;     bf16x8 At[4][2], B0[2][2], B1[2][2];
;     const char* cA = (const char*)g.A + (size_t)cur.pm * tstep; const char* cB = (const char*)g.Bt + (size_t)cur.pn * tstep;
;     PG8_STAGE(PG8_SB(0, 0), cB, voffB); PG8_STAGE(PG8_SA(0, 0), cA, voffA); PG8_STAGE(PG8_SB(0, 1), cB + hstep, voffB); PG8_STAGE(PG8_SA(0, 1), cA + hstep, voffA);
;     if (wr == 1) PG8_BAR;
.LBB0_358:
	s_andn2_b64 vcc, exec, s[0:1]
	s_cbranch_vccnz .LBB0_414
	v_bfe_i32 v1, v3, 27, 1
	s_waitcnt vmcnt(0)
	v_lshlrev_b32_e32 v4, 4, v3
	v_lshrrev_b32_e32 v1, 22, v1
	v_add_u32_e32 v1, v4, v1
	v_and_b32_e32 v1, 0xfffffc00, v1
	v_sub_u32_e32 v1, v4, v1
	v_lshrrev_b32_e32 v2, 4, v1
	v_bitop3_b32 v2, v2, v1, 32 bitop3:0x6c
	v_ashrrev_i32_e32 v1, 31, v1
	v_lshrrev_b32_e32 v1, 26, v1
	v_ashrrev_i32_e32 v0, 31, v3
	v_add_u32_e32 v1, v2, v1
	v_lshrrev_b32_e32 v0, 26, v0
	v_ashrrev_i32_e32 v1, 6, v1
	v_add_u32_e32 v0, v3, v0
	v_mul_i32_i24_e32 v7, 64, v1
	v_ashrrev_i32_e32 v0, 6, v0
	v_sub_u32_e32 v2, v2, v7
	v_lshlrev_b32_e32 v5, 3, v0
	v_lshlrev_b32_e32 v6, 5, v0
	v_ashrrev_i16_sdwa v2, v236, sext(v2) dst_sel:DWORD dst_unused:UNUSED_PAD src0_sel:DWORD src1_sel:BYTE_0
	v_and_b32_e32 v5, -16, v5
	v_and_b32_e32 v6, 32, v6
	v_bfe_i32 v2, v2, 0, 16
	v_add_u32_e32 v5, v1, v5
	v_and_b32_e32 v9, 3, v1
	s_mov_b32 s1, 0xfffe0
	v_add_lshl_u32 v6, v6, v2, 1
	v_lshlrev_b32_e32 v7, 1, v5
	v_lshrrev_b32_e32 v8, 2, v5
	v_and_or_b32 v9, v5, s1, v9
	v_lshl_add_u32 v128, v5, 12, v6
	v_add_u32_e32 v5, 0x2000, v4
	v_ashrrev_i32_e32 v4, 31, v5
	v_lshrrev_b32_e32 v4, 22, v4
	v_and_b32_e32 v7, 24, v7
	v_and_b32_e32 v8, 4, v8
	v_add_u32_e32 v4, v5, v4
	v_or3_b32 v7, v9, v8, v7
	v_ashrrev_i32_e32 v4, 10, v4
	v_lshl_add_u32 v184, v7, 12, v6
	v_mul_i32_i24_e32 v6, 0x400, v4
	v_sub_u32_e32 v5, v5, v6
	v_lshrrev_b32_e32 v6, 4, v5
	v_bitop3_b32 v6, v6, v5, 32 bitop3:0x6c
	v_lshlrev_b32_e32 v5, 3, v4
	v_and_b32_e32 v7, -16, v5
	v_ashrrev_i32_e32 v5, 31, v6
	v_lshrrev_b32_e32 v5, 26, v5
	v_add_u32_e32 v8, v6, v5
	v_ashrrev_i32_e32 v5, 6, v8
	v_add_u32_e32 v7, v5, v7
	v_and_b32_e32 v11, 3, v5
	v_and_or_b32 v11, v7, s1, v11
	s_ashr_i32 s1, s37, 6
	s_ashr_i32 s25, s24, 31
	s_ashr_i32 s9, s8, 31
	s_ashr_i32 s0, s37, 8
	v_and_b32_e32 v8, 0xc0, v8
	s_lshl_b32 s38, s1, 10
	s_lshl_b64 s[6:7], s[24:25], 20
	s_lshl_b64 s[18:19], s[8:9], 20
	v_sub_u32_e32 v6, v6, v8
	s_add_u32 s28, s90, s18
	v_lshlrev_b32_e32 v9, 5, v4
	v_ashrrev_i16_sdwa v6, v236, sext(v6) dst_sel:DWORD dst_unused:UNUSED_PAD src0_sel:DWORD src1_sel:BYTE_0
	v_lshlrev_b32_e32 v8, 1, v7
	v_lshrrev_b32_e32 v10, 2, v7
	s_addc_u32 s29, s91, s19
	s_add_i32 s25, s38, 0
	v_and_b32_e32 v9, 32, v9
	v_bfe_i32 v6, v6, 0, 16
	v_and_b32_e32 v8, 24, v8
	v_and_b32_e32 v10, 4, v10
	s_add_i32 m0, s25, 0x10000
	v_or3_b32 v8, v11, v10, v8
	v_add_lshl_u32 v9, v9, v6, 1
	global_load_lds_dwordx4 v184, s[28:29]
	s_add_i32 m0, s25, 0x12000
	v_lshl_add_u32 v132, v8, 12, v9
	s_add_u32 s26, s87, s6
	global_load_lds_dwordx4 v132, s[28:29]
	s_addc_u32 s27, s76, s7
	s_mov_b32 m0, s25
	s_add_i32 s39, s25, 0x2000
	v_lshl_add_u32 v130, v7, 12, v9
	global_load_lds_dwordx4 v128, s[26:27]
	s_mov_b32 m0, s39
	s_add_u32 s6, s28, 0x80000
	global_load_lds_dwordx4 v130, s[26:27]
	s_addc_u32 s7, s29, 0
	s_add_i32 m0, s25, 0x14000
	s_nop 0
	global_load_lds_dwordx4 v184, s[6:7]
	s_add_i32 m0, s25, 0x16000
	s_nop 0
	global_load_lds_dwordx4 v132, s[6:7]
	s_add_u32 s6, s26, 0x80000
	s_addc_u32 s7, s27, 0
	s_add_i32 s40, s25, 0x4000
	s_mov_b32 m0, s40
	s_add_i32 s41, s25, 0x6000
	global_load_lds_dwordx4 v128, s[6:7]
	s_mov_b32 m0, s41
	s_cmp_lg_u32 s0, 1
	global_load_lds_dwordx4 v130, s[6:7]
	s_cbranch_scc1 .LBB0_361
	s_setprio 1
	s_barrier

; #define PG8_STAGE(bufoff, gbase, voff) do { _Pragma("unroll") for (int _i = 0; _i < 2; ++_i) \
;         __builtin_amdgcn_global_load_lds((const unsigned*)((const char*)(gbase) + (voff)[_i]), (LAS unsigned*)(lds + (bufoff) + ldsw + _i * 8192), 16, 0, 0); } while (0)
; #define PG8_LDA(dst, b, h) do { _Pragma("unroll") for (int m = 0; m < 4; ++m) _Pragma("unroll") for (int k = 0; k < 2; ++k) dst[m][k] = *(const LAS bf16x8*)(lds + PG8_SA(b, h) + aoff + m * 2048 + k * 1024); } while (0)
; #define PG8_LDB(dst, b, h) do { _Pragma("unroll") for (int n = 0; n < 2; ++n) _Pragma("unroll") for (int k = 0; k < 2; ++k) dst[n][k] = *(const LAS bf16x8*)(lds + PG8_SB(b, h) + boff + n * 2048 + k * 1024); } while (0)
; #define PG8_MMA(ai, bj, At, Bt) do { __builtin_amdgcn_s_setprio(1); _Pragma("unroll") for (int m = 0; m < 4; ++m) _Pragma("unroll") for (int n = 0; n < 2; ++n) _Pragma("unroll") for (int k = 0; k < 2; ++k) \
;         acc[ai][bj][m][n] = __builtin_amdgcn_mfma_f32_16x16x32_bf16(Bt[n][k], At[m][k], acc[ai][bj][m][n], 0, 0, 0); __builtin_amdgcn_s_setprio(0); } while (0)
; #define PG8_WAIT_L(n) asm volatile("s_waitcnt lgkmcnt(" #n ")" ::: "memory")
; #define PG8_BAR __builtin_amdgcn_s_barrier()
; #define PG8_SCHED __builtin_amdgcn_sched_barrier(0)
; template <class Epi>
; __device__ __forceinline__ void gemm_phase(LAS unsigned char* lds, const Gemm g, const StaticOrder& S, const Epi& E) {
;     ...
;         for (int t = 0; t < nt; t += 2) {
;             const bool last = (t == nt - 2);
;             const char* a1 = cA + (size_t)(t + 1) * kstep;
;             const char* a2 = last ? nA : cA + (size_t)(t + 2) * kstep; const char* b2 = last ? nB : cB + (size_t)(t + 2) * kstep;
;             const char* a3 = a2 + kstep; const char* b3 = b2 + kstep;
;             PG8_LDB(B0, 0, 0); PG8_SCHED; PG8_LDA(At, 0, 0); PG8_STAGE(PG8_SA(1, 1), a1 + hstep, voffA);
;             PG8_WAIT_L(8); PG8_BAR; PG8_WAIT_L(0); PG8_MMA(0, 0, At, B0); PG8_BAR; PG8_SCHED;
;             PG8_LDB(B1, 0, 1); PG8_STAGE(PG8_SB(0, 0), b2, voffB);
;             PG8_BAR; PG8_WAIT_L(0); PG8_MMA(0, 1, At, B1); PG8_BAR;
;             PG8_LDA(At, 0, 1); PG8_STAGE(PG8_SA(0, 0), a2, voffA);
;             PG8_BAR; PG8_WAIT_L(0); PG8_MMA(1, 0, At, B0); PG8_BAR; PG8_SCHED;
.LBB0_366:
	s_add_u32 s28, s26, 0xfff80080
	s_addc_u32 s29, s27, -1
	s_add_i32 s47, 0, 0x10000
	v_add_u32_e32 v154, s47, v143
	ds_read_b128 v[138:141], v154
	ds_read_b128 v[146:149], v154 offset:1024
	ds_read_b128 v[150:153], v154 offset:2048
	ds_read_b128 v[154:157], v154 offset:3072
	s_cmp_eq_u32 s43, 28
	s_cselect_b32 s31, s3, s29
	s_cselect_b32 s30, s9, s28
	s_cselect_b32 s29, s1, s35
	s_cselect_b32 s28, s19, s34
	v_lshl_add_u64 v[182:183], s[26:27], 0, v[134:135]
	s_add_i32 m0, s25, 0xc000
	ds_read_b128 v[158:161], v145
	ds_read_b128 v[162:165], v145 offset:1024
	ds_read_b128 v[166:169], v145 offset:2048
	ds_read_b128 v[170:173], v145 offset:3072
	ds_read_b128 v[174:177], v145 offset:4096
	ds_read_b128 v[178:181], v145 offset:5120
	ds_read_b128 v[204:207], v145 offset:6144
	ds_read_b128 v[208:211], v145 offset:7168
	global_load_lds_dwordx4 v[182:183], off
	v_lshl_add_u64 v[182:183], s[26:27], 0, v[136:137]
	s_add_i32 m0, s25, 0xe000
	s_nop 0
	global_load_lds_dwordx4 v[182:183], off
	s_waitcnt lgkmcnt(8)
	s_barrier
	s_waitcnt lgkmcnt(0)
	s_waitcnt lgkmcnt(0)
	v_mfma_f32_16x16x32_bf16 v[124:127], v[138:141], v[158:161], v[124:127]
	v_mfma_f32_16x16x32_bf16 v[124:127], v[146:149], v[162:165], v[124:127]
	v_mfma_f32_16x16x32_bf16 v[108:111], v[138:141], v[166:169], v[108:111]
	v_mfma_f32_16x16x32_bf16 v[108:111], v[146:149], v[170:173], v[108:111]
	v_mfma_f32_16x16x32_bf16 v[92:95], v[138:141], v[174:177], v[92:95]
	v_mfma_f32_16x16x32_bf16 v[92:95], v[146:149], v[178:181], v[92:95]
	v_mfma_f32_16x16x32_bf16 v[76:79], v[138:141], v[204:207], v[76:79]
	v_mfma_f32_16x16x32_bf16 v[76:79], v[146:149], v[208:211], v[76:79]
	v_mfma_f32_16x16x32_bf16 v[72:75], v[150:153], v[204:207], v[72:75]
	v_mfma_f32_16x16x32_bf16 v[72:75], v[154:157], v[208:211], v[72:75]
	v_mfma_f32_16x16x32_bf16 v[88:91], v[150:153], v[174:177], v[88:91]
	v_mfma_f32_16x16x32_bf16 v[88:91], v[154:157], v[178:181], v[88:91]
	v_mfma_f32_16x16x32_bf16 v[104:107], v[150:153], v[166:169], v[104:107]
	v_mfma_f32_16x16x32_bf16 v[104:107], v[154:157], v[170:173], v[104:107]
	v_mfma_f32_16x16x32_bf16 v[120:123], v[150:153], v[158:161], v[120:123]
	v_mfma_f32_16x16x32_bf16 v[120:123], v[154:157], v[162:165], v[120:123]
	s_barrier
	s_add_i32 s52, 0, 0x14000
	v_add_u32_e32 v182, s52, v143
	s_add_i32 s47, s47, s38
	ds_read_b128 v[212:215], v182
	ds_read_b128 v[216:219], v182 offset:1024
	ds_read_b128 v[220:223], v182 offset:2048
	ds_read_b128 v[224:227], v182 offset:3072
	v_lshl_add_u64 v[182:183], s[28:29], 0, v[184:185]
	s_mov_b32 m0, s47
	v_lshl_add_u64 v[188:189], s[28:29], 0, v[132:133]
	global_load_lds_dwordx4 v[182:183], off
	s_add_i32 m0, s47, 0x2000
	s_nop 0
	global_load_lds_dwordx4 v[188:189], off
	s_barrier
	s_waitcnt lgkmcnt(0)
	s_waitcnt lgkmcnt(0)
	v_mfma_f32_16x16x32_bf16 v[116:119], v[212:215], v[158:161], v[116:119]
	v_mfma_f32_16x16x32_bf16 v[116:119], v[216:219], v[162:165], v[116:119]
	v_mfma_f32_16x16x32_bf16 v[100:103], v[212:215], v[166:169], v[100:103]
	v_mfma_f32_16x16x32_bf16 v[100:103], v[216:219], v[170:173], v[100:103]
	v_mfma_f32_16x16x32_bf16 v[84:87], v[212:215], v[174:177], v[84:87]
	v_mfma_f32_16x16x32_bf16 v[84:87], v[216:219], v[178:181], v[84:87]
	v_mfma_f32_16x16x32_bf16 v[68:71], v[212:215], v[204:207], v[68:71]
	v_mfma_f32_16x16x32_bf16 v[68:71], v[216:219], v[208:211], v[68:71]
	v_mfma_f32_16x16x32_bf16 v[64:67], v[220:223], v[204:207], v[64:67]
	v_mfma_f32_16x16x32_bf16 v[64:67], v[224:227], v[208:211], v[64:67]
	v_mfma_f32_16x16x32_bf16 v[80:83], v[220:223], v[174:177], v[80:83]
	v_mfma_f32_16x16x32_bf16 v[80:83], v[224:227], v[178:181], v[80:83]
	v_mfma_f32_16x16x32_bf16 v[96:99], v[220:223], v[166:169], v[96:99]
	v_mfma_f32_16x16x32_bf16 v[96:99], v[224:227], v[170:173], v[96:99]
	v_mfma_f32_16x16x32_bf16 v[112:115], v[220:223], v[158:161], v[112:115]
	v_mfma_f32_16x16x32_bf16 v[112:115], v[224:227], v[162:165], v[112:115]
	s_mov_b32 m0, s25
	v_lshl_add_u64 v[190:191], s[30:31], 0, v[128:129]
	s_barrier
	ds_read_b128 v[158:161], v145 offset:16384
	ds_read_b128 v[162:165], v145 offset:17408
	ds_read_b128 v[166:169], v145 offset:18432
	ds_read_b128 v[170:173], v145 offset:19456
	ds_read_b128 v[174:177], v145 offset:20480
	ds_read_b128 v[178:181], v145 offset:21504
	ds_read_b128 v[204:207], v145 offset:22528
	ds_read_b128 v[208:211], v145 offset:23552
	global_load_lds_dwordx4 v[190:191], off
	v_lshl_add_u64 v[192:193], s[30:31], 0, v[130:131]
	s_mov_b32 m0, s39
	s_nop 0
	global_load_lds_dwordx4 v[192:193], off
	s_barrier
	s_waitcnt lgkmcnt(0)
	s_waitcnt lgkmcnt(0)
	v_mfma_f32_16x16x32_bf16 v[60:63], v[138:141], v[158:161], v[60:63]
	v_mfma_f32_16x16x32_bf16 v[60:63], v[146:149], v[162:165], v[60:63]
	v_mfma_f32_16x16x32_bf16 v[44:47], v[138:141], v[166:169], v[44:47]
	v_mfma_f32_16x16x32_bf16 v[44:47], v[146:149], v[170:173], v[44:47]
	v_mfma_f32_16x16x32_bf16 v[28:31], v[138:141], v[174:177], v[28:31]
	v_mfma_f32_16x16x32_bf16 v[28:31], v[146:149], v[178:181], v[28:31]
	v_mfma_f32_16x16x32_bf16 v[12:15], v[138:141], v[204:207], v[12:15]
	v_mfma_f32_16x16x32_bf16 v[12:15], v[146:149], v[208:211], v[12:15]
	v_mfma_f32_16x16x32_bf16 v[8:11], v[150:153], v[204:207], v[8:11]
	v_mfma_f32_16x16x32_bf16 v[8:11], v[154:157], v[208:211], v[8:11]
	v_mfma_f32_16x16x32_bf16 v[24:27], v[150:153], v[174:177], v[24:27]
	v_mfma_f32_16x16x32_bf16 v[24:27], v[154:157], v[178:181], v[24:27]
	v_mfma_f32_16x16x32_bf16 v[40:43], v[150:153], v[166:169], v[40:43]
	v_mfma_f32_16x16x32_bf16 v[40:43], v[154:157], v[170:173], v[40:43]
	v_mfma_f32_16x16x32_bf16 v[56:59], v[150:153], v[158:161], v[56:59]
	v_mfma_f32_16x16x32_bf16 v[56:59], v[154:157], v[162:165], v[56:59]
	s_barrier
; #define PG8_STAGE(bufoff, gbase, voff) do { _Pragma("unroll") for (int _i = 0; _i < 2; ++_i) \
;         __builtin_amdgcn_global_load_lds((const unsigned*)((const char*)(gbase) + (voff)[_i]), (LAS unsigned*)(lds + (bufoff) + ldsw + _i * 8192), 16, 0, 0); } while (0)
; #define PG8_LDA(dst, b, h) do { _Pragma("unroll") for (int m = 0; m < 4; ++m) _Pragma("unroll") for (int k = 0; k < 2; ++k) dst[m][k] = *(const LAS bf16x8*)(lds + PG8_SA(b, h) + aoff + m * 2048 + k * 1024); } while (0)
; #define PG8_LDB(dst, b, h) do { _Pragma("unroll") for (int n = 0; n < 2; ++n) _Pragma("unroll") for (int k = 0; k < 2; ++k) dst[n][k] = *(const LAS bf16x8*)(lds + PG8_SB(b, h) + boff + n * 2048 + k * 1024); } while (0)
; #define PG8_MMA(ai, bj, At, Bt) do { __builtin_amdgcn_s_setprio(1); _Pragma("unroll") for (int m = 0; m < 4; ++m) _Pragma("unroll") for (int n = 0; n < 2; ++n) _Pragma("unroll") for (int k = 0; k < 2; ++k) \
;         acc[ai][bj][m][n] = __builtin_amdgcn_mfma_f32_16x16x32_bf16(Bt[n][k], At[m][k], acc[ai][bj][m][n], 0, 0, 0); __builtin_amdgcn_s_setprio(0); } while (0)
; #define PG8_WAIT_V(n) asm volatile("s_waitcnt vmcnt(" #n ")" ::: "memory")
; #define PG8_WAIT_L(n) asm volatile("s_waitcnt lgkmcnt(" #n ")" ::: "memory")
; #define PG8_BAR __builtin_amdgcn_s_barrier()
; #define PG8_SCHED __builtin_amdgcn_sched_barrier(0)
; template <class Epi>
; __device__ __forceinline__ void gemm_phase(LAS unsigned char* lds, const Gemm g, const StaticOrder& S, const Epi& E) {
;     ...
;             PG8_STAGE(PG8_SB(0, 1), b2 + hstep, voffB);
;             PG8_WAIT_V(6); PG8_BAR; PG8_MMA(1, 1, At, B1); PG8_BAR;
;             PG8_LDB(B0, 1, 0); PG8_SCHED; PG8_LDA(At, 1, 0); PG8_STAGE(PG8_SA(0, 1), a2 + hstep, voffA);
;             PG8_WAIT_L(8); PG8_BAR; PG8_WAIT_L(0); PG8_MMA(0, 0, At, B0); PG8_BAR; PG8_SCHED;
;             PG8_LDB(B1, 1, 1); PG8_STAGE(PG8_SB(1, 0), b3, voffB);
;             PG8_BAR; PG8_WAIT_L(0); PG8_MMA(0, 1, At, B1); PG8_BAR;
;             PG8_LDA(At, 1, 1); PG8_STAGE(PG8_SA(1, 0), a3, voffA);
;             PG8_BAR; PG8_WAIT_L(0); PG8_MMA(1, 0, At, B0); PG8_BAR; PG8_SCHED;
	s_add_u32 s50, s28, 0x80000
	s_addc_u32 s51, s29, 0
	s_add_i32 s47, s52, s38
	v_lshl_add_u64 v[138:139], s[50:51], 0, v[184:185]
	s_mov_b32 m0, s47
	s_nop 0
	global_load_lds_dwordx4 v[138:139], off
	v_lshl_add_u64 v[138:139], s[50:51], 0, v[132:133]
	s_add_i32 m0, s47, 0x2000
	s_nop 0
	global_load_lds_dwordx4 v[138:139], off
	s_waitcnt vmcnt(6)
	s_barrier
	v_mfma_f32_16x16x32_bf16 v[52:55], v[212:215], v[158:161], v[52:55]
	v_mfma_f32_16x16x32_bf16 v[52:55], v[216:219], v[162:165], v[52:55]
	v_mfma_f32_16x16x32_bf16 v[36:39], v[212:215], v[166:169], v[36:39]
	v_mfma_f32_16x16x32_bf16 v[36:39], v[216:219], v[170:173], v[36:39]
	v_mfma_f32_16x16x32_bf16 v[20:23], v[212:215], v[174:177], v[20:23]
	v_mfma_f32_16x16x32_bf16 v[20:23], v[216:219], v[178:181], v[20:23]
	v_mfma_f32_16x16x32_bf16 v[4:7], v[212:215], v[204:207], v[4:7]
	v_mfma_f32_16x16x32_bf16 v[4:7], v[216:219], v[208:211], v[4:7]
	v_mfma_f32_16x16x32_bf16 v[0:3], v[220:223], v[204:207], v[0:3]
	v_mfma_f32_16x16x32_bf16 v[0:3], v[224:227], v[208:211], v[0:3]
	v_mfma_f32_16x16x32_bf16 v[16:19], v[220:223], v[174:177], v[16:19]
	v_mfma_f32_16x16x32_bf16 v[16:19], v[224:227], v[178:181], v[16:19]
	v_mfma_f32_16x16x32_bf16 v[32:35], v[220:223], v[166:169], v[32:35]
	v_mfma_f32_16x16x32_bf16 v[32:35], v[224:227], v[170:173], v[32:35]
	v_mfma_f32_16x16x32_bf16 v[48:51], v[220:223], v[158:161], v[48:51]
	v_mfma_f32_16x16x32_bf16 v[48:51], v[224:227], v[162:165], v[48:51]
	s_add_i32 s47, 0, 0x18000
	v_add_u32_e32 v154, s47, v143
	s_barrier
	ds_read_b128 v[138:141], v154
	ds_read_b128 v[146:149], v154 offset:1024
	ds_read_b128 v[150:153], v154 offset:2048
	ds_read_b128 v[154:157], v154 offset:3072
	s_add_u32 s30, s30, 0x80000
	s_addc_u32 s31, s31, 0
	s_mov_b32 m0, s40
	v_lshl_add_u64 v[212:213], s[30:31], 0, v[128:129]
	ds_read_b128 v[158:161], v145 offset:32768
	ds_read_b128 v[162:165], v145 offset:33792
	ds_read_b128 v[166:169], v145 offset:34816
	ds_read_b128 v[170:173], v145 offset:35840
	ds_read_b128 v[174:177], v145 offset:36864
	ds_read_b128 v[178:181], v145 offset:37888
	ds_read_b128 v[204:207], v145 offset:38912
	ds_read_b128 v[208:211], v145 offset:39936
	global_load_lds_dwordx4 v[212:213], off
	v_lshl_add_u64 v[212:213], s[30:31], 0, v[130:131]
	s_mov_b32 m0, s41
	s_nop 0
	global_load_lds_dwordx4 v[212:213], off
	s_waitcnt lgkmcnt(8)
	s_barrier
	s_waitcnt lgkmcnt(0)
	s_waitcnt lgkmcnt(0)
	v_mfma_f32_16x16x32_bf16 v[124:127], v[138:141], v[158:161], v[124:127]
	v_mfma_f32_16x16x32_bf16 v[124:127], v[146:149], v[162:165], v[124:127]
	v_mfma_f32_16x16x32_bf16 v[108:111], v[138:141], v[166:169], v[108:111]
	v_mfma_f32_16x16x32_bf16 v[108:111], v[146:149], v[170:173], v[108:111]
	v_mfma_f32_16x16x32_bf16 v[92:95], v[138:141], v[174:177], v[92:95]
	v_mfma_f32_16x16x32_bf16 v[92:95], v[146:149], v[178:181], v[92:95]
	v_mfma_f32_16x16x32_bf16 v[76:79], v[138:141], v[204:207], v[76:79]
	v_mfma_f32_16x16x32_bf16 v[76:79], v[146:149], v[208:211], v[76:79]
	v_mfma_f32_16x16x32_bf16 v[72:75], v[150:153], v[204:207], v[72:75]
	v_mfma_f32_16x16x32_bf16 v[72:75], v[154:157], v[208:211], v[72:75]
	v_mfma_f32_16x16x32_bf16 v[88:91], v[150:153], v[174:177], v[88:91]
	v_mfma_f32_16x16x32_bf16 v[88:91], v[154:157], v[178:181], v[88:91]
	v_mfma_f32_16x16x32_bf16 v[104:107], v[150:153], v[166:169], v[104:107]
	v_mfma_f32_16x16x32_bf16 v[104:107], v[154:157], v[170:173], v[104:107]
	v_mfma_f32_16x16x32_bf16 v[120:123], v[150:153], v[158:161], v[120:123]
	v_mfma_f32_16x16x32_bf16 v[120:123], v[154:157], v[162:165], v[120:123]
	s_barrier
	s_add_i32 s30, 0, 0x1c000
	s_add_i32 s31, s47, s38
	v_add_u32_e32 v187, s30, v143
	v_lshl_add_u64 v[182:183], v[182:183], 0, s[58:59]
	s_mov_b32 m0, s31
	ds_read_b128 v[212:215], v187
	ds_read_b128 v[216:219], v187 offset:1024
	ds_read_b128 v[220:223], v187 offset:2048
	ds_read_b128 v[224:227], v187 offset:3072
	global_load_lds_dwordx4 v[182:183], off
	v_lshl_add_u64 v[182:183], v[188:189], 0, s[58:59]
	s_add_i32 m0, s31, 0x2000
	s_nop 0
	global_load_lds_dwordx4 v[182:183], off
	s_barrier
; #define PG8_STAGE(bufoff, gbase, voff) do { _Pragma("unroll") for (int _i = 0; _i < 2; ++_i) \
;         __builtin_amdgcn_global_load_lds((const unsigned*)((const char*)(gbase) + (voff)[_i]), (LAS unsigned*)(lds + (bufoff) + ldsw + _i * 8192), 16, 0, 0); } while (0)
; #define PG8_LDA(dst, b, h) do { _Pragma("unroll") for (int m = 0; m < 4; ++m) _Pragma("unroll") for (int k = 0; k < 2; ++k) dst[m][k] = *(const LAS bf16x8*)(lds + PG8_SA(b, h) + aoff + m * 2048 + k * 1024); } while (0)
; #define PG8_LDB(dst, b, h) do { _Pragma("unroll") for (int n = 0; n < 2; ++n) _Pragma("unroll") for (int k = 0; k < 2; ++k) dst[n][k] = *(const LAS bf16x8*)(lds + PG8_SB(b, h) + boff + n * 2048 + k * 1024); } while (0)
; #define PG8_MMA(ai, bj, At, Bt) do { __builtin_amdgcn_s_setprio(1); _Pragma("unroll") for (int m = 0; m < 4; ++m) _Pragma("unroll") for (int n = 0; n < 2; ++n) _Pragma("unroll") for (int k = 0; k < 2; ++k) \
;         acc[ai][bj][m][n] = __builtin_amdgcn_mfma_f32_16x16x32_bf16(Bt[n][k], At[m][k], acc[ai][bj][m][n], 0, 0, 0); __builtin_amdgcn_s_setprio(0); } while (0)
; template <class Epi>
; __device__ __forceinline__ void gemm_phase(LAS unsigned char* lds, const Gemm g, const StaticOrder& S, const Epi& E) {
;     ...
;             PG8_LDB(B1, 1, 1); PG8_STAGE(PG8_SB(1, 0), b3, voffB);
;             PG8_BAR; PG8_WAIT_L(0); PG8_MMA(0, 1, At, B1); PG8_BAR;
;             PG8_LDA(At, 1, 1); PG8_STAGE(PG8_SA(1, 0), a3, voffA);
;             PG8_BAR; PG8_WAIT_L(0); PG8_MMA(1, 0, At, B0); PG8_BAR; PG8_SCHED;
;             PG8_STAGE(PG8_SB(1, 1), b3 + hstep, voffB);
;             PG8_WAIT_V(6); PG8_BAR; PG8_MMA(1, 1, At, B1); PG8_BAR;
;     __device__ __forceinline__ void operator()(const Acc& acc, const Unit& u, int wr, int wc, int fr, int fq) const {
;         const int pn = u.pn; const int row0 = u.pm * 256 + wr * 64 + fr;
;         bf16_t* base; int ld, cb; bool act;
;         if (vt) { base = vt; ld = TH; cb = 256 * pn; act = false; }
;         else if (gmode) { base = g; ld = 4096; cb = 256 * pn; act = true; }
;         else if (pn < 8) { base = zna; ld = 2048; cb = 256 * pn; act = false; }
;         else if (pn < 16) { base = zqk; ld = 2048; cb = 256 * (pn - 8); act = false; }
;         else if (pn < 24) { base = vo; ld = 2048; cb = 256 * (pn - 16); act = pn >= 20; }
;         else { base = g; ld = 4096; cb = 256 * (pn - 24); act = true; }
	s_waitcnt lgkmcnt(0)
	s_waitcnt lgkmcnt(0)
	v_mfma_f32_16x16x32_bf16 v[116:119], v[212:215], v[158:161], v[116:119]
	v_mfma_f32_16x16x32_bf16 v[116:119], v[216:219], v[162:165], v[116:119]
	v_mfma_f32_16x16x32_bf16 v[100:103], v[212:215], v[166:169], v[100:103]
	v_mfma_f32_16x16x32_bf16 v[100:103], v[216:219], v[170:173], v[100:103]
	v_mfma_f32_16x16x32_bf16 v[84:87], v[212:215], v[174:177], v[84:87]
	v_mfma_f32_16x16x32_bf16 v[84:87], v[216:219], v[178:181], v[84:87]
	v_mfma_f32_16x16x32_bf16 v[68:71], v[212:215], v[204:207], v[68:71]
	v_mfma_f32_16x16x32_bf16 v[68:71], v[216:219], v[208:211], v[68:71]
	v_mfma_f32_16x16x32_bf16 v[64:67], v[220:223], v[204:207], v[64:67]
	v_mfma_f32_16x16x32_bf16 v[64:67], v[224:227], v[208:211], v[64:67]
	v_mfma_f32_16x16x32_bf16 v[80:83], v[220:223], v[174:177], v[80:83]
	v_mfma_f32_16x16x32_bf16 v[80:83], v[224:227], v[178:181], v[80:83]
	v_mfma_f32_16x16x32_bf16 v[96:99], v[220:223], v[166:169], v[96:99]
	v_mfma_f32_16x16x32_bf16 v[96:99], v[224:227], v[170:173], v[96:99]
	v_mfma_f32_16x16x32_bf16 v[112:115], v[220:223], v[158:161], v[112:115]
	v_mfma_f32_16x16x32_bf16 v[112:115], v[224:227], v[162:165], v[112:115]
	s_mov_b32 m0, s42
	v_lshl_add_u64 v[182:183], v[190:191], 0, s[58:59]
	s_barrier
	ds_read_b128 v[158:161], v145 offset:49152
	ds_read_b128 v[162:165], v145 offset:50176
	ds_read_b128 v[166:169], v145 offset:51200
	ds_read_b128 v[170:173], v145 offset:52224
	ds_read_b128 v[174:177], v145 offset:53248
	ds_read_b128 v[178:181], v145 offset:54272
	ds_read_b128 v[204:207], v145 offset:55296
	ds_read_b128 v[208:211], v145 offset:56320
	global_load_lds_dwordx4 v[182:183], off
	v_lshl_add_u64 v[182:183], v[192:193], 0, s[58:59]
	s_mov_b32 m0, s44
	s_nop 0
	global_load_lds_dwordx4 v[182:183], off
	s_barrier
	s_waitcnt lgkmcnt(0)
	s_waitcnt lgkmcnt(0)
	v_mfma_f32_16x16x32_bf16 v[60:63], v[138:141], v[158:161], v[60:63]
	v_mfma_f32_16x16x32_bf16 v[60:63], v[146:149], v[162:165], v[60:63]
	v_mfma_f32_16x16x32_bf16 v[44:47], v[138:141], v[166:169], v[44:47]
	v_mfma_f32_16x16x32_bf16 v[44:47], v[146:149], v[170:173], v[44:47]
	v_mfma_f32_16x16x32_bf16 v[28:31], v[138:141], v[174:177], v[28:31]
	v_mfma_f32_16x16x32_bf16 v[28:31], v[146:149], v[178:181], v[28:31]
	v_mfma_f32_16x16x32_bf16 v[12:15], v[138:141], v[204:207], v[12:15]
	v_mfma_f32_16x16x32_bf16 v[12:15], v[146:149], v[208:211], v[12:15]
	v_mfma_f32_16x16x32_bf16 v[8:11], v[150:153], v[204:207], v[8:11]
	v_mfma_f32_16x16x32_bf16 v[8:11], v[154:157], v[208:211], v[8:11]
	v_mfma_f32_16x16x32_bf16 v[24:27], v[150:153], v[174:177], v[24:27]
	v_mfma_f32_16x16x32_bf16 v[24:27], v[154:157], v[178:181], v[24:27]
	v_mfma_f32_16x16x32_bf16 v[40:43], v[150:153], v[166:169], v[40:43]
	v_mfma_f32_16x16x32_bf16 v[40:43], v[154:157], v[170:173], v[40:43]
	v_mfma_f32_16x16x32_bf16 v[56:59], v[150:153], v[158:161], v[56:59]
	v_mfma_f32_16x16x32_bf16 v[56:59], v[154:157], v[162:165], v[56:59]
	s_barrier
	s_add_u32 s28, s28, 0x80080
	s_addc_u32 s29, s29, 0
	s_add_i32 s30, s30, s38
	v_lshl_add_u64 v[138:139], s[28:29], 0, v[184:185]
	s_mov_b32 m0, s30
	s_nop 0
	global_load_lds_dwordx4 v[138:139], off
	v_lshl_add_u64 v[138:139], s[28:29], 0, v[132:133]
	s_add_i32 m0, s30, 0x2000
	s_nop 0
	global_load_lds_dwordx4 v[138:139], off
	s_waitcnt vmcnt(6)
	s_barrier
	v_mfma_f32_16x16x32_bf16 v[52:55], v[212:215], v[158:161], v[52:55]
	v_mfma_f32_16x16x32_bf16 v[52:55], v[216:219], v[162:165], v[52:55]
	v_mfma_f32_16x16x32_bf16 v[36:39], v[212:215], v[166:169], v[36:39]
	v_mfma_f32_16x16x32_bf16 v[36:39], v[216:219], v[170:173], v[36:39]
	v_mfma_f32_16x16x32_bf16 v[20:23], v[212:215], v[174:177], v[20:23]
	v_mfma_f32_16x16x32_bf16 v[20:23], v[216:219], v[178:181], v[20:23]
	v_mfma_f32_16x16x32_bf16 v[4:7], v[212:215], v[204:207], v[4:7]
	v_mfma_f32_16x16x32_bf16 v[4:7], v[216:219], v[208:211], v[4:7]
	v_mfma_f32_16x16x32_bf16 v[0:3], v[220:223], v[204:207], v[0:3]
	v_mfma_f32_16x16x32_bf16 v[0:3], v[224:227], v[208:211], v[0:3]
	v_mfma_f32_16x16x32_bf16 v[16:19], v[220:223], v[174:177], v[16:19]
	v_mfma_f32_16x16x32_bf16 v[16:19], v[224:227], v[178:181], v[16:19]
	v_mfma_f32_16x16x32_bf16 v[32:35], v[220:223], v[166:169], v[32:35]
	v_mfma_f32_16x16x32_bf16 v[32:35], v[224:227], v[170:173], v[32:35]
	v_mfma_f32_16x16x32_bf16 v[48:51], v[220:223], v[158:161], v[48:51]
	v_mfma_f32_16x16x32_bf16 v[48:51], v[224:227], v[162:165], v[48:51]
	s_add_i32 s43, s43, 2
	s_add_u32 s26, s26, 0x100
	s_addc_u32 s27, s27, 0
	s_add_u32 s34, s34, 0x100
	s_addc_u32 s35, s35, 0
	s_cmp_gt_u32 s43, 29
	s_barrier
	s_cbranch_scc0 .LBB0_366
	s_andn2_b64 vcc, exec, s[16:17]
	s_lshl_b32 s1, s8, 8
	s_cbranch_vccnz .LBB0_378
	s_cmp_lt_i32 s8, 8
	s_cbranch_scc1 .LBB0_410
	s_cmp_gt_u32 s8, 15
	s_mov_b64 s[34:35], -1
	s_cbranch_scc0 .LBB0_375
	s_mov_b64 s[30:31], -1
	s_cmp_gt_u32 s8, 23
	s_mov_b64 s[28:29], -1
	s_cbranch_scc0 .LBB0_372
	s_add_i32 s3, s1, 0xffffe800
	s_mov_b64 s[28:29], 0

; __device__ __forceinline__ int otid() { int t = threadIdx.x; asm volatile("" : "+v"(t)); return t; }
; #define PG8_STAGE(bufoff, gbase, voff) do { _Pragma("unroll") for (int _i = 0; _i < 2; ++_i) \
;         __builtin_amdgcn_global_load_lds((const unsigned*)((const char*)(gbase) + (voff)[_i]), (LAS unsigned*)(lds + (bufoff) + ldsw + _i * 8192), 16, 0, 0); } while (0)
; #define PG8_BAR __builtin_amdgcn_s_barrier()
; template <class Epi>
; __device__ __forceinline__ void gemm_phase(LAS unsigned char* lds, const Gemm g, const StaticOrder& S, const Epi& E) {
;     const int tid = otid(), wid = __builtin_amdgcn_readfirstlane(tid >> 6), lane = tid & 63, wr = wid >> 2, wc = wid & 3, fr = lane & 15, fq = lane >> 4;
;     const int K = g.K, nt = K / BK;
;     unsigned voffA[2], voffB[2];
; #pragma unroll
;     for (int i = 0; i < 2; ++i) { int R, C; stage_rc(tid * 16 + i * 8192, R, C); const int Rb = Epi::PERM ? ((R & ~31) + perm32(R & 31)) : R;
;         voffA[i] = (unsigned)(R * K + C) * 2u; voffB[i] = (unsigned)(Rb * K + C) * 2u; }
;     const size_t kstep = (size_t)(BK * 2);
;     const size_t hstep = (size_t)HALF * K * 2;
;     const size_t tstep = 2 * hstep;
;     const unsigned ldsw = (unsigned)wid * 1024u;
;     const int aoff = lds_byte(wr * 64 + fr, fq * 8), boff = lds_byte(wc * 32 + fr, fq * 8);
;     ...
;     Unit cur, nxt; int ui = 0;
;     if (!S.next(0, cur)) return;
;     f32x4 acc[2][2][4][2];
; #pragma unroll
;     for (int a = 0; a < 2; ++a)
; #pragma unroll
;         for (int b = 0; b < 2; ++b)
; #pragma unroll
;             for (int m = 0; m < 4; ++m)
; #pragma unroll
;                 for (int n = 0; n < 2; ++n) acc[a][b][m][n] = (f32x4){0.f, 0.f, 0.f, 0.f};
;     bf16x8 At[4][2], B0[2][2], B1[2][2];
;     const char* cA = (const char*)g.A + (size_t)cur.pm * tstep; const char* cB = (const char*)g.Bt + (size_t)cur.pn * tstep;
;     PG8_STAGE(PG8_SB(0, 0), cB, voffB); PG8_STAGE(PG8_SA(0, 0), cA, voffA); PG8_STAGE(PG8_SB(0, 1), cB + hstep, voffB); PG8_STAGE(PG8_SA(0, 1), cA + hstep, voffA);
;     if (wr == 1) PG8_BAR;
.LBB0_425:
	s_andn2_b64 vcc, exec, s[0:1]
	s_cbranch_vccnz .LBB0_478
	v_bfe_i32 v1, v5, 27, 1
	v_lshlrev_b32_e32 v3, 4, v5
	v_lshrrev_b32_e32 v1, 22, v1
	v_add_u32_e32 v1, v3, v1
	v_and_b32_e32 v1, 0xfffffc00, v1
	v_sub_u32_e32 v1, v3, v1
	v_lshrrev_b32_e32 v2, 4, v1
	v_bitop3_b32 v2, v2, v1, 32 bitop3:0x6c
	v_ashrrev_i32_e32 v1, 31, v1
	v_lshrrev_b32_e32 v1, 26, v1
	v_ashrrev_i32_e32 v0, 31, v5
	v_add_u32_e32 v1, v2, v1
	v_lshrrev_b32_e32 v0, 26, v0
	v_ashrrev_i32_e32 v1, 6, v1
	v_add_u32_e32 v0, v5, v0
	v_mul_i32_i24_e32 v7, 64, v1
	v_ashrrev_i32_e32 v0, 6, v0
	v_sub_u32_e32 v2, v2, v7
	v_lshlrev_b32_e32 v4, 3, v0
	v_lshlrev_b32_e32 v6, 5, v0
	v_ashrrev_i16_sdwa v2, v236, sext(v2) dst_sel:DWORD dst_unused:UNUSED_PAD src0_sel:DWORD src1_sel:BYTE_0
	v_and_b32_e32 v4, -16, v4
	v_and_b32_e32 v6, 32, v6
	v_bfe_i32 v2, v2, 0, 16
	v_add_u32_e32 v4, v1, v4
	v_and_b32_e32 v9, 3, v1
	s_mov_b32 s1, 0xfffe0
	v_add_lshl_u32 v6, v6, v2, 1
	v_lshlrev_b32_e32 v7, 1, v4
	v_lshrrev_b32_e32 v8, 2, v4
	v_and_or_b32 v9, v4, s1, v9
	v_lshl_add_u32 v128, v4, 12, v6
	v_add_u32_e32 v4, 0x2000, v3
	v_ashrrev_i32_e32 v3, 31, v4
	v_lshrrev_b32_e32 v3, 22, v3
	v_and_b32_e32 v7, 24, v7
	v_and_b32_e32 v8, 4, v8
	v_add_u32_e32 v3, v4, v3
	v_or3_b32 v7, v9, v8, v7
	v_ashrrev_i32_e32 v3, 10, v3
	v_lshl_add_u32 v184, v7, 12, v6
	v_mul_i32_i24_e32 v6, 0x400, v3
	v_sub_u32_e32 v4, v4, v6
	v_lshrrev_b32_e32 v6, 4, v4
	v_bitop3_b32 v6, v6, v4, 32 bitop3:0x6c
	v_lshlrev_b32_e32 v4, 3, v3
	v_and_b32_e32 v7, -16, v4
	v_ashrrev_i32_e32 v4, 31, v6
	v_lshrrev_b32_e32 v4, 26, v4
	v_add_u32_e32 v8, v6, v4
	v_ashrrev_i32_e32 v4, 6, v8
	v_add_u32_e32 v7, v4, v7
	v_and_b32_e32 v11, 3, v4
	v_and_or_b32 v11, v7, s1, v11
	s_ashr_i32 s1, s37, 6
	s_ashr_i32 s25, s24, 31
	s_ashr_i32 s9, s8, 31
	s_ashr_i32 s0, s37, 8
	v_and_b32_e32 v8, 0xc0, v8
	s_lshl_b32 s38, s1, 10
	s_lshl_b64 s[6:7], s[24:25], 20
	s_lshl_b64 s[18:19], s[8:9], 20
	v_sub_u32_e32 v6, v6, v8
	s_add_u32 s28, s68, s18
	v_lshlrev_b32_e32 v9, 5, v3
	v_ashrrev_i16_sdwa v6, v236, sext(v6) dst_sel:DWORD dst_unused:UNUSED_PAD src0_sel:DWORD src1_sel:BYTE_0
	v_lshlrev_b32_e32 v8, 1, v7
	v_lshrrev_b32_e32 v10, 2, v7
	s_addc_u32 s29, s69, s19
	s_add_i32 s25, s38, 0
	v_and_b32_e32 v9, 32, v9
	v_bfe_i32 v6, v6, 0, 16
	v_and_b32_e32 v8, 24, v8
	v_and_b32_e32 v10, 4, v10
	s_add_i32 m0, s25, 0x10000
	v_or3_b32 v8, v11, v10, v8
	v_add_lshl_u32 v9, v9, v6, 1
	global_load_lds_dwordx4 v184, s[28:29]
	s_add_i32 m0, s25, 0x12000
	v_lshl_add_u32 v132, v8, 12, v9
	s_add_u32 s26, s90, s6
	global_load_lds_dwordx4 v132, s[28:29]
	s_addc_u32 s27, s91, s7
	s_mov_b32 m0, s25
	s_add_i32 s39, s25, 0x2000
	v_lshl_add_u32 v130, v7, 12, v9
	global_load_lds_dwordx4 v128, s[26:27]
	s_mov_b32 m0, s39
	s_add_u32 s6, s28, 0x80000
	global_load_lds_dwordx4 v130, s[26:27]
	s_addc_u32 s7, s29, 0
	s_add_i32 m0, s25, 0x14000
	s_nop 0
	global_load_lds_dwordx4 v184, s[6:7]
	s_add_i32 m0, s25, 0x16000
	s_nop 0
	global_load_lds_dwordx4 v132, s[6:7]
	s_add_u32 s6, s26, 0x80000
	s_addc_u32 s7, s27, 0
	s_add_i32 s40, s25, 0x4000
	s_mov_b32 m0, s40
	s_add_i32 s41, s25, 0x6000
	global_load_lds_dwordx4 v128, s[6:7]
	s_mov_b32 m0, s41
	s_cmp_lg_u32 s0, 1
	global_load_lds_dwordx4 v130, s[6:7]
	s_cbranch_scc1 .LBB0_428
	s_setprio 1
	s_barrier

; __device__ __forceinline__ int otid() { int t = threadIdx.x; asm volatile("" : "+v"(t)); return t; }
; #define PG8_STAGE(bufoff, gbase, voff) do { _Pragma("unroll") for (int _i = 0; _i < 2; ++_i) \
;         __builtin_amdgcn_global_load_lds((const unsigned*)((const char*)(gbase) + (voff)[_i]), (LAS unsigned*)(lds + (bufoff) + ldsw + _i * 8192), 16, 0, 0); } while (0)
; #define PG8_BAR __builtin_amdgcn_s_barrier()
; template <class Epi>
; __device__ __forceinline__ void gemm_phase(LAS unsigned char* lds, const Gemm g, const StaticOrder& S, const Epi& E) {
;     const int tid = otid(), wid = __builtin_amdgcn_readfirstlane(tid >> 6), lane = tid & 63, wr = wid >> 2, wc = wid & 3, fr = lane & 15, fq = lane >> 4;
;     const int K = g.K, nt = K / BK;
;     unsigned voffA[2], voffB[2];
; #pragma unroll
;     for (int i = 0; i < 2; ++i) { int R, C; stage_rc(tid * 16 + i * 8192, R, C); const int Rb = Epi::PERM ? ((R & ~31) + perm32(R & 31)) : R;
;         voffA[i] = (unsigned)(R * K + C) * 2u; voffB[i] = (unsigned)(Rb * K + C) * 2u; }
;     const size_t kstep = (size_t)(BK * 2);
;     const size_t hstep = (size_t)HALF * K * 2;
;     const size_t tstep = 2 * hstep;
;     const unsigned ldsw = (unsigned)wid * 1024u;
;     const int aoff = lds_byte(wr * 64 + fr, fq * 8), boff = lds_byte(wc * 32 + fr, fq * 8);
;     ...
;     Unit cur, nxt; int ui = 0;
;     if (!S.next(0, cur)) return;
;     f32x4 acc[2][2][4][2];
; #pragma unroll
;     for (int a = 0; a < 2; ++a)
; #pragma unroll
;         for (int b = 0; b < 2; ++b)
; #pragma unroll
;             for (int m = 0; m < 4; ++m)
; #pragma unroll
;                 for (int n = 0; n < 2; ++n) acc[a][b][m][n] = (f32x4){0.f, 0.f, 0.f, 0.f};
;     bf16x8 At[4][2], B0[2][2], B1[2][2];
;     const char* cA = (const char*)g.A + (size_t)cur.pm * tstep; const char* cB = (const char*)g.Bt + (size_t)cur.pn * tstep;
;     PG8_STAGE(PG8_SB(0, 0), cB, voffB); PG8_STAGE(PG8_SA(0, 0), cA, voffA); PG8_STAGE(PG8_SB(0, 1), cB + hstep, voffB); PG8_STAGE(PG8_SA(0, 1), cA + hstep, voffA);
;     if (wr == 1) PG8_BAR;
.LBB0_482:
	s_andn2_b64 vcc, exec, s[0:1]
	s_cbranch_vccnz .LBB0_353
	v_ashrrev_i32_e32 v1, 31, v14
	v_lshrrev_b32_e32 v1, 26, v1
	v_add_u32_e32 v1, v14, v1
	v_ashrrev_i32_e32 v8, 6, v1
	v_bfe_i32 v1, v14, 27, 1
	v_lshlrev_b32_e32 v0, 4, v14
	v_lshrrev_b32_e32 v1, 22, v1
	v_add_u32_e32 v1, v0, v1
	v_and_b32_e32 v1, 0xfffffc00, v1
	v_sub_u32_e32 v1, v0, v1
	v_lshrrev_b32_e32 v2, 4, v1
	v_bitop3_b32 v2, v2, v1, 32 bitop3:0x6c
	v_ashrrev_i32_e32 v1, 31, v1
	v_lshrrev_b32_e32 v1, 26, v1
	v_add_u32_e32 v1, v2, v1
	v_ashrrev_i32_e32 v9, 6, v1
	v_lshlrev_b32_e32 v3, 3, v8
	v_mul_i32_i24_e32 v4, 64, v9
	v_and_b32_e32 v3, -16, v3
	v_sub_u32_e32 v2, v2, v4
	v_add_u32_e32 v1, v9, v3
	v_lshlrev_b32_e32 v3, 5, v8
	v_ashrrev_i16_sdwa v2, v236, sext(v2) dst_sel:DWORD dst_unused:UNUSED_PAD src0_sel:DWORD src1_sel:BYTE_0
	v_and_b32_e32 v3, 32, v3
	v_bfe_i32 v10, v2, 0, 16
	v_and_b32_e32 v5, 3, v9
	s_mov_b32 s1, 0xfffe0
	v_add_lshl_u32 v3, v3, v10, 1
	v_add_u32_e32 v0, 0x2000, v0
	v_lshlrev_b32_e32 v2, 1, v1
	v_lshrrev_b32_e32 v4, 2, v1
	v_and_or_b32 v5, v1, s1, v5
	v_lshl_add_u32 v128, v1, 12, v3
	v_ashrrev_i32_e32 v1, 31, v0
	v_lshrrev_b32_e32 v1, 22, v1
	v_add_u32_e32 v1, v0, v1
	v_ashrrev_i32_e32 v11, 10, v1
	v_mul_i32_i24_e32 v1, 0x400, v11
	v_sub_u32_e32 v0, v0, v1
	v_and_b32_e32 v2, 24, v2
	v_and_b32_e32 v4, 4, v4
	v_lshrrev_b32_e32 v1, 4, v0
	v_or3_b32 v2, v5, v4, v2
	v_bitop3_b32 v0, v1, v0, 32 bitop3:0x6c
	v_lshl_add_u32 v184, v2, 12, v3
	v_ashrrev_i32_e32 v2, 31, v0
	v_lshrrev_b32_e32 v2, 26, v2
	v_lshlrev_b32_e32 v1, 3, v11
	v_add_u32_e32 v2, v0, v2
	v_and_b32_e32 v1, -16, v1
	v_ashrrev_i32_e32 v12, 6, v2
	v_add_u32_e32 v1, v12, v1
	v_and_b32_e32 v4, 3, v12
	v_and_b32_e32 v2, 0xc0, v2
	v_and_or_b32 v4, v1, s1, v4
	s_ashr_i32 s1, s37, 6
	s_ashr_i32 s29, s28, 31
	s_ashr_i32 s27, s26, 31
	s_ashr_i32 s0, s37, 8
	v_sub_u32_e32 v0, v0, v2
	s_lshl_b32 s38, s1, 10
	s_lshl_b64 s[6:7], s[28:29], 20
	s_lshl_b64 s[8:9], s[26:27], 20
	v_ashrrev_i16_sdwa v0, v236, sext(v0) dst_sel:DWORD dst_unused:UNUSED_PAD src0_sel:DWORD src1_sel:BYTE_0
	s_add_u32 s30, s73, s8
	v_lshlrev_b32_e32 v3, 5, v11
	v_bfe_i32 v13, v0, 0, 16
	v_lshlrev_b32_e32 v0, 1, v1
	v_lshrrev_b32_e32 v2, 2, v1
	s_addc_u32 s31, s75, s9
	s_add_i32 s27, s38, 0
	v_and_b32_e32 v3, 32, v3
	v_and_b32_e32 v0, 24, v0
	v_and_b32_e32 v2, 4, v2
	s_add_i32 m0, s27, 0x10000
	v_or3_b32 v0, v4, v2, v0
	v_add_lshl_u32 v2, v3, v13, 1
	global_load_lds_dwordx4 v184, s[30:31]
	s_add_i32 m0, s27, 0x12000
	v_lshl_add_u32 v132, v0, 12, v2
	s_add_u32 s8, s90, s6
	global_load_lds_dwordx4 v132, s[30:31]
	s_addc_u32 s9, s91, s7
	s_mov_b32 m0, s27
	s_add_i32 s29, s27, 0x2000
	v_lshl_add_u32 v130, v1, 12, v2
	global_load_lds_dwordx4 v128, s[8:9]
	s_mov_b32 m0, s29
	s_add_u32 s6, s30, 0x80000
	global_load_lds_dwordx4 v130, s[8:9]
	s_addc_u32 s7, s31, 0
	s_add_i32 m0, s27, 0x14000
	v_mov_b32_e32 v133, v185
	global_load_lds_dwordx4 v184, s[6:7]
	s_add_i32 m0, s27, 0x16000
	v_mov_b32_e32 v129, v185
	global_load_lds_dwordx4 v132, s[6:7]
	s_add_u32 s6, s8, 0x80000
	s_addc_u32 s7, s9, 0
	s_add_i32 s39, s27, 0x4000
	s_mov_b32 m0, s39
	s_add_i32 s40, s27, 0x6000
	global_load_lds_dwordx4 v128, s[6:7]
	s_mov_b32 m0, s40
	v_mov_b32_e32 v131, v185
	global_load_lds_dwordx4 v130, s[6:7]
	v_lshl_add_u64 v[6:7], s[30:31], 0, v[184:185]
	v_lshl_add_u64 v[4:5], s[30:31], 0, v[132:133]
	v_lshl_add_u64 v[2:3], s[8:9], 0, v[128:129]
	s_cmp_lg_u32 s0, 1
	v_lshl_add_u64 v[0:1], s[8:9], 0, v[130:131]
	s_cbranch_scc1 .LBB0_485
	s_setprio 1
	s_barrier

; #define PG8_STAGE(bufoff, gbase, voff) do { _Pragma("unroll") for (int _i = 0; _i < 2; ++_i) \
;         __builtin_amdgcn_global_load_lds((const unsigned*)((const char*)(gbase) + (voff)[_i]), (LAS unsigned*)(lds + (bufoff) + ldsw + _i * 8192), 16, 0, 0); } while (0)
; #define PG8_LDA(dst, b, h) do { _Pragma("unroll") for (int m = 0; m < 4; ++m) _Pragma("unroll") for (int k = 0; k < 2; ++k) dst[m][k] = *(const LAS bf16x8*)(lds + PG8_SA(b, h) + aoff + m * 2048 + k * 1024); } while (0)
; #define PG8_LDB(dst, b, h) do { _Pragma("unroll") for (int n = 0; n < 2; ++n) _Pragma("unroll") for (int k = 0; k < 2; ++k) dst[n][k] = *(const LAS bf16x8*)(lds + PG8_SB(b, h) + boff + n * 2048 + k * 1024); } while (0)
; #define PG8_MMA(ai, bj, At, Bt) do { __builtin_amdgcn_s_setprio(1); _Pragma("unroll") for (int m = 0; m < 4; ++m) _Pragma("unroll") for (int n = 0; n < 2; ++n) _Pragma("unroll") for (int k = 0; k < 2; ++k) \
;         acc[ai][bj][m][n] = __builtin_amdgcn_mfma_f32_16x16x32_bf16(Bt[n][k], At[m][k], acc[ai][bj][m][n], 0, 0, 0); __builtin_amdgcn_s_setprio(0); } while (0)
; #define PG8_WAIT_L(n) asm volatile("s_waitcnt lgkmcnt(" #n ")" ::: "memory")
; #define PG8_BAR __builtin_amdgcn_s_barrier()
; #define PG8_SCHED __builtin_amdgcn_sched_barrier(0)
; template <class Epi>
; __device__ __forceinline__ void gemm_phase(LAS unsigned char* lds, const Gemm g, const StaticOrder& S, const Epi& E) {
;     ...
;         for (int t = 0; t < nt; t += 2) {
;             const bool last = (t == nt - 2);
;             const char* a1 = cA + (size_t)(t + 1) * kstep;
;             const char* a2 = last ? nA : cA + (size_t)(t + 2) * kstep; const char* b2 = last ? nB : cB + (size_t)(t + 2) * kstep;
;             const char* a3 = a2 + kstep; const char* b3 = b2 + kstep;
;             PG8_LDB(B0, 0, 0); PG8_SCHED; PG8_LDA(At, 0, 0); PG8_STAGE(PG8_SA(1, 1), a1 + hstep, voffA);
;             PG8_WAIT_L(8); PG8_BAR; PG8_WAIT_L(0); PG8_MMA(0, 0, At, B0); PG8_BAR; PG8_SCHED;
;             PG8_LDB(B1, 0, 1); PG8_STAGE(PG8_SB(0, 0), b2, voffB);
;             PG8_BAR; PG8_WAIT_L(0); PG8_MMA(0, 1, At, B1); PG8_BAR;
;             PG8_LDA(At, 0, 1); PG8_STAGE(PG8_SA(0, 0), a2, voffA);
;             PG8_BAR; PG8_WAIT_L(0); PG8_MMA(1, 0, At, B0); PG8_BAR; PG8_SCHED;
.LBB0_490:
	s_add_u32 s30, s8, 0xfff80080
	s_addc_u32 s31, s9, -1
	s_add_i32 s52, 0, 0x10000
	v_add_u32_e32 v154, s52, v143
	ds_read_b128 v[138:141], v154
	ds_read_b128 v[146:149], v154 offset:1024
	ds_read_b128 v[150:153], v154 offset:2048
	ds_read_b128 v[154:157], v154 offset:3072
	s_cmp_eq_u32 s51, 28
	s_cselect_b32 s35, s3, s31
	s_cselect_b32 s34, s21, s30
	s_cselect_b32 s31, s19, s50
	s_cselect_b32 s30, s43, s47
	v_lshl_add_u64 v[182:183], s[8:9], 0, v[134:135]
	s_add_i32 m0, s27, 0xc000
	ds_read_b128 v[158:161], v145
	ds_read_b128 v[162:165], v145 offset:1024
	ds_read_b128 v[166:169], v145 offset:2048
	ds_read_b128 v[170:173], v145 offset:3072
	ds_read_b128 v[174:177], v145 offset:4096
	ds_read_b128 v[178:181], v145 offset:5120
	ds_read_b128 v[204:207], v145 offset:6144
	ds_read_b128 v[208:211], v145 offset:7168
	global_load_lds_dwordx4 v[182:183], off
	v_lshl_add_u64 v[182:183], s[8:9], 0, v[136:137]
	s_add_i32 m0, s27, 0xe000
	s_nop 0
	global_load_lds_dwordx4 v[182:183], off
	s_waitcnt lgkmcnt(8)
	s_barrier
	s_waitcnt lgkmcnt(0)
	s_waitcnt lgkmcnt(0)
	v_mfma_f32_16x16x32_bf16 v[124:127], v[138:141], v[158:161], v[124:127]
	v_mfma_f32_16x16x32_bf16 v[124:127], v[146:149], v[162:165], v[124:127]
	v_mfma_f32_16x16x32_bf16 v[108:111], v[138:141], v[166:169], v[108:111]
	v_mfma_f32_16x16x32_bf16 v[108:111], v[146:149], v[170:173], v[108:111]
	v_mfma_f32_16x16x32_bf16 v[92:95], v[138:141], v[174:177], v[92:95]
	v_mfma_f32_16x16x32_bf16 v[92:95], v[146:149], v[178:181], v[92:95]
	v_mfma_f32_16x16x32_bf16 v[76:79], v[138:141], v[204:207], v[76:79]
	v_mfma_f32_16x16x32_bf16 v[76:79], v[146:149], v[208:211], v[76:79]
	v_mfma_f32_16x16x32_bf16 v[72:75], v[150:153], v[204:207], v[72:75]
	v_mfma_f32_16x16x32_bf16 v[72:75], v[154:157], v[208:211], v[72:75]
	v_mfma_f32_16x16x32_bf16 v[88:91], v[150:153], v[174:177], v[88:91]
	v_mfma_f32_16x16x32_bf16 v[88:91], v[154:157], v[178:181], v[88:91]
	v_mfma_f32_16x16x32_bf16 v[104:107], v[150:153], v[166:169], v[104:107]
	v_mfma_f32_16x16x32_bf16 v[104:107], v[154:157], v[170:173], v[104:107]
	v_mfma_f32_16x16x32_bf16 v[120:123], v[150:153], v[158:161], v[120:123]
	v_mfma_f32_16x16x32_bf16 v[120:123], v[154:157], v[162:165], v[120:123]
	s_barrier
	s_add_i32 s56, 0, 0x14000
	v_add_u32_e32 v182, s56, v143
	s_add_i32 s52, s52, s38
	ds_read_b128 v[212:215], v182
	ds_read_b128 v[216:219], v182 offset:1024
	ds_read_b128 v[220:223], v182 offset:2048
	ds_read_b128 v[224:227], v182 offset:3072
	v_lshl_add_u64 v[182:183], s[30:31], 0, v[184:185]
	s_mov_b32 m0, s52
	v_lshl_add_u64 v[188:189], s[30:31], 0, v[132:133]
	global_load_lds_dwordx4 v[182:183], off
	s_add_i32 m0, s52, 0x2000
	s_nop 0
	global_load_lds_dwordx4 v[188:189], off
	s_barrier
	s_waitcnt lgkmcnt(0)
	s_waitcnt lgkmcnt(0)
	v_mfma_f32_16x16x32_bf16 v[116:119], v[212:215], v[158:161], v[116:119]
	v_mfma_f32_16x16x32_bf16 v[116:119], v[216:219], v[162:165], v[116:119]
	v_mfma_f32_16x16x32_bf16 v[100:103], v[212:215], v[166:169], v[100:103]
	v_mfma_f32_16x16x32_bf16 v[100:103], v[216:219], v[170:173], v[100:103]
	v_mfma_f32_16x16x32_bf16 v[84:87], v[212:215], v[174:177], v[84:87]
	v_mfma_f32_16x16x32_bf16 v[84:87], v[216:219], v[178:181], v[84:87]
	v_mfma_f32_16x16x32_bf16 v[68:71], v[212:215], v[204:207], v[68:71]
	v_mfma_f32_16x16x32_bf16 v[68:71], v[216:219], v[208:211], v[68:71]
	v_mfma_f32_16x16x32_bf16 v[64:67], v[220:223], v[204:207], v[64:67]
	v_mfma_f32_16x16x32_bf16 v[64:67], v[224:227], v[208:211], v[64:67]
	v_mfma_f32_16x16x32_bf16 v[80:83], v[220:223], v[174:177], v[80:83]
	v_mfma_f32_16x16x32_bf16 v[80:83], v[224:227], v[178:181], v[80:83]
	v_mfma_f32_16x16x32_bf16 v[96:99], v[220:223], v[166:169], v[96:99]
	v_mfma_f32_16x16x32_bf16 v[96:99], v[224:227], v[170:173], v[96:99]
	v_mfma_f32_16x16x32_bf16 v[112:115], v[220:223], v[158:161], v[112:115]
	v_mfma_f32_16x16x32_bf16 v[112:115], v[224:227], v[162:165], v[112:115]
	s_mov_b32 m0, s27
	v_lshl_add_u64 v[190:191], s[34:35], 0, v[128:129]
	s_barrier
	ds_read_b128 v[158:161], v145 offset:16384
	ds_read_b128 v[162:165], v145 offset:17408
	ds_read_b128 v[166:169], v145 offset:18432
	ds_read_b128 v[170:173], v145 offset:19456
	ds_read_b128 v[174:177], v145 offset:20480
	ds_read_b128 v[178:181], v145 offset:21504
	ds_read_b128 v[204:207], v145 offset:22528
	ds_read_b128 v[208:211], v145 offset:23552
	global_load_lds_dwordx4 v[190:191], off
	v_lshl_add_u64 v[192:193], s[34:35], 0, v[130:131]
	s_mov_b32 m0, s29
	s_nop 0
	global_load_lds_dwordx4 v[192:193], off
	s_barrier
	s_waitcnt lgkmcnt(0)
	s_waitcnt lgkmcnt(0)
	v_mfma_f32_16x16x32_bf16 v[60:63], v[138:141], v[158:161], v[60:63]
	v_mfma_f32_16x16x32_bf16 v[60:63], v[146:149], v[162:165], v[60:63]
	v_mfma_f32_16x16x32_bf16 v[44:47], v[138:141], v[166:169], v[44:47]
	v_mfma_f32_16x16x32_bf16 v[44:47], v[146:149], v[170:173], v[44:47]
	v_mfma_f32_16x16x32_bf16 v[28:31], v[138:141], v[174:177], v[28:31]
	v_mfma_f32_16x16x32_bf16 v[28:31], v[146:149], v[178:181], v[28:31]
	v_mfma_f32_16x16x32_bf16 v[12:15], v[138:141], v[204:207], v[12:15]
	v_mfma_f32_16x16x32_bf16 v[12:15], v[146:149], v[208:211], v[12:15]
	v_mfma_f32_16x16x32_bf16 v[8:11], v[150:153], v[204:207], v[8:11]
	v_mfma_f32_16x16x32_bf16 v[8:11], v[154:157], v[208:211], v[8:11]
	v_mfma_f32_16x16x32_bf16 v[24:27], v[150:153], v[174:177], v[24:27]
	v_mfma_f32_16x16x32_bf16 v[24:27], v[154:157], v[178:181], v[24:27]
	v_mfma_f32_16x16x32_bf16 v[40:43], v[150:153], v[166:169], v[40:43]
	v_mfma_f32_16x16x32_bf16 v[40:43], v[154:157], v[170:173], v[40:43]
	v_mfma_f32_16x16x32_bf16 v[56:59], v[150:153], v[158:161], v[56:59]
	v_mfma_f32_16x16x32_bf16 v[56:59], v[154:157], v[162:165], v[56:59]
	s_barrier
; #define PG8_STAGE(bufoff, gbase, voff) do { _Pragma("unroll") for (int _i = 0; _i < 2; ++_i) \
;         __builtin_amdgcn_global_load_lds((const unsigned*)((const char*)(gbase) + (voff)[_i]), (LAS unsigned*)(lds + (bufoff) + ldsw + _i * 8192), 16, 0, 0); } while (0)
; #define PG8_LDA(dst, b, h) do { _Pragma("unroll") for (int m = 0; m < 4; ++m) _Pragma("unroll") for (int k = 0; k < 2; ++k) dst[m][k] = *(const LAS bf16x8*)(lds + PG8_SA(b, h) + aoff + m * 2048 + k * 1024); } while (0)
; #define PG8_LDB(dst, b, h) do { _Pragma("unroll") for (int n = 0; n < 2; ++n) _Pragma("unroll") for (int k = 0; k < 2; ++k) dst[n][k] = *(const LAS bf16x8*)(lds + PG8_SB(b, h) + boff + n * 2048 + k * 1024); } while (0)
; #define PG8_MMA(ai, bj, At, Bt) do { __builtin_amdgcn_s_setprio(1); _Pragma("unroll") for (int m = 0; m < 4; ++m) _Pragma("unroll") for (int n = 0; n < 2; ++n) _Pragma("unroll") for (int k = 0; k < 2; ++k) \
;         acc[ai][bj][m][n] = __builtin_amdgcn_mfma_f32_16x16x32_bf16(Bt[n][k], At[m][k], acc[ai][bj][m][n], 0, 0, 0); __builtin_amdgcn_s_setprio(0); } while (0)
; #define PG8_WAIT_V(n) asm volatile("s_waitcnt vmcnt(" #n ")" ::: "memory")
; #define PG8_WAIT_L(n) asm volatile("s_waitcnt lgkmcnt(" #n ")" ::: "memory")
; #define PG8_BAR __builtin_amdgcn_s_barrier()
; #define PG8_SCHED __builtin_amdgcn_sched_barrier(0)
; template <class Epi>
; __device__ __forceinline__ void gemm_phase(LAS unsigned char* lds, const Gemm g, const StaticOrder& S, const Epi& E) {
;     ...
;             PG8_STAGE(PG8_SB(0, 1), b2 + hstep, voffB);
;             PG8_WAIT_V(6); PG8_BAR; PG8_MMA(1, 1, At, B1); PG8_BAR;
;             PG8_LDB(B0, 1, 0); PG8_SCHED; PG8_LDA(At, 1, 0); PG8_STAGE(PG8_SA(0, 1), a2 + hstep, voffA);
;             PG8_WAIT_L(8); PG8_BAR; PG8_WAIT_L(0); PG8_MMA(0, 0, At, B0); PG8_BAR; PG8_SCHED;
;             PG8_LDB(B1, 1, 1); PG8_STAGE(PG8_SB(1, 0), b3, voffB);
;             PG8_BAR; PG8_WAIT_L(0); PG8_MMA(0, 1, At, B1); PG8_BAR;
;             PG8_LDA(At, 1, 1); PG8_STAGE(PG8_SA(1, 0), a3, voffA);
;             PG8_BAR; PG8_WAIT_L(0); PG8_MMA(1, 0, At, B0); PG8_BAR; PG8_SCHED;
	s_add_u32 s54, s30, 0x80000
	s_addc_u32 s55, s31, 0
	s_add_i32 s52, s56, s38
	v_lshl_add_u64 v[138:139], s[54:55], 0, v[184:185]
	s_mov_b32 m0, s52
	s_nop 0
	global_load_lds_dwordx4 v[138:139], off
	v_lshl_add_u64 v[138:139], s[54:55], 0, v[132:133]
	s_add_i32 m0, s52, 0x2000
	s_nop 0
	global_load_lds_dwordx4 v[138:139], off
	s_waitcnt vmcnt(6)
	s_barrier
	v_mfma_f32_16x16x32_bf16 v[52:55], v[212:215], v[158:161], v[52:55]
	v_mfma_f32_16x16x32_bf16 v[52:55], v[216:219], v[162:165], v[52:55]
	v_mfma_f32_16x16x32_bf16 v[36:39], v[212:215], v[166:169], v[36:39]
	v_mfma_f32_16x16x32_bf16 v[36:39], v[216:219], v[170:173], v[36:39]
	v_mfma_f32_16x16x32_bf16 v[20:23], v[212:215], v[174:177], v[20:23]
	v_mfma_f32_16x16x32_bf16 v[20:23], v[216:219], v[178:181], v[20:23]
	v_mfma_f32_16x16x32_bf16 v[4:7], v[212:215], v[204:207], v[4:7]
	v_mfma_f32_16x16x32_bf16 v[4:7], v[216:219], v[208:211], v[4:7]
	v_mfma_f32_16x16x32_bf16 v[0:3], v[220:223], v[204:207], v[0:3]
	v_mfma_f32_16x16x32_bf16 v[0:3], v[224:227], v[208:211], v[0:3]
	v_mfma_f32_16x16x32_bf16 v[16:19], v[220:223], v[174:177], v[16:19]
	v_mfma_f32_16x16x32_bf16 v[16:19], v[224:227], v[178:181], v[16:19]
	v_mfma_f32_16x16x32_bf16 v[32:35], v[220:223], v[166:169], v[32:35]
	v_mfma_f32_16x16x32_bf16 v[32:35], v[224:227], v[170:173], v[32:35]
	v_mfma_f32_16x16x32_bf16 v[48:51], v[220:223], v[158:161], v[48:51]
	v_mfma_f32_16x16x32_bf16 v[48:51], v[224:227], v[162:165], v[48:51]
	s_add_i32 s52, 0, 0x18000
	v_add_u32_e32 v154, s52, v143
	s_barrier
	ds_read_b128 v[138:141], v154
	ds_read_b128 v[146:149], v154 offset:1024
	ds_read_b128 v[150:153], v154 offset:2048
	ds_read_b128 v[154:157], v154 offset:3072
	s_add_u32 s34, s34, 0x80000
	s_addc_u32 s35, s35, 0
	s_mov_b32 m0, s39
	v_lshl_add_u64 v[212:213], s[34:35], 0, v[128:129]
	ds_read_b128 v[158:161], v145 offset:32768
	ds_read_b128 v[162:165], v145 offset:33792
	ds_read_b128 v[166:169], v145 offset:34816
	ds_read_b128 v[170:173], v145 offset:35840
	ds_read_b128 v[174:177], v145 offset:36864
	ds_read_b128 v[178:181], v145 offset:37888
	ds_read_b128 v[204:207], v145 offset:38912
	ds_read_b128 v[208:211], v145 offset:39936
	global_load_lds_dwordx4 v[212:213], off
	v_lshl_add_u64 v[212:213], s[34:35], 0, v[130:131]
	s_mov_b32 m0, s40
	s_nop 0
	global_load_lds_dwordx4 v[212:213], off
	s_waitcnt lgkmcnt(8)
	s_barrier
	s_waitcnt lgkmcnt(0)
	s_waitcnt lgkmcnt(0)
	v_mfma_f32_16x16x32_bf16 v[124:127], v[138:141], v[158:161], v[124:127]
	v_mfma_f32_16x16x32_bf16 v[124:127], v[146:149], v[162:165], v[124:127]
	v_mfma_f32_16x16x32_bf16 v[108:111], v[138:141], v[166:169], v[108:111]
	v_mfma_f32_16x16x32_bf16 v[108:111], v[146:149], v[170:173], v[108:111]
	v_mfma_f32_16x16x32_bf16 v[92:95], v[138:141], v[174:177], v[92:95]
	v_mfma_f32_16x16x32_bf16 v[92:95], v[146:149], v[178:181], v[92:95]
	v_mfma_f32_16x16x32_bf16 v[76:79], v[138:141], v[204:207], v[76:79]
	v_mfma_f32_16x16x32_bf16 v[76:79], v[146:149], v[208:211], v[76:79]
	v_mfma_f32_16x16x32_bf16 v[72:75], v[150:153], v[204:207], v[72:75]
	v_mfma_f32_16x16x32_bf16 v[72:75], v[154:157], v[208:211], v[72:75]
	v_mfma_f32_16x16x32_bf16 v[88:91], v[150:153], v[174:177], v[88:91]
	v_mfma_f32_16x16x32_bf16 v[88:91], v[154:157], v[178:181], v[88:91]
	v_mfma_f32_16x16x32_bf16 v[104:107], v[150:153], v[166:169], v[104:107]
	v_mfma_f32_16x16x32_bf16 v[104:107], v[154:157], v[170:173], v[104:107]
	v_mfma_f32_16x16x32_bf16 v[120:123], v[150:153], v[158:161], v[120:123]
	v_mfma_f32_16x16x32_bf16 v[120:123], v[154:157], v[162:165], v[120:123]
	s_barrier
	s_add_i32 s34, 0, 0x1c000
	s_add_i32 s35, s52, s38
	v_add_u32_e32 v187, s34, v143
	v_lshl_add_u64 v[182:183], v[182:183], 0, s[58:59]
	s_mov_b32 m0, s35
	ds_read_b128 v[212:215], v187
	ds_read_b128 v[216:219], v187 offset:1024
	ds_read_b128 v[220:223], v187 offset:2048
	ds_read_b128 v[224:227], v187 offset:3072
	global_load_lds_dwordx4 v[182:183], off
	v_lshl_add_u64 v[182:183], v[188:189], 0, s[58:59]
	s_add_i32 m0, s35, 0x2000
	s_nop 0
	global_load_lds_dwordx4 v[182:183], off
	s_barrier
	s_waitcnt lgkmcnt(0)
	s_waitcnt lgkmcnt(0)
	v_mfma_f32_16x16x32_bf16 v[116:119], v[212:215], v[158:161], v[116:119]
	v_mfma_f32_16x16x32_bf16 v[116:119], v[216:219], v[162:165], v[116:119]
	v_mfma_f32_16x16x32_bf16 v[100:103], v[212:215], v[166:169], v[100:103]
	v_mfma_f32_16x16x32_bf16 v[100:103], v[216:219], v[170:173], v[100:103]
	v_mfma_f32_16x16x32_bf16 v[84:87], v[212:215], v[174:177], v[84:87]
	v_mfma_f32_16x16x32_bf16 v[84:87], v[216:219], v[178:181], v[84:87]
	v_mfma_f32_16x16x32_bf16 v[68:71], v[212:215], v[204:207], v[68:71]
	v_mfma_f32_16x16x32_bf16 v[68:71], v[216:219], v[208:211], v[68:71]
	v_mfma_f32_16x16x32_bf16 v[64:67], v[220:223], v[204:207], v[64:67]
	v_mfma_f32_16x16x32_bf16 v[64:67], v[224:227], v[208:211], v[64:67]
	v_mfma_f32_16x16x32_bf16 v[80:83], v[220:223], v[174:177], v[80:83]
	v_mfma_f32_16x16x32_bf16 v[80:83], v[224:227], v[178:181], v[80:83]
	v_mfma_f32_16x16x32_bf16 v[96:99], v[220:223], v[166:169], v[96:99]
	v_mfma_f32_16x16x32_bf16 v[96:99], v[224:227], v[170:173], v[96:99]
	v_mfma_f32_16x16x32_bf16 v[112:115], v[220:223], v[158:161], v[112:115]
	v_mfma_f32_16x16x32_bf16 v[112:115], v[224:227], v[162:165], v[112:115]
	s_mov_b32 m0, s41
	v_lshl_add_u64 v[182:183], v[190:191], 0, s[58:59]
	s_barrier
; __device__ __forceinline__ float sigmoidf_(float x) { return __builtin_amdgcn_rcpf(1.0f + __builtin_amdgcn_exp2f(-1.4426950408889634f * x)); }
; #define PG8_STAGE(bufoff, gbase, voff) do { _Pragma("unroll") for (int _i = 0; _i < 2; ++_i) \
;         __builtin_amdgcn_global_load_lds((const unsigned*)((const char*)(gbase) + (voff)[_i]), (LAS unsigned*)(lds + (bufoff) + ldsw + _i * 8192), 16, 0, 0); } while (0)
; #define PG8_LDA(dst, b, h) do { _Pragma("unroll") for (int m = 0; m < 4; ++m) _Pragma("unroll") for (int k = 0; k < 2; ++k) dst[m][k] = *(const LAS bf16x8*)(lds + PG8_SA(b, h) + aoff + m * 2048 + k * 1024); } while (0)
; #define PG8_MMA(ai, bj, At, Bt) do { __builtin_amdgcn_s_setprio(1); _Pragma("unroll") for (int m = 0; m < 4; ++m) _Pragma("unroll") for (int n = 0; n < 2; ++n) _Pragma("unroll") for (int k = 0; k < 2; ++k) \
;         acc[ai][bj][m][n] = __builtin_amdgcn_mfma_f32_16x16x32_bf16(Bt[n][k], At[m][k], acc[ai][bj][m][n], 0, 0, 0); __builtin_amdgcn_s_setprio(0); } while (0)
; #define PG8_WAIT_V(n) asm volatile("s_waitcnt vmcnt(" #n ")" ::: "memory")
; #define PG8_WAIT_L(n) asm volatile("s_waitcnt lgkmcnt(" #n ")" ::: "memory")
; #define PG8_BAR __builtin_amdgcn_s_barrier()
; #define PG8_SCHED __builtin_amdgcn_sched_barrier(0)
; template <class Epi>
; __device__ __forceinline__ void gemm_phase(LAS unsigned char* lds, const Gemm g, const StaticOrder& S, const Epi& E) {
;     ...
;             PG8_LDA(At, 1, 1); PG8_STAGE(PG8_SA(1, 0), a3, voffA);
;             PG8_BAR; PG8_WAIT_L(0); PG8_MMA(1, 0, At, B0); PG8_BAR; PG8_SCHED;
;             PG8_STAGE(PG8_SB(1, 1), b3 + hstep, voffB);
;             PG8_WAIT_V(6); PG8_BAR; PG8_MMA(1, 1, At, B1); PG8_BAR;
;     __device__ __forceinline__ void operator()(const Acc& acc, const Unit& u, int wr, int wc, int fr, int fq) const {
;     ...
;                 for (int bj = 0; bj < 2; ++bj) { f32x4 v0 = acc[ai][bj][m][0], v1 = acc[ai][bj][m][1];
;                     if (act) {
; #pragma unroll
;                         for (int j = 0; j < 4; ++j) { v0[j] = sigmoidf_(v0[j]); v1[j] = sigmoidf_(v1[j]); } }
	ds_read_b128 v[158:161], v145 offset:49152
	ds_read_b128 v[162:165], v145 offset:50176
	ds_read_b128 v[166:169], v145 offset:51200
	ds_read_b128 v[170:173], v145 offset:52224
	ds_read_b128 v[174:177], v145 offset:53248
	ds_read_b128 v[178:181], v145 offset:54272
	ds_read_b128 v[204:207], v145 offset:55296
	ds_read_b128 v[208:211], v145 offset:56320
	global_load_lds_dwordx4 v[182:183], off
	v_lshl_add_u64 v[182:183], v[192:193], 0, s[58:59]
	s_mov_b32 m0, s42
	s_nop 0
	global_load_lds_dwordx4 v[182:183], off
	s_barrier
	s_waitcnt lgkmcnt(0)
	s_waitcnt lgkmcnt(0)
	v_mfma_f32_16x16x32_bf16 v[60:63], v[138:141], v[158:161], v[60:63]
	v_mfma_f32_16x16x32_bf16 v[60:63], v[146:149], v[162:165], v[60:63]
	v_mfma_f32_16x16x32_bf16 v[44:47], v[138:141], v[166:169], v[44:47]
	v_mfma_f32_16x16x32_bf16 v[44:47], v[146:149], v[170:173], v[44:47]
	v_mfma_f32_16x16x32_bf16 v[28:31], v[138:141], v[174:177], v[28:31]
	v_mfma_f32_16x16x32_bf16 v[28:31], v[146:149], v[178:181], v[28:31]
	v_mfma_f32_16x16x32_bf16 v[12:15], v[138:141], v[204:207], v[12:15]
	v_mfma_f32_16x16x32_bf16 v[12:15], v[146:149], v[208:211], v[12:15]
	v_mfma_f32_16x16x32_bf16 v[8:11], v[150:153], v[204:207], v[8:11]
	v_mfma_f32_16x16x32_bf16 v[8:11], v[154:157], v[208:211], v[8:11]
	v_mfma_f32_16x16x32_bf16 v[24:27], v[150:153], v[174:177], v[24:27]
	v_mfma_f32_16x16x32_bf16 v[24:27], v[154:157], v[178:181], v[24:27]
	v_mfma_f32_16x16x32_bf16 v[40:43], v[150:153], v[166:169], v[40:43]
	v_mfma_f32_16x16x32_bf16 v[40:43], v[154:157], v[170:173], v[40:43]
	v_mfma_f32_16x16x32_bf16 v[56:59], v[150:153], v[158:161], v[56:59]
	v_mfma_f32_16x16x32_bf16 v[56:59], v[154:157], v[162:165], v[56:59]
	s_barrier
	s_add_u32 s30, s30, 0x80080
	s_addc_u32 s31, s31, 0
	s_add_i32 s34, s34, s38
	v_lshl_add_u64 v[138:139], s[30:31], 0, v[184:185]
	s_mov_b32 m0, s34
	s_nop 0
	global_load_lds_dwordx4 v[138:139], off
	v_lshl_add_u64 v[138:139], s[30:31], 0, v[132:133]
	s_add_i32 m0, s34, 0x2000
	s_nop 0
	global_load_lds_dwordx4 v[138:139], off
	s_waitcnt vmcnt(6)
	s_barrier
	v_mfma_f32_16x16x32_bf16 v[52:55], v[212:215], v[158:161], v[52:55]
	v_mfma_f32_16x16x32_bf16 v[52:55], v[216:219], v[162:165], v[52:55]
	v_mfma_f32_16x16x32_bf16 v[36:39], v[212:215], v[166:169], v[36:39]
	v_mfma_f32_16x16x32_bf16 v[36:39], v[216:219], v[170:173], v[36:39]
	v_mfma_f32_16x16x32_bf16 v[20:23], v[212:215], v[174:177], v[20:23]
	v_mfma_f32_16x16x32_bf16 v[20:23], v[216:219], v[178:181], v[20:23]
	v_mfma_f32_16x16x32_bf16 v[4:7], v[212:215], v[204:207], v[4:7]
	v_mfma_f32_16x16x32_bf16 v[4:7], v[216:219], v[208:211], v[4:7]
	v_mfma_f32_16x16x32_bf16 v[0:3], v[220:223], v[204:207], v[0:3]
	v_mfma_f32_16x16x32_bf16 v[0:3], v[224:227], v[208:211], v[0:3]
	v_mfma_f32_16x16x32_bf16 v[16:19], v[220:223], v[174:177], v[16:19]
	v_mfma_f32_16x16x32_bf16 v[16:19], v[224:227], v[178:181], v[16:19]
	v_mfma_f32_16x16x32_bf16 v[32:35], v[220:223], v[166:169], v[32:35]
	v_mfma_f32_16x16x32_bf16 v[32:35], v[224:227], v[170:173], v[32:35]
	v_mfma_f32_16x16x32_bf16 v[48:51], v[220:223], v[158:161], v[48:51]
	v_mfma_f32_16x16x32_bf16 v[48:51], v[224:227], v[162:165], v[48:51]
	s_add_i32 s51, s51, 2
	s_add_u32 s8, s8, 0x100
	s_addc_u32 s9, s9, 0
	s_add_u32 s47, s47, 0x100
	s_addc_u32 s50, s50, 0
	s_cmp_gt_u32 s51, 29
	s_barrier
	s_cbranch_scc0 .LBB0_490
	v_cndmask_b32_e64 v138, 0, 1, s[16:17]
	v_cmp_ne_u32_e64 s[8:9], 1, v138
	s_andn2_b64 vcc, exec, s[16:17]
	s_cbranch_vccnz .LBB0_493
	v_mul_f32_e32 v124, 0xbfb8aa3b, v124
	v_mul_f32_e32 v120, 0xbfb8aa3b, v120
	v_mul_f32_e32 v125, 0xbfb8aa3b, v125
	v_mul_f32_e32 v121, 0xbfb8aa3b, v121
	v_mul_f32_e32 v126, 0xbfb8aa3b, v126
	v_mul_f32_e32 v122, 0xbfb8aa3b, v122
	v_mul_f32_e32 v127, 0xbfb8aa3b, v127
	v_mul_f32_e32 v123, 0xbfb8aa3b, v123
	v_exp_f32_e32 v124, v124
	v_exp_f32_e32 v120, v120
	v_exp_f32_e32 v125, v125
	v_exp_f32_e32 v121, v121
	v_exp_f32_e32 v126, v126
	v_exp_f32_e32 v122, v122
	v_exp_f32_e32 v127, v127
	v_exp_f32_e32 v123, v123
	v_add_f32_e32 v124, 1.0, v124
	v_add_f32_e32 v120, 1.0, v120
	v_add_f32_e32 v125, 1.0, v125
	v_add_f32_e32 v121, 1.0, v121
	v_add_f32_e32 v126, 1.0, v126
	v_add_f32_e32 v122, 1.0, v122
	v_add_f32_e32 v127, 1.0, v127
	v_add_f32_e32 v123, 1.0, v123
	v_rcp_f32_e32 v124, v124
	v_rcp_f32_e32 v120, v120
	v_rcp_f32_e32 v125, v125
	v_rcp_f32_e32 v121, v121
	v_rcp_f32_e32 v126, v126
	v_rcp_f32_e32 v122, v122
	v_rcp_f32_e32 v127, v127
	v_rcp_f32_e32 v123, v123

; #define PG8_STAGE(bufoff, gbase, voff) do { _Pragma("unroll") for (int _i = 0; _i < 2; ++_i) \
;         __builtin_amdgcn_global_load_lds((const unsigned*)((const char*)(gbase) + (voff)[_i]), (LAS unsigned*)(lds + (bufoff) + ldsw + _i * 8192), 16, 0, 0); } while (0)
; #define PG8_WAIT_V(n) asm volatile("s_waitcnt vmcnt(" #n ")" ::: "memory")
; #define PG8_BAR __builtin_amdgcn_s_barrier()
; template <class Epi>
; __device__ __forceinline__ void gemm_phase(LAS unsigned char* lds, const Gemm g, const StaticOrder& S, const Epi& E) {
;     ...
;     for (int i = 0; i < 2; ++i) { int R, C; stage_rc(tid * 16 + i * 8192, R, C); const int Rb = Epi::PERM ? ((R & ~31) + perm32(R & 31)) : R;
;         voffA[i] = (unsigned)(R * K + C) * 2u; voffB[i] = (unsigned)(Rb * K + C) * 2u; }
;     const size_t kstep = (size_t)(BK * 2);
;     const size_t hstep = (size_t)HALF * K * 2;
;     const size_t tstep = 2 * hstep;
;     const unsigned ldsw = (unsigned)wid * 1024u;
;     const int aoff = lds_byte(wr * 64 + fr, fq * 8), boff = lds_byte(wc * 32 + fr, fq * 8);
;     ...
;     Unit cur, nxt; int ui = 0;
;     if (!S.next(0, cur)) return;
;     f32x4 acc[2][2][4][2];
; #pragma unroll
;     for (int a = 0; a < 2; ++a)
; #pragma unroll
;         for (int b = 0; b < 2; ++b)
; #pragma unroll
;             for (int m = 0; m < 4; ++m)
; #pragma unroll
;                 for (int n = 0; n < 2; ++n) acc[a][b][m][n] = (f32x4){0.f, 0.f, 0.f, 0.f};
;     bf16x8 At[4][2], B0[2][2], B1[2][2];
;     const char* cA = (const char*)g.A + (size_t)cur.pm * tstep; const char* cB = (const char*)g.Bt + (size_t)cur.pn * tstep;
;     PG8_STAGE(PG8_SB(0, 0), cB, voffB); PG8_STAGE(PG8_SA(0, 0), cA, voffA); PG8_STAGE(PG8_SB(0, 1), cB + hstep, voffB); PG8_STAGE(PG8_SA(0, 1), cA + hstep, voffA);
;     if (wr == 1) PG8_BAR;
;     PG8_WAIT_V(4); PG8_BAR;
;     PG8_STAGE(PG8_SB(1, 0), cB + kstep, voffB); PG8_STAGE(PG8_SA(1, 0), cA + kstep, voffA); PG8_STAGE(PG8_SB(1, 1), cB + hstep + kstep, voffB);
.LBB0_579:
	s_andn2_b64 vcc, exec, s[0:1]
	s_cbranch_vccnz .LBB0_711
	v_bfe_i32 v2, v12, 27, 1
	v_lshlrev_b32_e32 v0, 4, v12
	v_lshrrev_b32_e32 v2, 22, v2
	v_add_u32_e32 v2, v0, v2
	v_and_b32_e32 v2, 0xfffffc00, v2
	v_ashrrev_i32_e32 v1, 31, v12
	v_sub_u32_e32 v2, v0, v2
	v_lshrrev_b32_e32 v1, 26, v1
	v_lshrrev_b32_e32 v3, 4, v2
	v_add_u32_e32 v1, v12, v1
	v_bitop3_b32 v3, v3, v2, 32 bitop3:0x6c
	v_ashrrev_i32_e32 v2, 31, v2
	v_ashrrev_i32_e32 v1, 6, v1
	v_lshrrev_b32_e32 v2, 26, v2
	v_lshlrev_b32_e32 v4, 3, v1
	v_add_u32_e32 v2, v3, v2
	v_and_b32_e32 v4, -16, v4
	v_ashrrev_i32_e32 v2, 6, v2
	v_lshlrev_b32_e32 v1, 5, v1
	v_add_u32_e32 v4, v2, v4
	v_and_b32_e32 v13, 32, v1
	v_mul_i32_i24_e32 v1, 64, v2
	v_sub_u32_e32 v1, v3, v1
	v_lshlrev_b32_e32 v3, 1, v4
	v_lshrrev_b32_e32 v5, 2, v4
	v_and_b32_e32 v2, 3, v2
	s_mov_b32 s0, 0x7fffffe0
	v_ashrrev_i16_sdwa v1, v236, sext(v1) dst_sel:DWORD dst_unused:UNUSED_PAD src0_sel:DWORD src1_sel:BYTE_0
	v_and_b32_e32 v3, 24, v3
	v_and_b32_e32 v5, 4, v5
	v_and_or_b32 v2, v4, s0, v2
	v_bfe_i32 v14, v1, 0, 16
	v_or3_b32 v2, v2, v5, v3
	v_add_u32_e32 v1, v13, v14
	v_mul_lo_u32 v15, v4, s6
	v_mul_lo_u32 v2, v2, s6
	v_add_u32_e32 v0, 0x2000, v0
	v_add_lshl_u32 v208, v1, v15, 1
	v_add_lshl_u32 v184, v2, v1, 1
	v_ashrrev_i32_e32 v1, 31, v0
	v_lshrrev_b32_e32 v1, 22, v1
	v_add_u32_e32 v1, v0, v1
	v_ashrrev_i32_e32 v1, 10, v1
	v_mul_i32_i24_e32 v2, 0x400, v1
	v_sub_u32_e32 v0, v0, v2
	v_lshrrev_b32_e32 v2, 4, v0
	v_bitop3_b32 v0, v2, v0, 32 bitop3:0x6c
	v_ashrrev_i32_e32 v3, 31, v0
	v_lshrrev_b32_e32 v3, 26, v3
	v_lshlrev_b32_e32 v2, 3, v1
	v_add_u32_e32 v3, v0, v3
	s_ashr_i32 s7, s39, 6
	v_and_b32_e32 v2, -16, v2
	v_ashrrev_i32_e32 v4, 6, v3
	v_lshlrev_b32_e32 v1, 5, v1
	s_lshl_b32 s40, s6, 9
	v_add_u32_e32 v2, v4, v2
	v_and_b32_e32 v16, 32, v1
	v_and_b32_e32 v1, 0xc0, v3
	s_ashr_i32 s8, s39, 8
	s_lshl_b32 s52, s6, 8
	s_lshl_b32 s41, s7, 10
	s_mul_i32 s10, s40, s42
	v_sub_u32_e32 v0, v0, v1
	v_lshlrev_b32_e32 v1, 1, v2
	v_lshrrev_b32_e32 v3, 2, v2
	v_and_b32_e32 v4, 3, v4
	s_mul_hi_i32 s9, s40, s42
	s_add_u32 s36, s24, s10
	v_ashrrev_i16_sdwa v0, v236, sext(v0) dst_sel:DWORD dst_unused:UNUSED_PAD src0_sel:DWORD src1_sel:BYTE_0
	v_and_b32_e32 v1, 24, v1
	v_and_b32_e32 v3, 4, v3
	v_and_or_b32 v4, v2, s0, v4
	s_addc_u32 s37, s25, s9
	s_add_i32 s44, s41, 0
	v_bfe_i32 v17, v0, 0, 16
	v_or3_b32 v1, v4, v3, v1
	s_add_i32 m0, s44, 0x10000
	v_add_u32_e32 v0, v16, v17
	v_mul_lo_u32 v1, v1, s6
	s_mul_i32 s0, s40, s3
	global_load_lds_dwordx4 v184, s[36:37]
	s_add_i32 m0, s44, 0x12000
	v_add_lshl_u32 v212, v1, v0, 1
	s_mul_hi_i32 s1, s40, s3
	s_add_u32 s0, s66, s0
	v_mul_lo_u32 v18, v2, s6
	global_load_lds_dwordx4 v212, s[36:37]
	s_addc_u32 s1, s67, s1
	s_mov_b32 m0, s44
	s_add_i32 s45, s44, 0x2000
	v_add_lshl_u32 v210, v0, v18, 1
	global_load_lds_dwordx4 v208, s[0:1]
	s_mov_b32 m0, s45
	s_add_u32 s10, s36, s52
	global_load_lds_dwordx4 v210, s[0:1]
	s_addc_u32 s11, s37, 0
	s_add_i32 m0, s44, 0x14000
	v_mov_b32_e32 v213, v185
	global_load_lds_dwordx4 v184, s[10:11]
	s_add_i32 m0, s44, 0x16000
	v_lshl_add_u64 v[8:9], s[10:11], 0, v[184:185]
	v_lshl_add_u64 v[10:11], s[10:11], 0, v[212:213]
	global_load_lds_dwordx4 v212, s[10:11]
	s_add_u32 s10, s0, s52
	s_addc_u32 s11, s1, 0
	s_add_i32 s46, s44, 0x4000
	s_mov_b32 m0, s46
	s_add_i32 s47, s44, 0x6000
	global_load_lds_dwordx4 v208, s[10:11]
	s_mov_b32 m0, s47
	v_mov_b32_e32 v209, v185
	global_load_lds_dwordx4 v210, s[10:11]
	v_mov_b32_e32 v211, v185
	v_lshl_add_u64 v[0:1], s[36:37], 0, v[184:185]
	v_lshl_add_u64 v[2:3], s[36:37], 0, v[212:213]
	v_lshl_add_u64 v[4:5], s[0:1], 0, v[208:209]
	v_lshl_add_u64 v[6:7], s[0:1], 0, v[210:211]
	s_cmp_lg_u32 s8, 1
	s_cbranch_scc1 .LBB0_582
	s_setprio 1
	s_barrier

; #define PG8_STAGE(bufoff, gbase, voff) do { _Pragma("unroll") for (int _i = 0; _i < 2; ++_i) \
;         __builtin_amdgcn_global_load_lds((const unsigned*)((const char*)(gbase) + (voff)[_i]), (LAS unsigned*)(lds + (bufoff) + ldsw + _i * 8192), 16, 0, 0); } while (0)
; #define PG8_LDA(dst, b, h) do { _Pragma("unroll") for (int m = 0; m < 4; ++m) _Pragma("unroll") for (int k = 0; k < 2; ++k) dst[m][k] = *(const LAS bf16x8*)(lds + PG8_SA(b, h) + aoff + m * 2048 + k * 1024); } while (0)
; #define PG8_LDB(dst, b, h) do { _Pragma("unroll") for (int n = 0; n < 2; ++n) _Pragma("unroll") for (int k = 0; k < 2; ++k) dst[n][k] = *(const LAS bf16x8*)(lds + PG8_SB(b, h) + boff + n * 2048 + k * 1024); } while (0)
; #define PG8_MMA(ai, bj, At, Bt) do { __builtin_amdgcn_s_setprio(1); _Pragma("unroll") for (int m = 0; m < 4; ++m) _Pragma("unroll") for (int n = 0; n < 2; ++n) _Pragma("unroll") for (int k = 0; k < 2; ++k) \
;         acc[ai][bj][m][n] = __builtin_amdgcn_mfma_f32_16x16x32_bf16(Bt[n][k], At[m][k], acc[ai][bj][m][n], 0, 0, 0); __builtin_amdgcn_s_setprio(0); } while (0)
; #define PG8_WAIT_L(n) asm volatile("s_waitcnt lgkmcnt(" #n ")" ::: "memory")
; #define PG8_BAR __builtin_amdgcn_s_barrier()
; #define PG8_SCHED __builtin_amdgcn_sched_barrier(0)
; template <class Epi>
; __device__ __forceinline__ void gemm_phase(LAS unsigned char* lds, const Gemm g, const StaticOrder& S, const Epi& E) {
;     ...
;             const char* a1 = cA + (size_t)(t + 1) * kstep;
;             const char* a2 = last ? nA : cA + (size_t)(t + 2) * kstep; const char* b2 = last ? nB : cB + (size_t)(t + 2) * kstep;
;             const char* a3 = a2 + kstep; const char* b3 = b2 + kstep;
;             PG8_LDB(B0, 0, 0); PG8_SCHED; PG8_LDA(At, 0, 0); PG8_STAGE(PG8_SA(1, 1), a1 + hstep, voffA);
;             PG8_WAIT_L(8); PG8_BAR; PG8_WAIT_L(0); PG8_MMA(0, 0, At, B0); PG8_BAR; PG8_SCHED;
;             PG8_LDB(B1, 0, 1); PG8_STAGE(PG8_SB(0, 0), b2, voffB);
;             PG8_BAR; PG8_WAIT_L(0); PG8_MMA(0, 1, At, B1); PG8_BAR;
;             PG8_LDA(At, 0, 1); PG8_STAGE(PG8_SA(0, 0), a2, voffA);
;             PG8_BAR; PG8_WAIT_L(0); PG8_MMA(1, 0, At, B0); PG8_BAR; PG8_SCHED;
.LBB0_591:
	s_add_i32 s68, s8, 2
	s_add_u32 s36, s0, 0x80
	s_addc_u32 s9, s1, 0
	s_add_i32 s66, 0, 0x10000
	v_add_u32_e32 v60, s66, v233
	ds_read_b128 v[48:51], v60
	ds_read_b128 v[52:55], v60 offset:1024
	ds_read_b128 v[56:59], v60 offset:2048
	ds_read_b128 v[60:63], v60 offset:3072
	s_cmp_eq_u32 s55, s8
	s_cselect_b32 s8, s34, s36
	s_cselect_b32 s9, s35, s9
	s_cselect_b32 s37, s11, s63
	s_cselect_b32 s36, s10, s43
	v_lshl_add_u64 v[176:177], s[0:1], 0, v[214:215]
	s_add_i32 m0, s44, 0xc000
	ds_read_b128 v[68:71], v248
	ds_read_b128 v[76:79], v248 offset:1024
	ds_read_b128 v[80:83], v248 offset:2048
	ds_read_b128 v[84:87], v248 offset:3072
	ds_read_b128 v[160:163], v248 offset:4096
	ds_read_b128 v[164:167], v248 offset:5120
	ds_read_b128 v[168:171], v248 offset:6144
	ds_read_b128 v[172:175], v248 offset:7168
	global_load_lds_dwordx4 v[176:177], off
	v_lshl_add_u64 v[176:177], s[0:1], 0, v[216:217]
	s_add_i32 m0, s44, 0xe000
	s_nop 0
	global_load_lds_dwordx4 v[176:177], off
	s_waitcnt lgkmcnt(8)
	s_barrier
	s_waitcnt lgkmcnt(0)
	s_waitcnt lgkmcnt(0)
	v_mfma_f32_16x16x32_bf16 v[156:159], v[48:51], v[68:71], v[156:159]
	v_mfma_f32_16x16x32_bf16 v[156:159], v[52:55], v[76:79], v[156:159]
	v_mfma_f32_16x16x32_bf16 v[140:143], v[48:51], v[80:83], v[140:143]
	v_mfma_f32_16x16x32_bf16 v[140:143], v[52:55], v[84:87], v[140:143]
	v_mfma_f32_16x16x32_bf16 v[124:127], v[48:51], v[160:163], v[124:127]
	v_mfma_f32_16x16x32_bf16 v[124:127], v[52:55], v[164:167], v[124:127]
	v_mfma_f32_16x16x32_bf16 v[108:111], v[48:51], v[168:171], v[108:111]
	v_mfma_f32_16x16x32_bf16 v[108:111], v[52:55], v[172:175], v[108:111]
	v_mfma_f32_16x16x32_bf16 v[104:107], v[56:59], v[168:171], v[104:107]
	v_mfma_f32_16x16x32_bf16 v[104:107], v[60:63], v[172:175], v[104:107]
	v_mfma_f32_16x16x32_bf16 v[120:123], v[56:59], v[160:163], v[120:123]
	v_mfma_f32_16x16x32_bf16 v[120:123], v[60:63], v[164:167], v[120:123]
	v_mfma_f32_16x16x32_bf16 v[136:139], v[56:59], v[80:83], v[136:139]
	v_mfma_f32_16x16x32_bf16 v[136:139], v[60:63], v[84:87], v[136:139]
	v_mfma_f32_16x16x32_bf16 v[152:155], v[56:59], v[68:71], v[152:155]
	v_mfma_f32_16x16x32_bf16 v[152:155], v[60:63], v[76:79], v[152:155]
	s_barrier
	s_add_i32 s67, 0, 0x14000
	s_add_i32 s66, s66, s41
	v_add_u32_e32 v187, s67, v233
	v_lshl_add_u64 v[230:231], s[36:37], 0, v[184:185]
	s_mov_b32 m0, s66
	ds_read_b128 v[176:179], v187
	ds_read_b128 v[180:183], v187 offset:1024
	ds_read_b128 v[218:221], v187 offset:2048
	ds_read_b128 v[222:225], v187 offset:3072
	global_load_lds_dwordx4 v[230:231], off
	v_lshl_add_u64 v[250:251], s[36:37], 0, v[212:213]
	s_add_i32 m0, s66, 0x2000
	s_nop 0
	global_load_lds_dwordx4 v[250:251], off
	s_barrier
	s_waitcnt lgkmcnt(0)
	s_waitcnt lgkmcnt(0)
	v_mfma_f32_16x16x32_bf16 v[148:151], v[176:179], v[68:71], v[148:151]
	v_mfma_f32_16x16x32_bf16 v[68:71], v[218:221], v[68:71], v[144:147]
	v_mfma_f32_16x16x32_bf16 v[148:151], v[180:183], v[76:79], v[148:151]
	v_mfma_f32_16x16x32_bf16 v[68:71], v[222:225], v[76:79], v[68:71]
	v_mfma_f32_16x16x32_bf16 v[76:79], v[176:179], v[80:83], v[132:135]
	v_mfma_f32_16x16x32_bf16 v[80:83], v[218:221], v[80:83], v[128:131]
	v_mfma_f32_16x16x32_bf16 v[112:115], v[218:221], v[160:163], v[112:115]
	v_mfma_f32_16x16x32_bf16 v[100:103], v[176:179], v[168:171], v[100:103]
	v_mfma_f32_16x16x32_bf16 v[96:99], v[218:221], v[168:171], v[96:99]
	v_mfma_f32_16x16x32_bf16 v[76:79], v[180:183], v[84:87], v[76:79]
	v_mfma_f32_16x16x32_bf16 v[80:83], v[222:225], v[84:87], v[80:83]
	v_mfma_f32_16x16x32_bf16 v[84:87], v[176:179], v[160:163], v[116:119]
	v_mfma_f32_16x16x32_bf16 v[112:115], v[222:225], v[164:167], v[112:115]
	v_mfma_f32_16x16x32_bf16 v[100:103], v[180:183], v[172:175], v[100:103]
	v_mfma_f32_16x16x32_bf16 v[96:99], v[222:225], v[172:175], v[96:99]
	v_mfma_f32_16x16x32_bf16 v[84:87], v[180:183], v[164:167], v[84:87]
	s_mov_b32 m0, s44
	v_lshl_add_u64 v[238:239], s[8:9], 0, v[208:209]
	s_barrier
	ds_read_b128 v[116:119], v248 offset:16384
	ds_read_b128 v[128:131], v248 offset:17408
	ds_read_b128 v[132:135], v248 offset:18432
	ds_read_b128 v[144:147], v248 offset:19456
	ds_read_b128 v[160:163], v248 offset:20480
	ds_read_b128 v[164:167], v248 offset:21504
	ds_read_b128 v[168:171], v248 offset:22528
	ds_read_b128 v[172:175], v248 offset:23552
	global_load_lds_dwordx4 v[238:239], off
	v_lshl_add_u64 v[188:189], s[8:9], 0, v[210:211]
	s_mov_b32 m0, s45
	s_nop 0
	global_load_lds_dwordx4 v[188:189], off
	s_barrier
	s_waitcnt lgkmcnt(0)
	s_waitcnt lgkmcnt(0)
	v_mfma_f32_16x16x32_bf16 v[92:95], v[48:51], v[116:119], v[92:95]
	v_mfma_f32_16x16x32_bf16 v[92:95], v[52:55], v[128:131], v[92:95]
	v_mfma_f32_16x16x32_bf16 v[44:47], v[48:51], v[132:135], v[44:47]
	v_mfma_f32_16x16x32_bf16 v[44:47], v[52:55], v[144:147], v[44:47]
	v_mfma_f32_16x16x32_bf16 v[28:31], v[48:51], v[160:163], v[28:31]
	v_mfma_f32_16x16x32_bf16 v[28:31], v[52:55], v[164:167], v[28:31]
	v_mfma_f32_16x16x32_bf16 v[12:15], v[48:51], v[168:171], v[12:15]
	v_mfma_f32_16x16x32_bf16 v[12:15], v[52:55], v[172:175], v[12:15]
	v_mfma_f32_16x16x32_bf16 v[8:11], v[56:59], v[168:171], v[8:11]
	v_mfma_f32_16x16x32_bf16 v[8:11], v[60:63], v[172:175], v[8:11]
	v_mfma_f32_16x16x32_bf16 v[24:27], v[56:59], v[160:163], v[24:27]
	v_mfma_f32_16x16x32_bf16 v[24:27], v[60:63], v[164:167], v[24:27]
	v_mfma_f32_16x16x32_bf16 v[40:43], v[56:59], v[132:135], v[40:43]
	v_mfma_f32_16x16x32_bf16 v[40:43], v[60:63], v[144:147], v[40:43]
	v_mfma_f32_16x16x32_bf16 v[88:91], v[56:59], v[116:119], v[88:91]
	v_mfma_f32_16x16x32_bf16 v[88:91], v[60:63], v[128:131], v[88:91]
	s_barrier
; #define PG8_STAGE(bufoff, gbase, voff) do { _Pragma("unroll") for (int _i = 0; _i < 2; ++_i) \
;         __builtin_amdgcn_global_load_lds((const unsigned*)((const char*)(gbase) + (voff)[_i]), (LAS unsigned*)(lds + (bufoff) + ldsw + _i * 8192), 16, 0, 0); } while (0)
; #define PG8_LDA(dst, b, h) do { _Pragma("unroll") for (int m = 0; m < 4; ++m) _Pragma("unroll") for (int k = 0; k < 2; ++k) dst[m][k] = *(const LAS bf16x8*)(lds + PG8_SA(b, h) + aoff + m * 2048 + k * 1024); } while (0)
; #define PG8_LDB(dst, b, h) do { _Pragma("unroll") for (int n = 0; n < 2; ++n) _Pragma("unroll") for (int k = 0; k < 2; ++k) dst[n][k] = *(const LAS bf16x8*)(lds + PG8_SB(b, h) + boff + n * 2048 + k * 1024); } while (0)
; #define PG8_MMA(ai, bj, At, Bt) do { __builtin_amdgcn_s_setprio(1); _Pragma("unroll") for (int m = 0; m < 4; ++m) _Pragma("unroll") for (int n = 0; n < 2; ++n) _Pragma("unroll") for (int k = 0; k < 2; ++k) \
;         acc[ai][bj][m][n] = __builtin_amdgcn_mfma_f32_16x16x32_bf16(Bt[n][k], At[m][k], acc[ai][bj][m][n], 0, 0, 0); __builtin_amdgcn_s_setprio(0); } while (0)
; #define PG8_WAIT_V(n) asm volatile("s_waitcnt vmcnt(" #n ")" ::: "memory")
; #define PG8_WAIT_L(n) asm volatile("s_waitcnt lgkmcnt(" #n ")" ::: "memory")
; #define PG8_BAR __builtin_amdgcn_s_barrier()
; #define PG8_SCHED __builtin_amdgcn_sched_barrier(0)
; template <class Epi>
; __device__ __forceinline__ void gemm_phase(LAS unsigned char* lds, const Gemm g, const StaticOrder& S, const Epi& E) {
;     ...
;             PG8_STAGE(PG8_SB(0, 1), b2 + hstep, voffB);
;             PG8_WAIT_V(6); PG8_BAR; PG8_MMA(1, 1, At, B1); PG8_BAR;
;             PG8_LDB(B0, 1, 0); PG8_SCHED; PG8_LDA(At, 1, 0); PG8_STAGE(PG8_SA(0, 1), a2 + hstep, voffA);
;             PG8_WAIT_L(8); PG8_BAR; PG8_WAIT_L(0); PG8_MMA(0, 0, At, B0); PG8_BAR; PG8_SCHED;
;             PG8_LDB(B1, 1, 1); PG8_STAGE(PG8_SB(1, 0), b3, voffB);
;             PG8_BAR; PG8_WAIT_L(0); PG8_MMA(0, 1, At, B1); PG8_BAR;
	s_add_u32 s36, s36, s52
	s_addc_u32 s37, s37, 0
	s_add_i32 s66, s67, s41
	v_lshl_add_u64 v[190:191], s[36:37], 0, v[184:185]
	s_mov_b32 m0, s66
	v_lshl_add_u64 v[192:193], s[36:37], 0, v[212:213]
	global_load_lds_dwordx4 v[190:191], off
	s_add_i32 m0, s66, 0x2000
	s_nop 0
	global_load_lds_dwordx4 v[192:193], off
	s_waitcnt vmcnt(6)
	s_barrier
	v_mfma_f32_16x16x32_bf16 v[36:39], v[176:179], v[132:135], v[36:39]
	v_mfma_f32_16x16x32_bf16 v[36:39], v[180:183], v[144:147], v[36:39]
	v_mfma_f32_16x16x32_bf16 v[20:23], v[176:179], v[160:163], v[20:23]
	v_mfma_f32_16x16x32_bf16 v[20:23], v[180:183], v[164:167], v[20:23]
	v_mfma_f32_16x16x32_bf16 v[4:7], v[176:179], v[168:171], v[4:7]
	v_mfma_f32_16x16x32_bf16 v[4:7], v[180:183], v[172:175], v[4:7]
	v_mfma_f32_16x16x32_bf16 v[48:51], v[176:179], v[116:119], v[72:75]
	v_mfma_f32_16x16x32_bf16 v[48:51], v[180:183], v[128:131], v[48:51]
	v_mfma_f32_16x16x32_bf16 v[52:55], v[218:221], v[116:119], v[64:67]
	v_mfma_f32_16x16x32_bf16 v[52:55], v[222:225], v[128:131], v[52:55]
	v_mfma_f32_16x16x32_bf16 v[0:3], v[218:221], v[168:171], v[0:3]
	v_mfma_f32_16x16x32_bf16 v[0:3], v[222:225], v[172:175], v[0:3]
	v_mfma_f32_16x16x32_bf16 v[16:19], v[218:221], v[160:163], v[16:19]
	v_mfma_f32_16x16x32_bf16 v[16:19], v[222:225], v[164:167], v[16:19]
	v_mfma_f32_16x16x32_bf16 v[32:35], v[218:221], v[132:135], v[32:35]
	v_mfma_f32_16x16x32_bf16 v[32:35], v[222:225], v[144:147], v[32:35]
	s_add_i32 s36, 0, 0x18000
	v_add_u32_e32 v72, s36, v233
	s_barrier
	ds_read_b128 v[56:59], v72
	ds_read_b128 v[60:63], v72 offset:1024
	ds_read_b128 v[64:67], v72 offset:2048
	ds_read_b128 v[72:75], v72 offset:3072
	s_add_u32 s8, s8, s52
	s_addc_u32 s9, s9, 0
	s_mov_b32 m0, s46
	v_lshl_add_u64 v[132:133], s[8:9], 0, v[208:209]
	ds_read_b128 v[116:119], v248 offset:32768
	ds_read_b128 v[128:131], v248 offset:33792
	ds_read_b128 v[160:163], v248 offset:34816
	ds_read_b128 v[164:167], v248 offset:35840
	ds_read_b128 v[168:171], v248 offset:36864
	ds_read_b128 v[172:175], v248 offset:37888
	ds_read_b128 v[176:179], v248 offset:38912
	ds_read_b128 v[180:183], v248 offset:39936
	global_load_lds_dwordx4 v[132:133], off
	v_lshl_add_u64 v[132:133], s[8:9], 0, v[210:211]
	s_mov_b32 m0, s47
	s_nop 0
	global_load_lds_dwordx4 v[132:133], off
	s_waitcnt lgkmcnt(8)
	s_barrier
	s_waitcnt lgkmcnt(0)
	s_waitcnt lgkmcnt(0)
	v_mfma_f32_16x16x32_bf16 v[132:135], v[56:59], v[116:119], v[156:159]
	v_mfma_f32_16x16x32_bf16 v[156:159], v[60:63], v[128:131], v[132:135]
	v_mfma_f32_16x16x32_bf16 v[132:135], v[64:67], v[116:119], v[152:155]
	v_mfma_f32_16x16x32_bf16 v[152:155], v[72:75], v[128:131], v[132:135]
	v_mfma_f32_16x16x32_bf16 v[132:135], v[56:59], v[160:163], v[140:143]
	v_mfma_f32_16x16x32_bf16 v[140:143], v[60:63], v[164:167], v[132:135]
	v_mfma_f32_16x16x32_bf16 v[132:135], v[64:67], v[160:163], v[136:139]
	v_mfma_f32_16x16x32_bf16 v[124:127], v[56:59], v[168:171], v[124:127]
	v_mfma_f32_16x16x32_bf16 v[120:123], v[64:67], v[168:171], v[120:123]
	v_mfma_f32_16x16x32_bf16 v[108:111], v[56:59], v[176:179], v[108:111]
	v_mfma_f32_16x16x32_bf16 v[104:107], v[64:67], v[176:179], v[104:107]
	v_mfma_f32_16x16x32_bf16 v[136:139], v[72:75], v[164:167], v[132:135]
	v_mfma_f32_16x16x32_bf16 v[124:127], v[60:63], v[172:175], v[124:127]
	v_mfma_f32_16x16x32_bf16 v[120:123], v[72:75], v[172:175], v[120:123]
	v_mfma_f32_16x16x32_bf16 v[108:111], v[60:63], v[180:183], v[108:111]
	v_mfma_f32_16x16x32_bf16 v[104:107], v[72:75], v[180:183], v[104:107]
	s_barrier
	s_add_i32 s8, 0, 0x1c000
	v_add_u32_e32 v132, s8, v233
	s_add_i32 s9, s36, s41
	ds_read_b128 v[218:221], v132
	ds_read_b128 v[222:225], v132 offset:1024
	ds_read_b128 v[226:229], v132 offset:2048
	ds_read_b128 v[204:207], v132 offset:3072
	v_lshl_add_u64 v[132:133], v[230:231], 0, s[58:59]
	s_mov_b32 m0, s9
	s_nop 0
	global_load_lds_dwordx4 v[132:133], off
	v_lshl_add_u64 v[132:133], v[250:251], 0, s[58:59]
	s_add_i32 m0, s9, 0x2000
	s_nop 0
	global_load_lds_dwordx4 v[132:133], off
	s_barrier
; #define PG8_STAGE(bufoff, gbase, voff) do { _Pragma("unroll") for (int _i = 0; _i < 2; ++_i) \
;         __builtin_amdgcn_global_load_lds((const unsigned*)((const char*)(gbase) + (voff)[_i]), (LAS unsigned*)(lds + (bufoff) + ldsw + _i * 8192), 16, 0, 0); } while (0)
; #define PG8_LDA(dst, b, h) do { _Pragma("unroll") for (int m = 0; m < 4; ++m) _Pragma("unroll") for (int k = 0; k < 2; ++k) dst[m][k] = *(const LAS bf16x8*)(lds + PG8_SA(b, h) + aoff + m * 2048 + k * 1024); } while (0)
; #define PG8_MMA(ai, bj, At, Bt) do { __builtin_amdgcn_s_setprio(1); _Pragma("unroll") for (int m = 0; m < 4; ++m) _Pragma("unroll") for (int n = 0; n < 2; ++n) _Pragma("unroll") for (int k = 0; k < 2; ++k) \
;         acc[ai][bj][m][n] = __builtin_amdgcn_mfma_f32_16x16x32_bf16(Bt[n][k], At[m][k], acc[ai][bj][m][n], 0, 0, 0); __builtin_amdgcn_s_setprio(0); } while (0)
; #define PG8_WAIT_V(n) asm volatile("s_waitcnt vmcnt(" #n ")" ::: "memory")
; #define PG8_WAIT_L(n) asm volatile("s_waitcnt lgkmcnt(" #n ")" ::: "memory")
; #define PG8_BAR __builtin_amdgcn_s_barrier()
; #define PG8_SCHED __builtin_amdgcn_sched_barrier(0)
; template <class Epi>
; __device__ __forceinline__ void gemm_phase(LAS unsigned char* lds, const Gemm g, const StaticOrder& S, const Epi& E) {
;     ...
;             PG8_LDA(At, 1, 1); PG8_STAGE(PG8_SA(1, 0), a3, voffA);
;             PG8_BAR; PG8_WAIT_L(0); PG8_MMA(1, 0, At, B0); PG8_BAR; PG8_SCHED;
;             PG8_STAGE(PG8_SB(1, 1), b3 + hstep, voffB);
;             PG8_WAIT_V(6); PG8_BAR; PG8_MMA(1, 1, At, B1); PG8_BAR;
;     __device__ __forceinline__ void operator()(const Acc& acc, const Unit& u, int wr, int wc, int fr, int fq) const {
;         const int row0 = u.pm * 256 + wr * 64 + fr, col0 = u.pn * 256 + wc * 32 + 8 * fq;
;         const bf16_t* __restrict__ xr = xres; bf16_t* __restrict__ op = out;
;         f32x4 gv[2][2], bv[2][2];
;         if (stats) {
; #pragma unroll
;             for (int bj = 0; bj < 2; ++bj)
; #pragma unroll
;                 for (int n = 0; n < 2; ++n) { gv[bj][n] = *(const f32x4*)(lg + col0 + bj * 128 + n * 4); bv[bj][n] = *(const f32x4*)(lb + col0 + bj * 128 + n * 4); } }
	s_waitcnt lgkmcnt(0)
	s_waitcnt lgkmcnt(0)
	v_mfma_f32_16x16x32_bf16 v[68:71], v[226:229], v[116:119], v[68:71]
	v_mfma_f32_16x16x32_bf16 v[132:135], v[218:221], v[116:119], v[148:151]
	v_mfma_f32_16x16x32_bf16 v[144:147], v[204:207], v[128:131], v[68:71]
	v_mfma_f32_16x16x32_bf16 v[68:71], v[218:221], v[160:163], v[76:79]
	v_mfma_f32_16x16x32_bf16 v[148:151], v[222:225], v[128:131], v[132:135]
	v_mfma_f32_16x16x32_bf16 v[132:135], v[222:225], v[164:167], v[68:71]
	v_mfma_f32_16x16x32_bf16 v[68:71], v[226:229], v[160:163], v[80:83]
	v_mfma_f32_16x16x32_bf16 v[128:131], v[204:207], v[164:167], v[68:71]
	v_mfma_f32_16x16x32_bf16 v[68:71], v[218:221], v[168:171], v[84:87]
	v_mfma_f32_16x16x32_bf16 v[116:119], v[222:225], v[172:175], v[68:71]
	v_mfma_f32_16x16x32_bf16 v[68:71], v[226:229], v[168:171], v[112:115]
	v_mfma_f32_16x16x32_bf16 v[112:115], v[204:207], v[172:175], v[68:71]
	v_mfma_f32_16x16x32_bf16 v[68:71], v[218:221], v[176:179], v[100:103]
	v_mfma_f32_16x16x32_bf16 v[100:103], v[222:225], v[180:183], v[68:71]
	v_mfma_f32_16x16x32_bf16 v[68:71], v[226:229], v[176:179], v[96:99]
	v_mfma_f32_16x16x32_bf16 v[96:99], v[204:207], v[180:183], v[68:71]
	s_mov_b32 m0, s50
	v_lshl_add_u64 v[176:177], v[238:239], 0, s[58:59]
	s_barrier
	s_nop 2
	ds_read_b128 v[68:71], v248 offset:49152
	ds_read_b128 v[76:79], v248 offset:50176
	ds_read_b128 v[80:83], v248 offset:51200
	ds_read_b128 v[84:87], v248 offset:52224
	ds_read_b128 v[160:163], v248 offset:53248
	ds_read_b128 v[164:167], v248 offset:54272
	ds_read_b128 v[168:171], v248 offset:55296
	ds_read_b128 v[172:175], v248 offset:56320
	global_load_lds_dwordx4 v[176:177], off
	v_lshl_add_u64 v[176:177], v[188:189], 0, s[58:59]
	s_mov_b32 m0, s51
	s_nop 0
	global_load_lds_dwordx4 v[176:177], off
	s_barrier
	s_waitcnt lgkmcnt(0)
	s_waitcnt lgkmcnt(0)
	v_mfma_f32_16x16x32_bf16 v[92:95], v[56:59], v[68:71], v[92:95]
	v_mfma_f32_16x16x32_bf16 v[92:95], v[60:63], v[76:79], v[92:95]
	v_mfma_f32_16x16x32_bf16 v[44:47], v[56:59], v[80:83], v[44:47]
	v_mfma_f32_16x16x32_bf16 v[44:47], v[60:63], v[84:87], v[44:47]
	v_mfma_f32_16x16x32_bf16 v[28:31], v[56:59], v[160:163], v[28:31]
	v_mfma_f32_16x16x32_bf16 v[28:31], v[60:63], v[164:167], v[28:31]
	v_mfma_f32_16x16x32_bf16 v[12:15], v[56:59], v[168:171], v[12:15]
	v_mfma_f32_16x16x32_bf16 v[12:15], v[60:63], v[172:175], v[12:15]
	v_mfma_f32_16x16x32_bf16 v[8:11], v[64:67], v[168:171], v[8:11]
	v_mfma_f32_16x16x32_bf16 v[8:11], v[72:75], v[172:175], v[8:11]
	v_mfma_f32_16x16x32_bf16 v[24:27], v[64:67], v[160:163], v[24:27]
	v_mfma_f32_16x16x32_bf16 v[24:27], v[72:75], v[164:167], v[24:27]
	v_mfma_f32_16x16x32_bf16 v[40:43], v[64:67], v[80:83], v[40:43]
	v_mfma_f32_16x16x32_bf16 v[40:43], v[72:75], v[84:87], v[40:43]
	v_mfma_f32_16x16x32_bf16 v[88:91], v[64:67], v[68:71], v[88:91]
	v_mfma_f32_16x16x32_bf16 v[88:91], v[72:75], v[76:79], v[88:91]
	s_barrier
	s_add_i32 s8, s8, s41
	v_lshl_add_u64 v[56:57], v[190:191], 0, s[58:59]
	s_mov_b32 m0, s8
	s_nop 0
	global_load_lds_dwordx4 v[56:57], off
	v_lshl_add_u64 v[56:57], v[192:193], 0, s[58:59]
	s_add_i32 m0, s8, 0x2000
	s_nop 0
	global_load_lds_dwordx4 v[56:57], off
	s_waitcnt vmcnt(6)
	s_barrier
	v_mfma_f32_16x16x32_bf16 v[48:51], v[218:221], v[68:71], v[48:51]
	v_mfma_f32_16x16x32_bf16 v[72:75], v[222:225], v[76:79], v[48:51]
	v_mfma_f32_16x16x32_bf16 v[48:51], v[226:229], v[68:71], v[52:55]
	v_mfma_f32_16x16x32_bf16 v[36:39], v[218:221], v[80:83], v[36:39]
	v_mfma_f32_16x16x32_bf16 v[32:35], v[226:229], v[80:83], v[32:35]
	v_mfma_f32_16x16x32_bf16 v[20:23], v[218:221], v[160:163], v[20:23]
	v_mfma_f32_16x16x32_bf16 v[16:19], v[226:229], v[160:163], v[16:19]
	v_mfma_f32_16x16x32_bf16 v[4:7], v[218:221], v[168:171], v[4:7]
	v_mfma_f32_16x16x32_bf16 v[0:3], v[226:229], v[168:171], v[0:3]
	v_mfma_f32_16x16x32_bf16 v[64:67], v[204:207], v[76:79], v[48:51]
	v_mfma_f32_16x16x32_bf16 v[36:39], v[222:225], v[84:87], v[36:39]
	v_mfma_f32_16x16x32_bf16 v[32:35], v[204:207], v[84:87], v[32:35]
	v_mfma_f32_16x16x32_bf16 v[20:23], v[222:225], v[164:167], v[20:23]
	v_mfma_f32_16x16x32_bf16 v[16:19], v[204:207], v[164:167], v[16:19]
	v_mfma_f32_16x16x32_bf16 v[4:7], v[222:225], v[172:175], v[4:7]
	v_mfma_f32_16x16x32_bf16 v[0:3], v[204:207], v[172:175], v[0:3]
	s_add_u32 s0, s0, 0x100
	s_addc_u32 s1, s1, 0
	s_add_u32 s43, s43, 0x100
	s_addc_u32 s63, s63, 0
	s_cmp_ge_u32 s68, s54
	s_mov_b32 s8, s68
	s_barrier
	s_cbranch_scc0 .LBB0_591
	v_lshl_or_b32 v224, s42, 8, v247
	v_cndmask_b32_e64 v48, 0, 1, s[30:31]
	v_cmp_ne_u32_e64 s[8:9], 1, v48
	s_andn2_b64 vcc, exec, s[30:31]
	v_ashrrev_i32_e32 v225, 31, v224
	s_cbranch_vccnz .LBB0_594
	v_lshlrev_b64 v[48:49], 2, v[224:225]
	v_lshl_add_u64 v[52:53], s[20:21], 0, v[48:49]
	v_lshl_add_u64 v[60:61], s[22:23], 0, v[48:49]
	global_load_dwordx4 v[68:71], v[52:53], off offset:16
	global_load_dwordx4 v[80:83], v[52:53], off
	global_load_dwordx4 v[76:79], v[60:61], off offset:16
	global_load_dwordx4 v[84:87], v[60:61], off
	global_load_dwordx4 v[48:51], v[52:53], off offset:528
	global_load_dwordx4 v[56:59], v[52:53], off offset:512
	s_nop 0
	global_load_dwordx4 v[52:55], v[60:61], off offset:528
	s_nop 0
	global_load_dwordx4 v[60:63], v[60:61], off offset:512

; #define PG8_STAGE(bufoff, gbase, voff) do { _Pragma("unroll") for (int _i = 0; _i < 2; ++_i) \
;         __builtin_amdgcn_global_load_lds((const unsigned*)((const char*)(gbase) + (voff)[_i]), (LAS unsigned*)(lds + (bufoff) + ldsw + _i * 8192), 16, 0, 0); } while (0)
; #define PG8_BAR __builtin_amdgcn_s_barrier()
;     __device__ bool next(int i, Unit& u) const {
;         const long L = (long)i * G + c; if (L >= nwg) return false;
;         int wgid = (int)L; { const int q = nwg / NXCD, r = nwg % NXCD, xcd = wgid % NXCD, off = wgid / NXCD; wgid = (xcd < r ? xcd * (q + 1) : r * (q + 1) + (xcd - r) * q) + off; }
;         const int nig = WGM * nN, gid = wgid / nig, fm = gid * WGM, gsz = (nM - fm) < WGM ? (nM - fm) : WGM;
;         u.pm = fm + ((wgid % nig) % gsz); u.pn = (wgid % nig) / gsz; return true;
; template <class Epi>
; __device__ __forceinline__ void gemm_phase(LAS unsigned char* lds, const Gemm g, const StaticOrder& S, const Epi& E) {
;     ...
;     for (int i = 0; i < 2; ++i) { int R, C; stage_rc(tid * 16 + i * 8192, R, C); const int Rb = Epi::PERM ? ((R & ~31) + perm32(R & 31)) : R;
;         voffA[i] = (unsigned)(R * K + C) * 2u; voffB[i] = (unsigned)(Rb * K + C) * 2u; }
;     const size_t kstep = (size_t)(BK * 2);
;     const size_t hstep = (size_t)HALF * K * 2;
;     const size_t tstep = 2 * hstep;
;     const unsigned ldsw = (unsigned)wid * 1024u;
;     const int aoff = lds_byte(wr * 64 + fr, fq * 8), boff = lds_byte(wc * 32 + fr, fq * 8);
;     ...
;     Unit cur, nxt; int ui = 0;
;     if (!S.next(0, cur)) return;
;     f32x4 acc[2][2][4][2];
; #pragma unroll
;     for (int a = 0; a < 2; ++a)
; #pragma unroll
;         for (int b = 0; b < 2; ++b)
; #pragma unroll
;             for (int m = 0; m < 4; ++m)
; #pragma unroll
;                 for (int n = 0; n < 2; ++n) acc[a][b][m][n] = (f32x4){0.f, 0.f, 0.f, 0.f};
;     bf16x8 At[4][2], B0[2][2], B1[2][2];
;     const char* cA = (const char*)g.A + (size_t)cur.pm * tstep; const char* cB = (const char*)g.Bt + (size_t)cur.pn * tstep;
;     PG8_STAGE(PG8_SB(0, 0), cB, voffB); PG8_STAGE(PG8_SA(0, 0), cA, voffA); PG8_STAGE(PG8_SB(0, 1), cB + hstep, voffB); PG8_STAGE(PG8_SA(0, 1), cA + hstep, voffA);
;     if (wr == 1) PG8_BAR;
.LBB0_712:
	s_andn2_b64 vcc, exec, s[0:1]
	s_cbranch_vccnz .LBB0_785
	v_readlane_b32 s0, v255, 40
	s_cmp_gt_i32 s0, 0
	s_mov_b64 s[0:1], -1
	s_cbranch_scc0 .LBB0_727
	s_mov_b32 s0, s2
	s_cmp_ge_i32 s0, s82
	s_cselect_b32 s1, s82, 0
	s_sub_i32 s22, s0, s1
	v_mov_b32_e32 v0, v234
	s_cmpk_gt_i32 s22, 0x1b7f
	v_readfirstlane_b32 s23, v0
	s_cbranch_scc1 .LBB0_726
	s_waitcnt vmcnt(0)
	v_lshlrev_b32_e32 v4, 4, v0
	v_add_u32_e32 v2, 0x2000, v4
	v_ashrrev_i32_e32 v1, 31, v2
	v_lshrrev_b32_e32 v1, 22, v1
	v_add_u32_e32 v1, v2, v1
	v_ashrrev_i32_e32 v1, 10, v1
	v_mul_i32_i24_e32 v3, 0x400, v1
	v_sub_u32_e32 v2, v2, v3
	v_lshrrev_b32_e32 v3, 4, v2
	v_bitop3_b32 v3, v3, v2, 32 bitop3:0x6c
	v_ashrrev_i32_e32 v2, 31, v3
	v_lshrrev_b32_e32 v2, 26, v2
	v_add_u32_e32 v5, v3, v2
	v_lshlrev_b32_e32 v6, 3, v1
	v_ashrrev_i32_e32 v2, 6, v5
	v_and_b32_e32 v6, -16, v6
	v_add_u32_e32 v6, v2, v6
	v_and_b32_e32 v7, 3, v2
	s_mov_b32 s0, 0xfffe0
	v_lshrrev_b32_e32 v8, 2, v6
	v_lshlrev_b32_e32 v9, 1, v6
	v_and_b32_e32 v5, 0xc0, v5
	v_and_or_b32 v7, v6, s0, v7
	v_and_b32_e32 v8, 4, v8
	v_and_b32_e32 v9, 24, v9
	v_sub_u32_e32 v3, v3, v5
	v_or3_b32 v7, v7, v8, v9
	v_lshlrev_b32_e32 v8, 5, v1
	v_ashrrev_i16_sdwa v3, v236, sext(v3) dst_sel:DWORD dst_unused:UNUSED_PAD src0_sel:DWORD src1_sel:BYTE_0
	v_and_b32_e32 v8, 32, v8
	v_bfe_i32 v3, v3, 0, 16
	v_add_lshl_u32 v5, v8, v3, 1
	v_lshl_add_u32 v128, v7, 12, v5
	v_lshl_add_u32 v130, v6, 12, v5
	v_bfe_i32 v5, v0, 27, 1
	v_lshrrev_b32_e32 v5, 22, v5
	v_add_u32_e32 v5, v4, v5
	v_and_b32_e32 v5, 0xfffffc00, v5
	v_sub_u32_e32 v4, v4, v5
	v_lshrrev_b32_e32 v5, 4, v4
	v_bitop3_b32 v6, v5, v4, 32 bitop3:0x6c
	v_ashrrev_i32_e32 v5, 31, v0
	v_lshrrev_b32_e32 v5, 26, v5
	v_ashrrev_i32_e32 v4, 31, v4
	v_add_u32_e32 v5, v0, v5
	v_lshrrev_b32_e32 v4, 26, v4
	v_ashrrev_i32_e32 v5, 6, v5
	v_add_u32_e32 v4, v6, v4
	v_lshlrev_b32_e32 v7, 3, v5
	v_ashrrev_i32_e32 v4, 6, v4
	v_and_b32_e32 v7, -16, v7
	v_add_u32_e32 v7, v4, v7
	v_and_b32_e32 v8, 3, v4
	s_ashr_i32 s25, s22, 31
	v_and_or_b32 v8, v7, s0, v8
	s_lshr_b32 s0, s25, 29
	s_add_i32 s0, s22, s0
	s_ashr_i32 s3, s23, 6
	s_ashr_i32 s6, s0, 3
	s_and_b32 s0, s0, -8
	s_ashr_i32 s1, s23, 8
	s_lshl_b32 s24, s3, 10
	s_sub_i32 s0, s22, s0
	s_cmp_lt_i32 s0, 0
	s_movk_i32 s43, 0x371
	s_cselect_b32 s7, s43, 0x370
	s_mul_i32 s0, s7, s0
	s_add_i32 s0, s0, s6
	s_mul_hi_i32 s6, s0, 0x2e8ba2e9
	s_lshr_b32 s7, s6, 31
	s_ashr_i32 s6, s6, 6
	s_add_i32 s6, s6, s7
	s_lshl_b32 s7, s6, 3
	s_mulk_i32 s6, 0x160
	s_sub_i32 s6, s0, s6
	s_bfe_u32 s0, s6, 0x3001c
	s_add_i32 s8, s6, s0
	s_sext_i32_i16 s0, s8
	s_and_b32 s8, s8, 0xfff8
	v_lshrrev_b32_e32 v9, 2, v7
	v_lshlrev_b32_e32 v10, 1, v7
	s_sub_i32 s6, s6, s8
	v_and_b32_e32 v9, 4, v9
	v_and_b32_e32 v10, 24, v10
	s_sext_i32_i16 s6, s6
	v_or3_b32 v8, v8, v9, v10
	v_mul_i32_i24_e32 v10, 64, v4
	s_lshr_b32 s0, s0, 3
	s_add_i32 s14, s7, s6
	v_sub_u32_e32 v6, v6, v10
	s_ashr_i32 s15, s14, 31
	s_bfe_i64 s[8:9], s[0:1], 0x100000
	v_lshlrev_b32_e32 v9, 5, v5
	v_ashrrev_i16_sdwa v6, v236, sext(v6) dst_sel:DWORD dst_unused:UNUSED_PAD src0_sel:DWORD src1_sel:BYTE_0
	s_lshl_b64 s[6:7], s[14:15], 20
	s_lshl_b64 s[8:9], s[8:9], 20
	v_and_b32_e32 v9, 32, v9
	v_bfe_i32 v6, v6, 0, 16
	s_add_u32 s18, s80, s8
	v_add_lshl_u32 v9, v9, v6, 1
	s_addc_u32 s19, s81, s9
	s_add_i32 s15, s24, 0
	v_lshl_add_u32 v184, v8, 12, v9
	s_add_i32 m0, s15, 0x10000
	v_lshl_add_u32 v132, v7, 12, v9
	global_load_lds_dwordx4 v184, s[18:19]
	s_add_i32 m0, s15, 0x12000
	s_add_u32 s16, s90, s6
	global_load_lds_dwordx4 v128, s[18:19]
	s_addc_u32 s17, s91, s7
	s_mov_b32 m0, s15
	s_add_i32 s26, s15, 0x2000
	global_load_lds_dwordx4 v132, s[16:17]
	s_mov_b32 m0, s26
	s_add_u32 s6, s18, 0x80000
	global_load_lds_dwordx4 v130, s[16:17]
	s_addc_u32 s7, s19, 0
	s_add_i32 m0, s15, 0x14000
	s_nop 0
	global_load_lds_dwordx4 v184, s[6:7]
	s_add_i32 m0, s15, 0x16000
	s_nop 0
	global_load_lds_dwordx4 v128, s[6:7]
	s_add_u32 s6, s16, 0x80000
	s_addc_u32 s7, s17, 0
	s_add_i32 s27, s15, 0x4000
	s_mov_b32 m0, s27
	s_add_i32 s28, s15, 0x6000
	global_load_lds_dwordx4 v132, s[6:7]
	s_mov_b32 m0, s28
	s_cmp_lg_u32 s1, 1
	global_load_lds_dwordx4 v130, s[6:7]
	s_cbranch_scc1 .LBB0_717
	s_setprio 1
	s_barrier

; #define PG8_STAGE(bufoff, gbase, voff) do { _Pragma("unroll") for (int _i = 0; _i < 2; ++_i) \
;         __builtin_amdgcn_global_load_lds((const unsigned*)((const char*)(gbase) + (voff)[_i]), (LAS unsigned*)(lds + (bufoff) + ldsw + _i * 8192), 16, 0, 0); } while (0)
; #define PG8_LDA(dst, b, h) do { _Pragma("unroll") for (int m = 0; m < 4; ++m) _Pragma("unroll") for (int k = 0; k < 2; ++k) dst[m][k] = *(const LAS bf16x8*)(lds + PG8_SA(b, h) + aoff + m * 2048 + k * 1024); } while (0)
; #define PG8_LDB(dst, b, h) do { _Pragma("unroll") for (int n = 0; n < 2; ++n) _Pragma("unroll") for (int k = 0; k < 2; ++k) dst[n][k] = *(const LAS bf16x8*)(lds + PG8_SB(b, h) + boff + n * 2048 + k * 1024); } while (0)
; #define PG8_MMA(ai, bj, At, Bt) do { __builtin_amdgcn_s_setprio(1); _Pragma("unroll") for (int m = 0; m < 4; ++m) _Pragma("unroll") for (int n = 0; n < 2; ++n) _Pragma("unroll") for (int k = 0; k < 2; ++k) \
;         acc[ai][bj][m][n] = __builtin_amdgcn_mfma_f32_16x16x32_bf16(Bt[n][k], At[m][k], acc[ai][bj][m][n], 0, 0, 0); __builtin_amdgcn_s_setprio(0); } while (0)
; #define PG8_WAIT_L(n) asm volatile("s_waitcnt lgkmcnt(" #n ")" ::: "memory")
; #define PG8_BAR __builtin_amdgcn_s_barrier()
; #define PG8_SCHED __builtin_amdgcn_sched_barrier(0)
; template <class Epi>
; __device__ __forceinline__ void gemm_phase(LAS unsigned char* lds, const Gemm g, const StaticOrder& S, const Epi& E) {
;     ...
;             const char* a1 = cA + (size_t)(t + 1) * kstep;
;             const char* a2 = last ? nA : cA + (size_t)(t + 2) * kstep; const char* b2 = last ? nB : cB + (size_t)(t + 2) * kstep;
;             const char* a3 = a2 + kstep; const char* b3 = b2 + kstep;
;             PG8_LDB(B0, 0, 0); PG8_SCHED; PG8_LDA(At, 0, 0); PG8_STAGE(PG8_SA(1, 1), a1 + hstep, voffA);
;             PG8_WAIT_L(8); PG8_BAR; PG8_WAIT_L(0); PG8_MMA(0, 0, At, B0); PG8_BAR; PG8_SCHED;
;             PG8_LDB(B1, 0, 1); PG8_STAGE(PG8_SB(0, 0), b2, voffB);
;             PG8_BAR; PG8_WAIT_L(0); PG8_MMA(0, 1, At, B1); PG8_BAR;
;             PG8_LDA(At, 0, 1); PG8_STAGE(PG8_SA(0, 0), a2, voffA);
;             PG8_BAR; PG8_WAIT_L(0); PG8_MMA(1, 0, At, B0); PG8_BAR; PG8_SCHED;
.LBB0_721:
	s_add_u32 s18, s16, 0xfff80080
	s_addc_u32 s19, s17, -1
	s_add_i32 s39, 0, 0x10000
	v_add_u32_e32 v154, s39, v139
	ds_read_b128 v[142:145], v154
	ds_read_b128 v[146:149], v154 offset:1024
	ds_read_b128 v[150:153], v154 offset:2048
	ds_read_b128 v[154:157], v154 offset:3072
	s_cmp_eq_u32 s38, 28
	s_cselect_b32 s21, s9, s19
	s_cselect_b32 s20, s34, s18
	s_cselect_b32 s19, s1, s37
	s_cselect_b32 s18, s35, s36
	v_lshl_add_u64 v[182:183], s[16:17], 0, v[134:135]
	s_add_i32 m0, s15, 0xc000
	ds_read_b128 v[158:161], v141
	ds_read_b128 v[162:165], v141 offset:1024
	ds_read_b128 v[166:169], v141 offset:2048
	ds_read_b128 v[170:173], v141 offset:3072
	ds_read_b128 v[174:177], v141 offset:4096
	ds_read_b128 v[178:181], v141 offset:5120
	ds_read_b128 v[208:211], v141 offset:6144
	ds_read_b128 v[212:215], v141 offset:7168
	global_load_lds_dwordx4 v[182:183], off
	v_lshl_add_u64 v[182:183], s[16:17], 0, v[136:137]
	s_add_i32 m0, s15, 0xe000
	s_nop 0
	global_load_lds_dwordx4 v[182:183], off
	s_waitcnt lgkmcnt(8)
	s_barrier
	s_waitcnt lgkmcnt(0)
	s_waitcnt lgkmcnt(0)
	v_mfma_f32_16x16x32_bf16 v[124:127], v[142:145], v[158:161], v[124:127]
	v_mfma_f32_16x16x32_bf16 v[124:127], v[146:149], v[162:165], v[124:127]
	v_mfma_f32_16x16x32_bf16 v[108:111], v[142:145], v[166:169], v[108:111]
	v_mfma_f32_16x16x32_bf16 v[108:111], v[146:149], v[170:173], v[108:111]
	v_mfma_f32_16x16x32_bf16 v[92:95], v[142:145], v[174:177], v[92:95]
	v_mfma_f32_16x16x32_bf16 v[92:95], v[146:149], v[178:181], v[92:95]
	v_mfma_f32_16x16x32_bf16 v[76:79], v[142:145], v[208:211], v[76:79]
	v_mfma_f32_16x16x32_bf16 v[76:79], v[146:149], v[212:215], v[76:79]
	v_mfma_f32_16x16x32_bf16 v[68:71], v[150:153], v[208:211], v[68:71]
	v_mfma_f32_16x16x32_bf16 v[68:71], v[154:157], v[212:215], v[68:71]
	v_mfma_f32_16x16x32_bf16 v[84:87], v[150:153], v[174:177], v[84:87]
	v_mfma_f32_16x16x32_bf16 v[84:87], v[154:157], v[178:181], v[84:87]
	v_mfma_f32_16x16x32_bf16 v[100:103], v[150:153], v[166:169], v[100:103]
	v_mfma_f32_16x16x32_bf16 v[100:103], v[154:157], v[170:173], v[100:103]
	v_mfma_f32_16x16x32_bf16 v[116:119], v[150:153], v[158:161], v[116:119]
	v_mfma_f32_16x16x32_bf16 v[116:119], v[154:157], v[162:165], v[116:119]
	s_barrier
	s_add_i32 s42, 0, 0x14000
	v_add_u32_e32 v182, s42, v139
	s_add_i32 s39, s39, s24
	ds_read_b128 v[216:219], v182
	ds_read_b128 v[220:223], v182 offset:1024
	ds_read_b128 v[224:227], v182 offset:2048
	ds_read_b128 v[228:231], v182 offset:3072
	v_lshl_add_u64 v[182:183], s[18:19], 0, v[184:185]
	s_mov_b32 m0, s39
	v_lshl_add_u64 v[204:205], s[18:19], 0, v[128:129]
	global_load_lds_dwordx4 v[182:183], off
	s_add_i32 m0, s39, 0x2000
	s_nop 0
	global_load_lds_dwordx4 v[204:205], off
	s_barrier
	s_waitcnt lgkmcnt(0)
	s_waitcnt lgkmcnt(0)
	v_mfma_f32_16x16x32_bf16 v[120:123], v[216:219], v[158:161], v[120:123]
	v_mfma_f32_16x16x32_bf16 v[120:123], v[220:223], v[162:165], v[120:123]
	v_mfma_f32_16x16x32_bf16 v[104:107], v[216:219], v[166:169], v[104:107]
	v_mfma_f32_16x16x32_bf16 v[104:107], v[220:223], v[170:173], v[104:107]
	v_mfma_f32_16x16x32_bf16 v[88:91], v[216:219], v[174:177], v[88:91]
	v_mfma_f32_16x16x32_bf16 v[88:91], v[220:223], v[178:181], v[88:91]
	v_mfma_f32_16x16x32_bf16 v[72:75], v[216:219], v[208:211], v[72:75]
	v_mfma_f32_16x16x32_bf16 v[72:75], v[220:223], v[212:215], v[72:75]
	v_mfma_f32_16x16x32_bf16 v[64:67], v[224:227], v[208:211], v[64:67]
	v_mfma_f32_16x16x32_bf16 v[64:67], v[228:231], v[212:215], v[64:67]
	v_mfma_f32_16x16x32_bf16 v[80:83], v[224:227], v[174:177], v[80:83]
	v_mfma_f32_16x16x32_bf16 v[80:83], v[228:231], v[178:181], v[80:83]
	v_mfma_f32_16x16x32_bf16 v[96:99], v[224:227], v[166:169], v[96:99]
	v_mfma_f32_16x16x32_bf16 v[96:99], v[228:231], v[170:173], v[96:99]
	v_mfma_f32_16x16x32_bf16 v[112:115], v[224:227], v[158:161], v[112:115]
	v_mfma_f32_16x16x32_bf16 v[112:115], v[228:231], v[162:165], v[112:115]
	s_mov_b32 m0, s15
	v_lshl_add_u64 v[206:207], s[20:21], 0, v[132:133]
	s_barrier
	ds_read_b128 v[158:161], v141 offset:16384
	ds_read_b128 v[162:165], v141 offset:17408
	ds_read_b128 v[166:169], v141 offset:18432
	ds_read_b128 v[170:173], v141 offset:19456
	ds_read_b128 v[174:177], v141 offset:20480
	ds_read_b128 v[178:181], v141 offset:21504
	ds_read_b128 v[208:211], v141 offset:22528
	ds_read_b128 v[212:215], v141 offset:23552
	global_load_lds_dwordx4 v[206:207], off
	v_lshl_add_u64 v[232:233], s[20:21], 0, v[130:131]
	s_mov_b32 m0, s26
	s_nop 0
	global_load_lds_dwordx4 v[232:233], off
	s_barrier
	s_waitcnt lgkmcnt(0)
	s_waitcnt lgkmcnt(0)
	v_mfma_f32_16x16x32_bf16 v[60:63], v[142:145], v[158:161], v[60:63]
	v_mfma_f32_16x16x32_bf16 v[60:63], v[146:149], v[162:165], v[60:63]
	v_mfma_f32_16x16x32_bf16 v[44:47], v[142:145], v[166:169], v[44:47]
	v_mfma_f32_16x16x32_bf16 v[44:47], v[146:149], v[170:173], v[44:47]
	v_mfma_f32_16x16x32_bf16 v[28:31], v[142:145], v[174:177], v[28:31]
	v_mfma_f32_16x16x32_bf16 v[28:31], v[146:149], v[178:181], v[28:31]
	v_mfma_f32_16x16x32_bf16 v[12:15], v[142:145], v[208:211], v[12:15]
	v_mfma_f32_16x16x32_bf16 v[12:15], v[146:149], v[212:215], v[12:15]
	v_mfma_f32_16x16x32_bf16 v[4:7], v[150:153], v[208:211], v[4:7]
	v_mfma_f32_16x16x32_bf16 v[4:7], v[154:157], v[212:215], v[4:7]
	v_mfma_f32_16x16x32_bf16 v[20:23], v[150:153], v[174:177], v[20:23]
	v_mfma_f32_16x16x32_bf16 v[20:23], v[154:157], v[178:181], v[20:23]
	v_mfma_f32_16x16x32_bf16 v[36:39], v[150:153], v[166:169], v[36:39]
	v_mfma_f32_16x16x32_bf16 v[36:39], v[154:157], v[170:173], v[36:39]
	v_mfma_f32_16x16x32_bf16 v[52:55], v[150:153], v[158:161], v[52:55]
	v_mfma_f32_16x16x32_bf16 v[52:55], v[154:157], v[162:165], v[52:55]
	s_barrier
; #define PG8_STAGE(bufoff, gbase, voff) do { _Pragma("unroll") for (int _i = 0; _i < 2; ++_i) \
;         __builtin_amdgcn_global_load_lds((const unsigned*)((const char*)(gbase) + (voff)[_i]), (LAS unsigned*)(lds + (bufoff) + ldsw + _i * 8192), 16, 0, 0); } while (0)
; #define PG8_LDA(dst, b, h) do { _Pragma("unroll") for (int m = 0; m < 4; ++m) _Pragma("unroll") for (int k = 0; k < 2; ++k) dst[m][k] = *(const LAS bf16x8*)(lds + PG8_SA(b, h) + aoff + m * 2048 + k * 1024); } while (0)
; #define PG8_LDB(dst, b, h) do { _Pragma("unroll") for (int n = 0; n < 2; ++n) _Pragma("unroll") for (int k = 0; k < 2; ++k) dst[n][k] = *(const LAS bf16x8*)(lds + PG8_SB(b, h) + boff + n * 2048 + k * 1024); } while (0)
; #define PG8_MMA(ai, bj, At, Bt) do { __builtin_amdgcn_s_setprio(1); _Pragma("unroll") for (int m = 0; m < 4; ++m) _Pragma("unroll") for (int n = 0; n < 2; ++n) _Pragma("unroll") for (int k = 0; k < 2; ++k) \
;         acc[ai][bj][m][n] = __builtin_amdgcn_mfma_f32_16x16x32_bf16(Bt[n][k], At[m][k], acc[ai][bj][m][n], 0, 0, 0); __builtin_amdgcn_s_setprio(0); } while (0)
; #define PG8_WAIT_V(n) asm volatile("s_waitcnt vmcnt(" #n ")" ::: "memory")
; #define PG8_WAIT_L(n) asm volatile("s_waitcnt lgkmcnt(" #n ")" ::: "memory")
; #define PG8_BAR __builtin_amdgcn_s_barrier()
; #define PG8_SCHED __builtin_amdgcn_sched_barrier(0)
; template <class Epi>
; __device__ __forceinline__ void gemm_phase(LAS unsigned char* lds, const Gemm g, const StaticOrder& S, const Epi& E) {
;     ...
;             PG8_STAGE(PG8_SB(0, 1), b2 + hstep, voffB);
;             PG8_WAIT_V(6); PG8_BAR; PG8_MMA(1, 1, At, B1); PG8_BAR;
;             PG8_LDB(B0, 1, 0); PG8_SCHED; PG8_LDA(At, 1, 0); PG8_STAGE(PG8_SA(0, 1), a2 + hstep, voffA);
;             PG8_WAIT_L(8); PG8_BAR; PG8_WAIT_L(0); PG8_MMA(0, 0, At, B0); PG8_BAR; PG8_SCHED;
;             PG8_LDB(B1, 1, 1); PG8_STAGE(PG8_SB(1, 0), b3, voffB);
;             PG8_BAR; PG8_WAIT_L(0); PG8_MMA(0, 1, At, B1); PG8_BAR;
	s_add_u32 s40, s18, 0x80000
	s_addc_u32 s41, s19, 0
	s_add_i32 s39, s42, s24
	v_lshl_add_u64 v[142:143], s[40:41], 0, v[184:185]
	s_mov_b32 m0, s39
	s_nop 0
	global_load_lds_dwordx4 v[142:143], off
	v_lshl_add_u64 v[142:143], s[40:41], 0, v[128:129]
	s_add_i32 m0, s39, 0x2000
	s_nop 0
	global_load_lds_dwordx4 v[142:143], off
	s_waitcnt vmcnt(6)
	s_barrier
	v_mfma_f32_16x16x32_bf16 v[56:59], v[216:219], v[158:161], v[56:59]
	v_mfma_f32_16x16x32_bf16 v[56:59], v[220:223], v[162:165], v[56:59]
	v_mfma_f32_16x16x32_bf16 v[40:43], v[216:219], v[166:169], v[40:43]
	v_mfma_f32_16x16x32_bf16 v[40:43], v[220:223], v[170:173], v[40:43]
	v_mfma_f32_16x16x32_bf16 v[24:27], v[216:219], v[174:177], v[24:27]
	v_mfma_f32_16x16x32_bf16 v[24:27], v[220:223], v[178:181], v[24:27]
	v_mfma_f32_16x16x32_bf16 v[8:11], v[216:219], v[208:211], v[8:11]
	v_mfma_f32_16x16x32_bf16 v[8:11], v[220:223], v[212:215], v[8:11]
	v_mfma_f32_16x16x32_bf16 v[0:3], v[224:227], v[208:211], v[0:3]
	v_mfma_f32_16x16x32_bf16 v[0:3], v[228:231], v[212:215], v[0:3]
	v_mfma_f32_16x16x32_bf16 v[16:19], v[224:227], v[174:177], v[16:19]
	v_mfma_f32_16x16x32_bf16 v[16:19], v[228:231], v[178:181], v[16:19]
	v_mfma_f32_16x16x32_bf16 v[32:35], v[224:227], v[166:169], v[32:35]
	v_mfma_f32_16x16x32_bf16 v[32:35], v[228:231], v[170:173], v[32:35]
	v_mfma_f32_16x16x32_bf16 v[48:51], v[224:227], v[158:161], v[48:51]
	v_mfma_f32_16x16x32_bf16 v[48:51], v[228:231], v[162:165], v[48:51]
	s_add_i32 s39, 0, 0x18000
	v_add_u32_e32 v154, s39, v139
	s_barrier
	ds_read_b128 v[142:145], v154
	ds_read_b128 v[146:149], v154 offset:1024
	ds_read_b128 v[150:153], v154 offset:2048
	ds_read_b128 v[154:157], v154 offset:3072
	s_add_u32 s20, s20, 0x80000
	s_addc_u32 s21, s21, 0
	s_mov_b32 m0, s27
	v_lshl_add_u64 v[216:217], s[20:21], 0, v[132:133]
	ds_read_b128 v[158:161], v141 offset:32768
	ds_read_b128 v[162:165], v141 offset:33792
	ds_read_b128 v[166:169], v141 offset:34816
	ds_read_b128 v[170:173], v141 offset:35840
	ds_read_b128 v[174:177], v141 offset:36864
	ds_read_b128 v[178:181], v141 offset:37888
	ds_read_b128 v[208:211], v141 offset:38912
	ds_read_b128 v[212:215], v141 offset:39936
	global_load_lds_dwordx4 v[216:217], off
	v_lshl_add_u64 v[216:217], s[20:21], 0, v[130:131]
	s_mov_b32 m0, s28
	s_nop 0
	global_load_lds_dwordx4 v[216:217], off
	s_waitcnt lgkmcnt(8)
	s_barrier
	s_waitcnt lgkmcnt(0)
	s_waitcnt lgkmcnt(0)
	v_mfma_f32_16x16x32_bf16 v[124:127], v[142:145], v[158:161], v[124:127]
	v_mfma_f32_16x16x32_bf16 v[124:127], v[146:149], v[162:165], v[124:127]
	v_mfma_f32_16x16x32_bf16 v[108:111], v[142:145], v[166:169], v[108:111]
	v_mfma_f32_16x16x32_bf16 v[108:111], v[146:149], v[170:173], v[108:111]
	v_mfma_f32_16x16x32_bf16 v[92:95], v[142:145], v[174:177], v[92:95]
	v_mfma_f32_16x16x32_bf16 v[92:95], v[146:149], v[178:181], v[92:95]
	v_mfma_f32_16x16x32_bf16 v[76:79], v[142:145], v[208:211], v[76:79]
	v_mfma_f32_16x16x32_bf16 v[76:79], v[146:149], v[212:215], v[76:79]
	v_mfma_f32_16x16x32_bf16 v[68:71], v[150:153], v[208:211], v[68:71]
	v_mfma_f32_16x16x32_bf16 v[68:71], v[154:157], v[212:215], v[68:71]
	v_mfma_f32_16x16x32_bf16 v[84:87], v[150:153], v[174:177], v[84:87]
	v_mfma_f32_16x16x32_bf16 v[84:87], v[154:157], v[178:181], v[84:87]
	v_mfma_f32_16x16x32_bf16 v[100:103], v[150:153], v[166:169], v[100:103]
	v_mfma_f32_16x16x32_bf16 v[100:103], v[154:157], v[170:173], v[100:103]
	v_mfma_f32_16x16x32_bf16 v[116:119], v[150:153], v[158:161], v[116:119]
	v_mfma_f32_16x16x32_bf16 v[116:119], v[154:157], v[162:165], v[116:119]
	s_barrier
	s_add_i32 s20, 0, 0x1c000
	s_add_i32 s21, s39, s24
	v_add_u32_e32 v187, s20, v139
	v_lshl_add_u64 v[182:183], v[182:183], 0, s[58:59]
	s_mov_b32 m0, s21
	ds_read_b128 v[216:219], v187
	ds_read_b128 v[220:223], v187 offset:1024
	ds_read_b128 v[224:227], v187 offset:2048
	ds_read_b128 v[228:231], v187 offset:3072
	global_load_lds_dwordx4 v[182:183], off
	v_lshl_add_u64 v[182:183], v[204:205], 0, s[58:59]
	s_add_i32 m0, s21, 0x2000
	s_nop 0
	global_load_lds_dwordx4 v[182:183], off
	s_barrier
	s_waitcnt lgkmcnt(0)
	s_waitcnt lgkmcnt(0)
	v_mfma_f32_16x16x32_bf16 v[120:123], v[216:219], v[158:161], v[120:123]
	v_mfma_f32_16x16x32_bf16 v[120:123], v[220:223], v[162:165], v[120:123]
	v_mfma_f32_16x16x32_bf16 v[104:107], v[216:219], v[166:169], v[104:107]
	v_mfma_f32_16x16x32_bf16 v[104:107], v[220:223], v[170:173], v[104:107]
	v_mfma_f32_16x16x32_bf16 v[88:91], v[216:219], v[174:177], v[88:91]
	v_mfma_f32_16x16x32_bf16 v[88:91], v[220:223], v[178:181], v[88:91]
	v_mfma_f32_16x16x32_bf16 v[72:75], v[216:219], v[208:211], v[72:75]
	v_mfma_f32_16x16x32_bf16 v[72:75], v[220:223], v[212:215], v[72:75]
	v_mfma_f32_16x16x32_bf16 v[64:67], v[224:227], v[208:211], v[64:67]
	v_mfma_f32_16x16x32_bf16 v[64:67], v[228:231], v[212:215], v[64:67]
	v_mfma_f32_16x16x32_bf16 v[80:83], v[224:227], v[174:177], v[80:83]
	v_mfma_f32_16x16x32_bf16 v[80:83], v[228:231], v[178:181], v[80:83]
	v_mfma_f32_16x16x32_bf16 v[96:99], v[224:227], v[166:169], v[96:99]
	v_mfma_f32_16x16x32_bf16 v[96:99], v[228:231], v[170:173], v[96:99]
	v_mfma_f32_16x16x32_bf16 v[112:115], v[224:227], v[158:161], v[112:115]
	v_mfma_f32_16x16x32_bf16 v[112:115], v[228:231], v[162:165], v[112:115]
	s_mov_b32 m0, s29
	v_lshl_add_u64 v[182:183], v[206:207], 0, s[58:59]
	s_barrier
	ds_read_b128 v[158:161], v141 offset:49152
	ds_read_b128 v[162:165], v141 offset:50176
	ds_read_b128 v[166:169], v141 offset:51200
	ds_read_b128 v[170:173], v141 offset:52224
	ds_read_b128 v[174:177], v141 offset:53248
	ds_read_b128 v[178:181], v141 offset:54272
	ds_read_b128 v[208:211], v141 offset:55296
	ds_read_b128 v[212:215], v141 offset:56320
	global_load_lds_dwordx4 v[182:183], off
	v_lshl_add_u64 v[182:183], v[232:233], 0, s[58:59]
	s_mov_b32 m0, s30
	s_nop 0
	global_load_lds_dwordx4 v[182:183], off
	s_barrier
; __device__ __forceinline__ unsigned pk2(float lo, float hi) { unsigned r; asm("v_cvt_pk_bf16_f32 %0, %1, %2" : "=v"(r) : "v"(lo), "v"(hi)); return r; }
; __device__ __forceinline__ float sigmoidf_(float x) { return __builtin_amdgcn_rcpf(1.0f + __builtin_amdgcn_exp2f(-1.4426950408889634f * x)); }
; #define PG8_STAGE(bufoff, gbase, voff) do { _Pragma("unroll") for (int _i = 0; _i < 2; ++_i) \
;         __builtin_amdgcn_global_load_lds((const unsigned*)((const char*)(gbase) + (voff)[_i]), (LAS unsigned*)(lds + (bufoff) + ldsw + _i * 8192), 16, 0, 0); } while (0)
; #define PG8_LDA(dst, b, h) do { _Pragma("unroll") for (int m = 0; m < 4; ++m) _Pragma("unroll") for (int k = 0; k < 2; ++k) dst[m][k] = *(const LAS bf16x8*)(lds + PG8_SA(b, h) + aoff + m * 2048 + k * 1024); } while (0)
; #define PG8_MMA(ai, bj, At, Bt) do { __builtin_amdgcn_s_setprio(1); _Pragma("unroll") for (int m = 0; m < 4; ++m) _Pragma("unroll") for (int n = 0; n < 2; ++n) _Pragma("unroll") for (int k = 0; k < 2; ++k) \
;         acc[ai][bj][m][n] = __builtin_amdgcn_mfma_f32_16x16x32_bf16(Bt[n][k], At[m][k], acc[ai][bj][m][n], 0, 0, 0); __builtin_amdgcn_s_setprio(0); } while (0)
; template <class Epi>
; __device__ __forceinline__ void gemm_phase(LAS unsigned char* lds, const Gemm g, const StaticOrder& S, const Epi& E) {
;     ...
;             PG8_LDA(At, 1, 1); PG8_STAGE(PG8_SA(1, 0), a3, voffA);
;             PG8_BAR; PG8_WAIT_L(0); PG8_MMA(1, 0, At, B0); PG8_BAR; PG8_SCHED;
;             PG8_STAGE(PG8_SB(1, 1), b3 + hstep, voffB);
;             PG8_WAIT_V(6); PG8_BAR; PG8_MMA(1, 1, At, B1); PG8_BAR;
;     __device__ __forceinline__ void operator()(const Acc& acc, const Unit& u, int wr, int wc, int fr, int fq) const {
;         const int row0 = u.pm * 256 + wr * 64 + fr, col0 = u.pn * 128 + wc * 32 + 8 * fq;
; #pragma unroll
;         for (int ai = 0; ai < 2; ++ai)
; #pragma unroll
;             for (int m = 0; m < 4; ++m) {
;                 float h[8];
; #pragma unroll
;                 for (int n = 0; n < 2; ++n)
; #pragma unroll
;                     for (int j = 0; j < 4; ++j) { const float gv = acc[ai][0][m][n][j], uv = acc[ai][1][m][n][j]; h[n * 4 + j] = gv * sigmoidf_(gv) * uv; }
;                 u32x4 w; w.x = pk2(h[0], h[1]); w.y = pk2(h[2], h[3]); w.z = pk2(h[4], h[5]); w.w = pk2(h[6], h[7]);
;                 *(u32x4*)(H + (size_t)(row0 + ai * 128 + m * 16) * DFF + col0) = w;
	s_waitcnt lgkmcnt(0)
	s_waitcnt lgkmcnt(0)
	v_mfma_f32_16x16x32_bf16 v[60:63], v[142:145], v[158:161], v[60:63]
	v_mfma_f32_16x16x32_bf16 v[60:63], v[146:149], v[162:165], v[60:63]
	v_mfma_f32_16x16x32_bf16 v[44:47], v[142:145], v[166:169], v[44:47]
	v_mfma_f32_16x16x32_bf16 v[44:47], v[146:149], v[170:173], v[44:47]
	v_mfma_f32_16x16x32_bf16 v[28:31], v[142:145], v[174:177], v[28:31]
	v_mfma_f32_16x16x32_bf16 v[28:31], v[146:149], v[178:181], v[28:31]
	v_mfma_f32_16x16x32_bf16 v[12:15], v[142:145], v[208:211], v[12:15]
	v_mfma_f32_16x16x32_bf16 v[12:15], v[146:149], v[212:215], v[12:15]
	v_mfma_f32_16x16x32_bf16 v[4:7], v[150:153], v[208:211], v[4:7]
	v_mfma_f32_16x16x32_bf16 v[4:7], v[154:157], v[212:215], v[4:7]
	v_mfma_f32_16x16x32_bf16 v[20:23], v[150:153], v[174:177], v[20:23]
	v_mfma_f32_16x16x32_bf16 v[20:23], v[154:157], v[178:181], v[20:23]
	v_mfma_f32_16x16x32_bf16 v[36:39], v[150:153], v[166:169], v[36:39]
	v_mfma_f32_16x16x32_bf16 v[36:39], v[154:157], v[170:173], v[36:39]
	v_mfma_f32_16x16x32_bf16 v[52:55], v[150:153], v[158:161], v[52:55]
	v_mfma_f32_16x16x32_bf16 v[52:55], v[154:157], v[162:165], v[52:55]
	s_barrier
	s_add_u32 s18, s18, 0x80080
	s_addc_u32 s19, s19, 0
	s_add_i32 s20, s20, s24
	v_lshl_add_u64 v[142:143], s[18:19], 0, v[184:185]
	s_mov_b32 m0, s20
	s_nop 0
	global_load_lds_dwordx4 v[142:143], off
	v_lshl_add_u64 v[142:143], s[18:19], 0, v[128:129]
	s_add_i32 m0, s20, 0x2000
	s_nop 0
	global_load_lds_dwordx4 v[142:143], off
	s_waitcnt vmcnt(6)
	s_barrier
	v_mfma_f32_16x16x32_bf16 v[56:59], v[216:219], v[158:161], v[56:59]
	v_mfma_f32_16x16x32_bf16 v[56:59], v[220:223], v[162:165], v[56:59]
	v_mfma_f32_16x16x32_bf16 v[40:43], v[216:219], v[166:169], v[40:43]
	v_mfma_f32_16x16x32_bf16 v[40:43], v[220:223], v[170:173], v[40:43]
	v_mfma_f32_16x16x32_bf16 v[24:27], v[216:219], v[174:177], v[24:27]
	v_mfma_f32_16x16x32_bf16 v[24:27], v[220:223], v[178:181], v[24:27]
	v_mfma_f32_16x16x32_bf16 v[8:11], v[216:219], v[208:211], v[8:11]
	v_mfma_f32_16x16x32_bf16 v[8:11], v[220:223], v[212:215], v[8:11]
	v_mfma_f32_16x16x32_bf16 v[0:3], v[224:227], v[208:211], v[0:3]
	v_mfma_f32_16x16x32_bf16 v[0:3], v[228:231], v[212:215], v[0:3]
	v_mfma_f32_16x16x32_bf16 v[16:19], v[224:227], v[174:177], v[16:19]
	v_mfma_f32_16x16x32_bf16 v[16:19], v[228:231], v[178:181], v[16:19]
	v_mfma_f32_16x16x32_bf16 v[32:35], v[224:227], v[166:169], v[32:35]
	v_mfma_f32_16x16x32_bf16 v[32:35], v[228:231], v[170:173], v[32:35]
	v_mfma_f32_16x16x32_bf16 v[48:51], v[224:227], v[158:161], v[48:51]
	v_mfma_f32_16x16x32_bf16 v[48:51], v[228:231], v[162:165], v[48:51]
	s_add_i32 s38, s38, 2
	s_add_u32 s16, s16, 0x100
	s_addc_u32 s17, s17, 0
	s_add_u32 s36, s36, 0x100
	s_addc_u32 s37, s37, 0
	s_cmp_gt_u32 s38, 29
	s_barrier
	s_cbranch_scc0 .LBB0_721
	v_mul_f32_e32 v143, 0xbfb8aa3b, v124
	v_exp_f32_e32 v143, v143
	v_lshl_or_b32 v144, s3, 7, v140
	v_lshl_add_u32 v142, s14, 8, v138
	v_ashrrev_i32_e32 v145, 31, v144
	v_add_f32_e32 v143, 1.0, v143
	v_rcp_f32_e32 v143, v143
	s_movk_i32 s1, 0x2c00
	s_and_b64 vcc, exec, s[6:7]
	s_mov_b32 s3, s0
	v_mul_f32_e32 v124, v124, v143
	v_mul_f32_e32 v120, v124, v120
	v_mul_f32_e32 v124, 0xbfb8aa3b, v125
	v_exp_f32_e32 v124, v124
	s_mov_b32 s14, s8
	s_mov_b64 s[18:19], s[12:13]
	v_add_f32_e32 v124, 1.0, v124
	v_rcp_f32_e32 v124, v124
	s_nop 0
	v_mul_f32_e32 v124, v125, v124
	v_mul_f32_e32 v121, v124, v121
	v_mul_f32_e32 v124, 0xbfb8aa3b, v126
	v_exp_f32_e32 v124, v124
	s_nop 0
	v_add_f32_e32 v124, 1.0, v124
	v_rcp_f32_e32 v124, v124
	s_nop 0
	v_mul_f32_e32 v124, v126, v124
	v_mul_f32_e32 v122, v124, v122
	v_mul_f32_e32 v124, 0xbfb8aa3b, v127
	v_exp_f32_e32 v124, v124
	s_nop 0
	v_add_f32_e32 v124, 1.0, v124
	v_rcp_f32_e32 v124, v124
	s_nop 0
	v_mul_f32_e32 v124, v127, v124
	v_mul_f32_e32 v123, v124, v123
	v_mul_f32_e32 v124, 0xbfb8aa3b, v116
	v_exp_f32_e32 v124, v124
	s_nop 0
	v_add_f32_e32 v124, 1.0, v124
	v_rcp_f32_e32 v124, v124
	s_nop 0
	v_mul_f32_e32 v116, v116, v124
	v_mul_f32_e32 v112, v116, v112
	v_mul_f32_e32 v116, 0xbfb8aa3b, v117
	v_exp_f32_e32 v116, v116
	s_nop 0
	v_add_f32_e32 v116, 1.0, v116
	v_rcp_f32_e32 v116, v116
	s_nop 0
	v_mul_f32_e32 v116, v117, v116
	v_mul_f32_e32 v113, v116, v113
	v_mul_f32_e32 v116, 0xbfb8aa3b, v118
	v_exp_f32_e32 v116, v116
	v_cvt_pk_bf16_f32 v117, v122, v123
	s_nop 0
	v_add_f32_e32 v116, 1.0, v116
	v_rcp_f32_e32 v116, v116
	s_nop 0
	v_mul_f32_e32 v116, v118, v116
	v_mul_f32_e32 v114, v116, v114
	v_mul_f32_e32 v116, 0xbfb8aa3b, v119
	v_exp_f32_e32 v116, v116
	v_cvt_pk_bf16_f32 v118, v112, v113
	v_mov_b64_e32 v[112:113], s[66:67]
	v_add_f32_e32 v116, 1.0, v116
	v_rcp_f32_e32 v116, v116
	s_nop 0
	v_mul_f32_e32 v116, v119, v116
	v_mul_f32_e32 v115, v116, v115
	v_cvt_pk_bf16_f32 v116, v120, v121
	v_cvt_pk_bf16_f32 v119, v114, v115
	v_mad_i64_i32 v[120:121], s[16:17], v142, s1, v[112:113]
	v_lshlrev_b64 v[114:115], 1, v[144:145]
	v_lshl_add_u64 v[120:121], v[120:121], 0, v[114:115]
	global_store_dwordx4 v[120:121], v[116:119], off
	s_nop 1
	v_mul_f32_e32 v116, 0xbfb8aa3b, v108
	v_exp_f32_e32 v116, v116
	s_nop 0
	v_add_f32_e32 v116, 1.0, v116
	v_rcp_f32_e32 v116, v116
	s_nop 0
	v_mul_f32_e32 v108, v108, v116
	v_mul_f32_e32 v104, v108, v104
	v_mul_f32_e32 v108, 0xbfb8aa3b, v109
	v_exp_f32_e32 v108, v108
	s_nop 0
	v_add_f32_e32 v108, 1.0, v108
	v_rcp_f32_e32 v108, v108
	s_nop 0
	v_mul_f32_e32 v108, v109, v108
	v_mul_f32_e32 v105, v108, v105
	v_mul_f32_e32 v108, 0xbfb8aa3b, v110
	v_exp_f32_e32 v108, v108
	s_nop 0
	v_add_f32_e32 v108, 1.0, v108
	v_rcp_f32_e32 v108, v108
	s_nop 0
	v_mul_f32_e32 v108, v110, v108
	v_mul_f32_e32 v106, v108, v106
	v_mul_f32_e32 v108, 0xbfb8aa3b, v111
; __device__ __forceinline__ unsigned pk2(float lo, float hi) { unsigned r; asm("v_cvt_pk_bf16_f32 %0, %1, %2" : "=v"(r) : "v"(lo), "v"(hi)); return r; }
; __device__ __forceinline__ float sigmoidf_(float x) { return __builtin_amdgcn_rcpf(1.0f + __builtin_amdgcn_exp2f(-1.4426950408889634f * x)); }
;     __device__ __forceinline__ void operator()(const Acc& acc, const Unit& u, int wr, int wc, int fr, int fq) const {
;         const int row0 = u.pm * 256 + wr * 64 + fr, col0 = u.pn * 128 + wc * 32 + 8 * fq;
; #pragma unroll
;         for (int ai = 0; ai < 2; ++ai)
; #pragma unroll
;             for (int m = 0; m < 4; ++m) {
;                 float h[8];
; #pragma unroll
;                 for (int n = 0; n < 2; ++n)
; #pragma unroll
;                     for (int j = 0; j < 4; ++j) { const float gv = acc[ai][0][m][n][j], uv = acc[ai][1][m][n][j]; h[n * 4 + j] = gv * sigmoidf_(gv) * uv; }
;                 u32x4 w; w.x = pk2(h[0], h[1]); w.y = pk2(h[2], h[3]); w.z = pk2(h[4], h[5]); w.w = pk2(h[6], h[7]);
;                 *(u32x4*)(H + (size_t)(row0 + ai * 128 + m * 16) * DFF + col0) = w;
	v_exp_f32_e32 v108, v108
	s_nop 0
	v_add_f32_e32 v108, 1.0, v108
	v_rcp_f32_e32 v108, v108
	s_nop 0
	v_mul_f32_e32 v108, v111, v108
	v_mul_f32_e32 v107, v108, v107
	v_mul_f32_e32 v108, 0xbfb8aa3b, v100
	v_exp_f32_e32 v108, v108
	s_nop 0
	v_add_f32_e32 v108, 1.0, v108
	v_rcp_f32_e32 v108, v108
	s_nop 0
	v_mul_f32_e32 v100, v100, v108
	v_mul_f32_e32 v100, v100, v96
	v_mul_f32_e32 v96, 0xbfb8aa3b, v101
	v_exp_f32_e32 v96, v96
	s_nop 0
	v_add_f32_e32 v96, 1.0, v96
	v_rcp_f32_e32 v96, v96
	s_nop 0
	v_mul_f32_e32 v96, v101, v96
	v_mul_f32_e32 v101, v96, v97
	v_mul_f32_e32 v96, 0xbfb8aa3b, v102
	v_exp_f32_e32 v96, v96
	v_cvt_pk_bf16_f32 v97, v106, v107
	s_nop 0
	v_add_f32_e32 v96, 1.0, v96
	v_rcp_f32_e32 v96, v96
	s_nop 0
	v_mul_f32_e32 v96, v102, v96
	v_mul_f32_e32 v102, v96, v98
	v_mul_f32_e32 v96, 0xbfb8aa3b, v103
	v_exp_f32_e32 v96, v96
	v_cvt_pk_bf16_f32 v98, v100, v101
	v_or_b32_e32 v100, 16, v142
	v_mad_i64_i32 v[100:101], s[16:17], v100, s1, v[112:113]
	v_add_f32_e32 v96, 1.0, v96
	v_rcp_f32_e32 v96, v96
	v_lshl_add_u64 v[100:101], v[100:101], 0, v[114:115]
	v_mul_f32_e32 v96, v103, v96
	v_mul_f32_e32 v99, v96, v99
	v_cvt_pk_bf16_f32 v96, v104, v105
	v_cvt_pk_bf16_f32 v99, v102, v99
	global_store_dwordx4 v[100:101], v[96:99], off
	s_nop 1
	v_mul_f32_e32 v96, 0xbfb8aa3b, v92
	v_exp_f32_e32 v96, v96
	s_nop 0
	v_add_f32_e32 v96, 1.0, v96
	v_rcp_f32_e32 v96, v96
	s_nop 0
	v_mul_f32_e32 v92, v92, v96
	v_mul_f32_e32 v88, v92, v88
	v_mul_f32_e32 v92, 0xbfb8aa3b, v93
	v_exp_f32_e32 v92, v92
	s_nop 0
	v_add_f32_e32 v92, 1.0, v92
	v_rcp_f32_e32 v92, v92
	s_nop 0
	v_mul_f32_e32 v92, v93, v92
	v_mul_f32_e32 v89, v92, v89
	v_mul_f32_e32 v92, 0xbfb8aa3b, v94
	v_exp_f32_e32 v92, v92
	s_nop 0
	v_add_f32_e32 v92, 1.0, v92
	v_rcp_f32_e32 v92, v92
	s_nop 0
	v_mul_f32_e32 v92, v94, v92
	v_mul_f32_e32 v90, v92, v90
	v_mul_f32_e32 v92, 0xbfb8aa3b, v95
	v_exp_f32_e32 v92, v92
	s_nop 0
	v_add_f32_e32 v92, 1.0, v92
	v_rcp_f32_e32 v92, v92
	s_nop 0
	v_mul_f32_e32 v92, v95, v92
	v_mul_f32_e32 v91, v92, v91
	v_mul_f32_e32 v92, 0xbfb8aa3b, v84
	v_exp_f32_e32 v92, v92
	s_nop 0
	v_add_f32_e32 v92, 1.0, v92
	v_rcp_f32_e32 v92, v92
	s_nop 0
	v_mul_f32_e32 v84, v84, v92
	v_mul_f32_e32 v84, v84, v80
	v_mul_f32_e32 v80, 0xbfb8aa3b, v85
	v_exp_f32_e32 v80, v80
	s_nop 0
	v_add_f32_e32 v80, 1.0, v80
	v_rcp_f32_e32 v80, v80
	s_nop 0
	v_mul_f32_e32 v80, v85, v80
	v_mul_f32_e32 v85, v80, v81
	v_mul_f32_e32 v80, 0xbfb8aa3b, v86
	v_exp_f32_e32 v80, v80
	v_cvt_pk_bf16_f32 v81, v90, v91
	s_nop 0
	v_add_f32_e32 v80, 1.0, v80
	v_rcp_f32_e32 v80, v80
	s_nop 0
	v_mul_f32_e32 v80, v86, v80
	v_mul_f32_e32 v86, v80, v82
	v_mul_f32_e32 v80, 0xbfb8aa3b, v87
	v_exp_f32_e32 v80, v80
	v_cvt_pk_bf16_f32 v82, v84, v85
	v_or_b32_e32 v84, 32, v142
	v_mad_i64_i32 v[84:85], s[16:17], v84, s1, v[112:113]
	v_add_f32_e32 v80, 1.0, v80
	v_rcp_f32_e32 v80, v80
	v_lshl_add_u64 v[84:85], v[84:85], 0, v[114:115]
	v_mul_f32_e32 v80, v87, v80
	v_mul_f32_e32 v83, v80, v83
	v_cvt_pk_bf16_f32 v80, v88, v89
	v_cvt_pk_bf16_f32 v83, v86, v83
	global_store_dwordx4 v[84:85], v[80:83], off
	s_nop 1
	v_mul_f32_e32 v80, 0xbfb8aa3b, v76
	v_exp_f32_e32 v80, v80
	s_nop 0
	v_add_f32_e32 v80, 1.0, v80
	v_rcp_f32_e32 v80, v80
	s_nop 0
	v_mul_f32_e32 v76, v76, v80
	v_mul_f32_e32 v72, v76, v72
	v_mul_f32_e32 v76, 0xbfb8aa3b, v77
	v_exp_f32_e32 v76, v76
	s_nop 0
	v_add_f32_e32 v76, 1.0, v76
	v_rcp_f32_e32 v76, v76
	s_nop 0
	v_mul_f32_e32 v76, v77, v76
	v_mul_f32_e32 v73, v76, v73
	v_mul_f32_e32 v76, 0xbfb8aa3b, v78
	v_exp_f32_e32 v76, v76
	s_nop 0
	v_add_f32_e32 v76, 1.0, v76
	v_rcp_f32_e32 v76, v76
	s_nop 0
	v_mul_f32_e32 v76, v78, v76
	v_mul_f32_e32 v74, v76, v74
	v_mul_f32_e32 v76, 0xbfb8aa3b, v79
	v_exp_f32_e32 v76, v76
	s_nop 0
	v_add_f32_e32 v76, 1.0, v76
	v_rcp_f32_e32 v76, v76
	s_nop 0
	v_mul_f32_e32 v76, v79, v76
	v_mul_f32_e32 v75, v76, v75
	v_mul_f32_e32 v76, 0xbfb8aa3b, v68
	v_exp_f32_e32 v76, v76
	s_nop 0
	v_add_f32_e32 v76, 1.0, v76
	v_rcp_f32_e32 v76, v76
	s_nop 0
	v_mul_f32_e32 v68, v68, v76
	v_mul_f32_e32 v68, v68, v64
	v_mul_f32_e32 v64, 0xbfb8aa3b, v69
	v_exp_f32_e32 v64, v64
	s_nop 0
	v_add_f32_e32 v64, 1.0, v64
	v_rcp_f32_e32 v64, v64
	s_nop 0
	v_mul_f32_e32 v64, v69, v64
	v_mul_f32_e32 v69, v64, v65
	v_mul_f32_e32 v64, 0xbfb8aa3b, v70
	v_exp_f32_e32 v64, v64
	v_cvt_pk_bf16_f32 v65, v74, v75
	s_nop 0
	v_add_f32_e32 v64, 1.0, v64
	v_rcp_f32_e32 v64, v64
	s_nop 0
	v_mul_f32_e32 v64, v70, v64
	v_mul_f32_e32 v70, v64, v66
	v_mul_f32_e32 v64, 0xbfb8aa3b, v71
	v_exp_f32_e32 v64, v64
	v_cvt_pk_bf16_f32 v66, v68, v69
	v_or_b32_e32 v68, 48, v142
	v_mad_i64_i32 v[68:69], s[16:17], v68, s1, v[112:113]
	v_add_f32_e32 v64, 1.0, v64
	v_rcp_f32_e32 v64, v64
	v_lshl_add_u64 v[68:69], v[68:69], 0, v[114:115]
	v_mul_f32_e32 v64, v71, v64
	v_mul_f32_e32 v67, v64, v67
	v_cvt_pk_bf16_f32 v64, v72, v73
	v_cvt_pk_bf16_f32 v67, v70, v67
	global_store_dwordx4 v[68:69], v[64:67], off
	s_nop 1
	v_mul_f32_e32 v65, 0xbfb8aa3b, v60
	v_exp_f32_e32 v65, v65
	v_add_u32_e32 v64, 0x80, v142
	v_add_f32_e32 v65, 1.0, v65
	v_rcp_f32_e32 v65, v65
	s_nop 0
	v_mul_f32_e32 v60, v60, v65
	v_mul_f32_e32 v56, v60, v56
	v_mul_f32_e32 v60, 0xbfb8aa3b, v61
	v_exp_f32_e32 v60, v60
	s_nop 0
	v_add_f32_e32 v60, 1.0, v60
	v_rcp_f32_e32 v60, v60
	s_nop 0
	v_mul_f32_e32 v60, v61, v60
	v_mul_f32_e32 v57, v60, v57
	v_mul_f32_e32 v60, 0xbfb8aa3b, v62
	v_exp_f32_e32 v60, v60
	s_nop 0
	v_add_f32_e32 v60, 1.0, v60
	v_rcp_f32_e32 v60, v60
	s_nop 0
	v_mul_f32_e32 v60, v62, v60
	v_mul_f32_e32 v58, v60, v58
	v_mul_f32_e32 v60, 0xbfb8aa3b, v63
	v_exp_f32_e32 v60, v60
	s_nop 0
	v_add_f32_e32 v60, 1.0, v60
	v_rcp_f32_e32 v60, v60
	s_nop 0
	v_mul_f32_e32 v60, v63, v60
; __device__ __forceinline__ unsigned pk2(float lo, float hi) { unsigned r; asm("v_cvt_pk_bf16_f32 %0, %1, %2" : "=v"(r) : "v"(lo), "v"(hi)); return r; }
; __device__ __forceinline__ float sigmoidf_(float x) { return __builtin_amdgcn_rcpf(1.0f + __builtin_amdgcn_exp2f(-1.4426950408889634f * x)); }
; #define PG8_WAIT_V(n) asm volatile("s_waitcnt vmcnt(" #n ")" ::: "memory")
; #define PG8_BAR __builtin_amdgcn_s_barrier()
; template <class Epi>
; __device__ __forceinline__ void gemm_phase(LAS unsigned char* lds, const Gemm g, const StaticOrder& S, const Epi& E) {
;     ...
;     PG8_WAIT_V(0);
;     if (wr == 0) PG8_BAR;
;     __device__ __forceinline__ void operator()(const Acc& acc, const Unit& u, int wr, int wc, int fr, int fq) const {
;     ...
;         for (int ai = 0; ai < 2; ++ai)
; #pragma unroll
;             for (int m = 0; m < 4; ++m) {
;                 float h[8];
; #pragma unroll
;                 for (int n = 0; n < 2; ++n)
; #pragma unroll
;                     for (int j = 0; j < 4; ++j) { const float gv = acc[ai][0][m][n][j], uv = acc[ai][1][m][n][j]; h[n * 4 + j] = gv * sigmoidf_(gv) * uv; }
;                 u32x4 w; w.x = pk2(h[0], h[1]); w.y = pk2(h[2], h[3]); w.z = pk2(h[4], h[5]); w.w = pk2(h[6], h[7]);
;                 *(u32x4*)(H + (size_t)(row0 + ai * 128 + m * 16) * DFF + col0) = w;
	v_mul_f32_e32 v59, v60, v59
	v_mul_f32_e32 v60, 0xbfb8aa3b, v52
	v_exp_f32_e32 v60, v60
	s_nop 0
	v_add_f32_e32 v60, 1.0, v60
	v_rcp_f32_e32 v60, v60
	s_nop 0
	v_mul_f32_e32 v52, v52, v60
	v_mul_f32_e32 v52, v52, v48
	v_mul_f32_e32 v48, 0xbfb8aa3b, v53
	v_exp_f32_e32 v48, v48
	s_nop 0
	v_add_f32_e32 v48, 1.0, v48
	v_rcp_f32_e32 v48, v48
	s_nop 0
	v_mul_f32_e32 v48, v53, v48
	v_mul_f32_e32 v53, v48, v49
	v_mul_f32_e32 v48, 0xbfb8aa3b, v54
	v_exp_f32_e32 v48, v48
	v_cvt_pk_bf16_f32 v49, v58, v59
	s_nop 0
	v_add_f32_e32 v48, 1.0, v48
	v_rcp_f32_e32 v48, v48
	s_nop 0
	v_mul_f32_e32 v48, v54, v48
	v_mul_f32_e32 v54, v48, v50
	v_mul_f32_e32 v48, 0xbfb8aa3b, v55
	v_exp_f32_e32 v48, v48
	v_cvt_pk_bf16_f32 v50, v52, v53
	v_mad_i64_i32 v[52:53], s[16:17], v64, s1, v[112:113]
	v_add_f32_e32 v48, 1.0, v48
	v_rcp_f32_e32 v48, v48
	v_lshl_add_u64 v[52:53], v[52:53], 0, v[114:115]
	v_mul_f32_e32 v48, v55, v48
	v_mul_f32_e32 v51, v48, v51
	v_cvt_pk_bf16_f32 v48, v56, v57
	v_cvt_pk_bf16_f32 v51, v54, v51
	global_store_dwordx4 v[52:53], v[48:51], off
	s_nop 1
	v_mul_f32_e32 v48, 0xbfb8aa3b, v44
	v_exp_f32_e32 v48, v48
	s_nop 0
	v_add_f32_e32 v48, 1.0, v48
	v_rcp_f32_e32 v48, v48
	s_nop 0
	v_mul_f32_e32 v44, v44, v48
	v_mul_f32_e32 v40, v44, v40
	v_mul_f32_e32 v44, 0xbfb8aa3b, v45
	v_exp_f32_e32 v44, v44
	s_nop 0
	v_add_f32_e32 v44, 1.0, v44
	v_rcp_f32_e32 v44, v44
	s_nop 0
	v_mul_f32_e32 v44, v45, v44
	v_mul_f32_e32 v41, v44, v41
	v_mul_f32_e32 v44, 0xbfb8aa3b, v46
	v_exp_f32_e32 v44, v44
	s_nop 0
	v_add_f32_e32 v44, 1.0, v44
	v_rcp_f32_e32 v44, v44
	s_nop 0
	v_mul_f32_e32 v44, v46, v44
	v_mul_f32_e32 v42, v44, v42
	v_mul_f32_e32 v44, 0xbfb8aa3b, v47
	v_exp_f32_e32 v44, v44
	s_nop 0
	v_add_f32_e32 v44, 1.0, v44
	v_rcp_f32_e32 v44, v44
	s_nop 0
	v_mul_f32_e32 v44, v47, v44
	v_mul_f32_e32 v43, v44, v43
	v_mul_f32_e32 v44, 0xbfb8aa3b, v36
	v_exp_f32_e32 v44, v44
	s_nop 0
	v_add_f32_e32 v44, 1.0, v44
	v_rcp_f32_e32 v44, v44
	s_nop 0
	v_mul_f32_e32 v36, v36, v44
	v_mul_f32_e32 v36, v36, v32
	v_mul_f32_e32 v32, 0xbfb8aa3b, v37
	v_exp_f32_e32 v32, v32
	s_nop 0
	v_add_f32_e32 v32, 1.0, v32
	v_rcp_f32_e32 v32, v32
	s_nop 0
	v_mul_f32_e32 v32, v37, v32
	v_mul_f32_e32 v37, v32, v33
	v_mul_f32_e32 v32, 0xbfb8aa3b, v38
	v_exp_f32_e32 v32, v32
	v_cvt_pk_bf16_f32 v33, v42, v43
	s_nop 0
	v_add_f32_e32 v32, 1.0, v32
	v_rcp_f32_e32 v32, v32
	s_nop 0
	v_mul_f32_e32 v32, v38, v32
	v_mul_f32_e32 v38, v32, v34
	v_mul_f32_e32 v32, 0xbfb8aa3b, v39
	v_exp_f32_e32 v32, v32
	v_cvt_pk_bf16_f32 v34, v36, v37
	v_add_u32_e32 v36, 0x90, v142
	v_mad_i64_i32 v[36:37], s[16:17], v36, s1, v[112:113]
	v_add_f32_e32 v32, 1.0, v32
	v_rcp_f32_e32 v32, v32
	v_lshl_add_u64 v[36:37], v[36:37], 0, v[114:115]
	v_mul_f32_e32 v32, v39, v32
	v_mul_f32_e32 v35, v32, v35
	v_cvt_pk_bf16_f32 v32, v40, v41
	v_cvt_pk_bf16_f32 v35, v38, v35
	global_store_dwordx4 v[36:37], v[32:35], off
	s_nop 1
	v_mul_f32_e32 v32, 0xbfb8aa3b, v28
	v_exp_f32_e32 v32, v32
	s_nop 0
	v_add_f32_e32 v32, 1.0, v32
	v_rcp_f32_e32 v32, v32
	s_nop 0
	v_mul_f32_e32 v28, v28, v32
	v_mul_f32_e32 v24, v28, v24
	v_mul_f32_e32 v28, 0xbfb8aa3b, v29
	v_exp_f32_e32 v28, v28
	s_nop 0
	v_add_f32_e32 v28, 1.0, v28
	v_rcp_f32_e32 v28, v28
	s_nop 0
	v_mul_f32_e32 v28, v29, v28
	v_mul_f32_e32 v25, v28, v25
	v_mul_f32_e32 v28, 0xbfb8aa3b, v30
	v_exp_f32_e32 v28, v28
	s_nop 0
	v_add_f32_e32 v28, 1.0, v28
	v_rcp_f32_e32 v28, v28
	s_nop 0
	v_mul_f32_e32 v28, v30, v28
	v_mul_f32_e32 v26, v28, v26
	v_mul_f32_e32 v28, 0xbfb8aa3b, v31
	v_exp_f32_e32 v28, v28
	s_nop 0
	v_add_f32_e32 v28, 1.0, v28
	v_rcp_f32_e32 v28, v28
	s_nop 0
	v_mul_f32_e32 v28, v31, v28
	v_mul_f32_e32 v27, v28, v27
	v_mul_f32_e32 v28, 0xbfb8aa3b, v20
	v_exp_f32_e32 v28, v28
	s_nop 0
	v_add_f32_e32 v28, 1.0, v28
	v_rcp_f32_e32 v28, v28
	s_nop 0
	v_mul_f32_e32 v20, v20, v28
	v_mul_f32_e32 v20, v20, v16
	v_mul_f32_e32 v16, 0xbfb8aa3b, v21
	v_exp_f32_e32 v16, v16
	s_nop 0
	v_add_f32_e32 v16, 1.0, v16
	v_rcp_f32_e32 v16, v16
	s_nop 0
	v_mul_f32_e32 v16, v21, v16
	v_mul_f32_e32 v21, v16, v17
	v_mul_f32_e32 v16, 0xbfb8aa3b, v22
	v_exp_f32_e32 v16, v16
	v_cvt_pk_bf16_f32 v17, v26, v27
	s_nop 0
	v_add_f32_e32 v16, 1.0, v16
	v_rcp_f32_e32 v16, v16
	s_nop 0
	v_mul_f32_e32 v16, v22, v16
	v_mul_f32_e32 v22, v16, v18
	v_mul_f32_e32 v16, 0xbfb8aa3b, v23
	v_exp_f32_e32 v16, v16
	v_cvt_pk_bf16_f32 v18, v20, v21
	v_add_u32_e32 v20, 0xa0, v142
	v_mad_i64_i32 v[20:21], s[16:17], v20, s1, v[112:113]
	v_add_f32_e32 v16, 1.0, v16
	v_rcp_f32_e32 v16, v16
	v_lshl_add_u64 v[20:21], v[20:21], 0, v[114:115]
	v_mul_f32_e32 v16, v23, v16
	v_mul_f32_e32 v19, v16, v19
	v_cvt_pk_bf16_f32 v16, v24, v25
	v_cvt_pk_bf16_f32 v19, v22, v19
	global_store_dwordx4 v[20:21], v[16:19], off
	s_nop 1
	v_mul_f32_e32 v16, 0xbfb8aa3b, v12
	v_exp_f32_e32 v16, v16
	s_nop 0
	v_add_f32_e32 v16, 1.0, v16
	v_rcp_f32_e32 v16, v16
	s_nop 0
	v_mul_f32_e32 v12, v12, v16
	v_mul_f32_e32 v8, v12, v8
	v_mul_f32_e32 v12, 0xbfb8aa3b, v13
	v_exp_f32_e32 v12, v12
	s_nop 0
	v_add_f32_e32 v12, 1.0, v12
	v_rcp_f32_e32 v12, v12
	s_nop 0
	v_mul_f32_e32 v12, v13, v12
	v_mul_f32_e32 v9, v12, v9
	v_mul_f32_e32 v12, 0xbfb8aa3b, v14
	v_exp_f32_e32 v12, v12
	s_nop 0
	v_add_f32_e32 v12, 1.0, v12
	v_rcp_f32_e32 v12, v12
	s_nop 0
	v_mul_f32_e32 v12, v14, v12
	v_mul_f32_e32 v10, v12, v10
	v_mul_f32_e32 v12, 0xbfb8aa3b, v15
	v_exp_f32_e32 v12, v12
	s_nop 0
	v_add_f32_e32 v12, 1.0, v12
	v_rcp_f32_e32 v12, v12
	s_nop 0
	v_mul_f32_e32 v12, v15, v12
	v_mul_f32_e32 v11, v12, v11
	v_mul_f32_e32 v12, 0xbfb8aa3b, v4
	v_exp_f32_e32 v12, v12
	s_nop 0
	v_add_f32_e32 v12, 1.0, v12
	v_rcp_f32_e32 v12, v12
	s_nop 0
	v_mul_f32_e32 v4, v4, v12
	v_mul_f32_e32 v4, v4, v0
	v_mul_f32_e32 v0, 0xbfb8aa3b, v5
	v_exp_f32_e32 v0, v0
	s_nop 0
	v_add_f32_e32 v0, 1.0, v0
	v_rcp_f32_e32 v0, v0
	s_nop 0
	v_mul_f32_e32 v0, v5, v0
	v_mul_f32_e32 v5, v0, v1
	v_mul_f32_e32 v0, 0xbfb8aa3b, v6
	v_exp_f32_e32 v0, v0
	v_cvt_pk_bf16_f32 v1, v10, v11
	s_nop 0
	v_add_f32_e32 v0, 1.0, v0
	v_rcp_f32_e32 v0, v0
	s_nop 0
	v_mul_f32_e32 v0, v6, v0
	v_mul_f32_e32 v6, v0, v2
	v_mul_f32_e32 v0, 0xbfb8aa3b, v7
	v_exp_f32_e32 v0, v0
	v_cvt_pk_bf16_f32 v2, v4, v5
	v_add_u32_e32 v4, 0xb0, v142
	v_mad_i64_i32 v[4:5], s[16:17], v4, s1, v[112:113]
	v_add_f32_e32 v0, 1.0, v0
	v_rcp_f32_e32 v0, v0
	v_lshl_add_u64 v[4:5], v[4:5], 0, v[114:115]
	s_mov_b64 s[16:17], s[10:11]
	v_mul_f32_e32 v0, v7, v0
	v_mul_f32_e32 v3, v0, v3
	v_cvt_pk_bf16_f32 v0, v8, v9
	v_cvt_pk_bf16_f32 v3, v6, v3
	global_store_dwordx4 v[4:5], v[0:3], off
	s_cbranch_vccz .LBB0_718
	s_waitcnt vmcnt(0)
	s_cmpk_gt_u32 s23, 0xff
	s_cbranch_scc1 .LBB0_725
	s_barrier
